# static s_setprio 1 for waves 4-7 during the GEMM phases, all per-phase priority flips removed from the 7 GEMM loops (on top of v13)
# baseline (speedup 1.0000x reference)
; #define PG8_STAGE(bufoff, gbase, voff) do { _Pragma("unroll") for (int _i = 0; _i < 2; ++_i) \
;         __builtin_amdgcn_global_load_lds((const unsigned*)((const char*)(gbase) + (voff)[_i]), (LAS unsigned*)(lds + (bufoff) + ldsw + _i * 8192), 16, 0, 0); } while (0)
; #define PG8_WAIT_V(n) asm volatile("s_waitcnt vmcnt(" #n ")" ::: "memory")
; #define PG8_BAR __builtin_amdgcn_s_barrier()
; template <class Epi, bool ALIGN_EPI>
; __device__ __forceinline__ void gemm_phase(LAS unsigned char* lds, const Gemm g, const StaticOrder& S, const Epi& E) {
;     int tid_ = threadIdx.x; asm volatile("" : "+v"(tid_));
;     const int tid = tid_, wid = __builtin_amdgcn_readfirstlane(tid >> 6), lane = tid & 63, wr = wid >> 2, wc = wid & 3, fr = lane & 15, fq = lane >> 4;
;     const int K = g.K, nt = K / BK, lda = g.lda;
;     unsigned voffA[2], voffB[2];
; #pragma unroll
;     for (int i = 0; i < 2; ++i) { int R, C; stage_rc(tid * 16 + i * 8192, R, C); const int Rb = Epi::PERM ? ((R & ~31) + perm32(R & 31)) : R;
;         voffA[i] = (unsigned)(R * lda + C) * 2u; voffB[i] = (unsigned)(Rb * K + C) * 2u; }
;     const size_t kstep = (size_t)(BK * 2);
;     const size_t hstepA = (size_t)HALF * lda * 2, hstepB = (size_t)HALF * K * 2;
;     const size_t tstepA = 2 * hstepA, tstepB = 2 * hstepB;
;     const unsigned ldsw = (unsigned)wid * 1024u;
;     const int aoff = lds_byte(wr * 64 + fr, fq * 8), boff = lds_byte(wc * 32 + fr, fq * 8);
;     ...
;     Unit cur, nxt; int ui = 0;
;     if (!S.next(0, cur)) return;
;     f32x4 acc[2][2][4][2];
; #pragma unroll
;     for (int a = 0; a < 2; ++a)
; #pragma unroll
;         for (int b = 0; b < 2; ++b)
; #pragma unroll
;             for (int m = 0; m < 4; ++m)
; #pragma unroll
;                 for (int n = 0; n < 2; ++n) acc[a][b][m][n] = (f32x4){0.f, 0.f, 0.f, 0.f};
;     bf16x8 At[4][2], B0[2][2], B1[2][2];
;     const char* cA = (const char*)g.A + (size_t)cur.pm * tstepA; const char* cB = (const char*)g.Bt + (size_t)cur.pn * tstepB;
;     PG8_STAGE(PG8_SB(0, 0), cB, voffB); PG8_STAGE(PG8_SB(0, 1), cB + hstepB, voffB); PG8_STAGE(PG8_SA(0, 0), cA, voffA); PG8_STAGE(PG8_SA(0, 1), cA + hstepA, voffA);
;     if (wr == 1) PG8_BAR;
;     PG8_WAIT_V(2); PG8_BAR;
;     PG8_STAGE(PG8_SB(1, 0), cB + kstep, voffB); PG8_STAGE(PG8_SA(1, 0), cA + kstep, voffA); PG8_STAGE(PG8_SB(1, 1), cB + hstepB + kstep, voffB);
;     PG8_WAIT_V(6); PG8_BAR;
.LBB0_112:
	s_or_b64 exec, exec, s[0:1]
	s_setprio 0
	v_readfirstlane_b32 vcc_lo, v166
	s_nop 3
	s_lshr_b32 vcc_lo, vcc_lo, 8
	s_cmp_eq_u32 vcc_lo, 1
	s_cbranch_scc0 .Lprio_skip_0
	s_setprio 1
.Lprio_skip_0:
	s_add_i32 s0, 0, 0x230ec
	v_mov_b32_e32 v148, v166
	s_waitcnt lgkmcnt(0)
	v_mov_b32_e32 v0, s0
	s_barrier
	ds_read_b32 v1, v0
	s_add_i32 s1, 0, 0x230e8
	s_cmpk_lt_i32 s3, 0x1080
	v_mov_b32_e32 v8, v166
	s_cselect_b64 s[12:13], -1, 0
	s_waitcnt lgkmcnt(0)
	v_readfirstlane_b32 s0, v1
	v_mov_b32_e32 v1, s1
	ds_read_b32 v2, v1
	ds_read_b32 v3, v0
	ds_read_b32 v4, v1
	ds_read_b32 v0, v0
	ds_read_b32 v1, v1
	v_readfirstlane_b32 s2, v148
	s_waitcnt lgkmcnt(4)
	v_readfirstlane_b32 s7, v2
	s_waitcnt lgkmcnt(3)
	v_readfirstlane_b32 s6, v3
	s_waitcnt lgkmcnt(2)
	v_readfirstlane_b32 s10, v4
	s_waitcnt lgkmcnt(1)
	v_readfirstlane_b32 s9, v0
	s_waitcnt lgkmcnt(0)
	v_readfirstlane_b32 s8, v1
	v_writelane_b32 v252, s12, 8
	s_cmpk_gt_i32 s3, 0x107f
	v_readfirstlane_b32 s1, v8
	v_writelane_b32 v252, s13, 9
	s_cbranch_scc1 .LBB0_128
	v_lshlrev_b32_e32 v0, 4, v8
	v_add_u32_e32 v1, 0x2000, v0
	v_ashrrev_i32_e32 v2, 31, v1
	v_lshrrev_b32_e32 v2, 22, v2
	v_add_u32_e32 v2, v1, v2
	v_ashrrev_i32_e32 v9, 10, v2
	v_mul_i32_i24_e32 v2, 0x400, v9
	v_sub_u32_e32 v1, v1, v2
	v_lshrrev_b32_e32 v2, 4, v1
	v_bitop3_b32 v1, v2, v1, 32 bitop3:0x6c
	v_ashrrev_i32_e32 v2, 31, v1
	v_lshrrev_b32_e32 v2, 26, v2
	v_add_u32_e32 v2, v1, v2
	v_lshlrev_b32_e32 v3, 3, v9
	v_ashrrev_i32_e32 v10, 6, v2
	v_and_b32_e32 v3, -16, v3
	s_add_u32 s30, s7, 0x2200000
	v_add_u32_e32 v3, v10, v3
	s_addc_u32 s31, s0, 0
	v_and_b32_e32 v4, 3, v10
	s_mov_b32 s0, 0xfffe0
	v_lshrrev_b32_e32 v5, 2, v3
	v_lshlrev_b32_e32 v6, 1, v3
	v_and_b32_e32 v2, 0xc0, v2
	v_and_or_b32 v4, v3, s0, v4
	v_and_b32_e32 v5, 4, v5
	v_and_b32_e32 v6, 24, v6
	v_sub_u32_e32 v1, v1, v2
	v_mov_b32_e32 v2, 1
	v_or3_b32 v4, v4, v5, v6
	v_lshlrev_b32_e32 v5, 5, v9
	v_ashrrev_i16_sdwa v1, v2, sext(v1) dst_sel:DWORD dst_unused:UNUSED_PAD src0_sel:DWORD src1_sel:BYTE_0
	v_and_b32_e32 v5, 32, v5
	v_bfe_i32 v11, v1, 0, 16
	v_add_lshl_u32 v1, v5, v11, 1
	v_lshl_add_u32 v128, v4, 12, v1
	v_lshl_add_u32 v130, v3, 12, v1
	v_bfe_i32 v1, v8, 27, 1
	v_lshrrev_b32_e32 v1, 22, v1
	v_add_u32_e32 v1, v0, v1
	v_and_b32_e32 v1, 0xfffffc00, v1
	v_sub_u32_e32 v0, v0, v1
	v_lshrrev_b32_e32 v1, 4, v0
	v_ashrrev_i32_e32 v3, 31, v8
	v_bitop3_b32 v0, v1, v0, 32 bitop3:0x6c
	v_lshrrev_b32_e32 v3, 26, v3
	v_ashrrev_i32_e32 v1, 31, v0
	v_add_u32_e32 v3, v8, v3
	v_lshrrev_b32_e32 v1, 26, v1
	v_ashrrev_i32_e32 v13, 6, v3
	v_add_u32_e32 v1, v0, v1
	v_lshlrev_b32_e32 v3, 3, v13
	s_add_u32 s33, s10, 0x1a000000
	v_ashrrev_i32_e32 v12, 6, v1
	v_and_b32_e32 v3, -16, v3
	s_addc_u32 s34, s6, 0
	v_add_u32_e32 v3, v12, v3
	v_and_b32_e32 v4, 3, v12
	s_ashr_i32 s36, s3, 31
	v_and_or_b32 v4, v3, s0, v4
	s_lshr_b32 s0, s36, 29
	s_add_i32 s0, s3, s0
	s_ashr_i32 s10, s1, 6
	s_ashr_i32 s6, s0, 3
	s_and_b32 s0, s0, -8
	s_ashr_i32 s12, s1, 8
	s_lshl_b32 s35, s10, 10
	s_sub_i32 s0, s3, s0
	s_cmp_lt_i32 s0, 0
	s_movk_i32 s37, 0x211
	s_cselect_b32 s7, s37, 0x210
	s_mul_i32 s0, s7, s0
	s_add_i32 s0, s0, s6
	s_mul_hi_i32 s6, s0, 0x2e8ba2e9
	s_lshr_b32 s7, s6, 31
	s_ashr_i32 s6, s6, 6
	s_add_i32 s6, s6, s7
	s_lshl_b32 s7, s6, 3
	s_mulk_i32 s6, 0x160
	s_sub_i32 s6, s0, s6
	s_sext_i32_i16 s0, s6
	s_bfe_u32 s0, s0, 0x3001c
	s_add_i32 s11, s6, s0
	s_sext_i32_i16 s0, s11
	s_and_b32 s11, s11, 0xfff8
	s_sub_i32 s6, s6, s11
	s_sext_i32_i16 s6, s6
	v_lshrrev_b32_e32 v5, 2, v3
	v_lshlrev_b32_e32 v6, 1, v3
	v_and_b32_e32 v1, 0xc0, v1
	s_lshr_b32 s0, s0, 3
	s_add_i32 s22, s7, s6
	v_and_b32_e32 v5, 4, v5
	v_and_b32_e32 v6, 24, v6
	v_sub_u32_e32 v0, v0, v1
	s_ashr_i32 s23, s22, 31
	s_bfe_i64 s[14:15], s[0:1], 0x100000
	v_or3_b32 v4, v4, v5, v6
	v_lshlrev_b32_e32 v5, 5, v13
	v_ashrrev_i16_sdwa v0, v2, sext(v0) dst_sel:DWORD dst_unused:UNUSED_PAD src0_sel:DWORD src1_sel:BYTE_0
	s_lshl_b64 s[6:7], s[22:23], 20
	s_lshl_b64 s[14:15], s[14:15], 20
	v_and_b32_e32 v5, 32, v5
	v_bfe_i32 v14, v0, 0, 16
	s_add_u32 s24, s33, s14
	v_add_lshl_u32 v0, v5, v14, 1
	s_addc_u32 s25, s34, s15
	s_add_i32 s23, s35, 0
	v_lshl_add_u32 v132, v4, 12, v0
	s_add_i32 m0, s23, 0x10000
	v_lshl_add_u32 v134, v3, 12, v0
	global_load_lds_dwordx4 v132, s[24:25]
	s_add_i32 m0, s23, 0x12000
	s_add_u32 s14, s24, 0x80000
	global_load_lds_dwordx4 v128, s[24:25]
	s_addc_u32 s15, s25, 0
	s_add_i32 m0, s23, 0x14000
	v_mov_b32_e32 v133, 0
	global_load_lds_dwordx4 v132, s[14:15]
	s_add_i32 m0, s23, 0x16000
	s_add_u32 s26, s30, s6
	s_addc_u32 s27, s31, s7
	s_add_i32 s38, s23, 0x2000
	global_load_lds_dwordx4 v128, s[14:15]
	s_mov_b32 m0, s23
	s_add_u32 s6, s26, 0x80000
	global_load_lds_dwordx4 v134, s[26:27]
	s_mov_b32 m0, s38
	s_addc_u32 s7, s27, 0
	s_add_i32 s39, s23, 0x4000
	global_load_lds_dwordx4 v130, s[26:27]
	s_mov_b32 m0, s39
	s_add_i32 s40, s23, 0x6000
	global_load_lds_dwordx4 v134, s[6:7]
	s_mov_b32 m0, s40
	v_mov_b32_e32 v129, v133
	global_load_lds_dwordx4 v130, s[6:7]
	v_mov_b32_e32 v135, v133
	v_mov_b32_e32 v131, v133
	s_cmp_eq_u32 s12, 1
	v_lshl_add_u64 v[6:7], s[24:25], 0, v[132:133]
	v_lshl_add_u64 v[4:5], s[24:25], 0, v[128:129]
	v_lshl_add_u64 v[0:1], s[26:27], 0, v[134:135]
	s_cselect_b64 s[6:7], -1, 0
	s_cmp_lg_u32 s12, 1
	v_lshl_add_u64 v[2:3], s[26:27], 0, v[130:131]
	s_cbranch_scc1 .LBB0_115
	s_barrier

; #define PG8_STAGE(bufoff, gbase, voff) do { _Pragma("unroll") for (int _i = 0; _i < 2; ++_i) \
;         __builtin_amdgcn_global_load_lds((const unsigned*)((const char*)(gbase) + (voff)[_i]), (LAS unsigned*)(lds + (bufoff) + ldsw + _i * 8192), 16, 0, 0); } while (0)
; #define PG8_LDA(dst, b, h) do { _Pragma("unroll") for (int m = 0; m < 4; ++m) _Pragma("unroll") for (int k = 0; k < 2; ++k) dst[m][k] = *(const LAS bf16x8*)(lds + PG8_SA(b, h) + aoff + m * 2048 + k * 1024); } while (0)
; #define PG8_LDB(dst, b, h) do { _Pragma("unroll") for (int n = 0; n < 2; ++n) _Pragma("unroll") for (int k = 0; k < 2; ++k) dst[n][k] = *(const LAS bf16x8*)(lds + PG8_SB(b, h) + boff + n * 2048 + k * 1024); } while (0)
; #define PG8_MMA(ai, bj, At, Bt) do { __builtin_amdgcn_s_setprio(1); _Pragma("unroll") for (int m = 0; m < 4; ++m) _Pragma("unroll") for (int n = 0; n < 2; ++n) _Pragma("unroll") for (int k = 0; k < 2; ++k) \
;         acc[ai][bj][m][n] = __builtin_amdgcn_mfma_f32_16x16x32_bf16(Bt[n][k], At[m][k], acc[ai][bj][m][n], 0, 0, 0); __builtin_amdgcn_s_setprio(0); } while (0)
; #define PG8_WAIT_V(n) asm volatile("s_waitcnt vmcnt(" #n ")" ::: "memory")
; #define PG8_WAIT_L(n) asm volatile("s_waitcnt lgkmcnt(" #n ")" ::: "memory")
; #define PG8_BAR __builtin_amdgcn_s_barrier()
; #define PG8_SCHED __builtin_amdgcn_sched_barrier(0)
; template <class Epi, bool ALIGN_EPI>
; __device__ __forceinline__ void gemm_phase(LAS unsigned char* lds, const Gemm g, const StaticOrder& S, const Epi& E) {
;     ...
;             PG8_LDB(B0, 0, 0); PG8_LDB(B1, 0, 1); PG8_SCHED; PG8_LDA(At, 0, 0); PG8_STAGE(PG8_SA(1, 1), a1 + hstepA, voffA);
;             PG8_WAIT_V(8); PG8_WAIT_L(0); PG8_BAR; PG8_MMA(0, 0, At, B0); PG8_MMA(0, 1, At, B1); PG8_BAR; PG8_SCHED;
;             PG8_LDA(At, 0, 1); PG8_STAGE(PG8_SB(0, 0), b2, voffB); PG8_STAGE(PG8_SB(0, 1), b2 + hstepB, voffB); PG8_STAGE(PG8_SA(0, 0), a2, voffA);
;             PG8_WAIT_V(8); PG8_WAIT_L(0); PG8_BAR; PG8_MMA(1, 0, At, B0); PG8_MMA(1, 1, At, B1); PG8_BAR; PG8_SCHED;
.LBB0_121:
	ds_read_b128 v[144:147], v152
	ds_read_b128 v[156:159], v152 offset:1024
	ds_read_b128 v[160:163], v152 offset:2048
	ds_read_b128 v[168:171], v152 offset:3072
	ds_read_b128 v[172:175], v153
	ds_read_b128 v[176:179], v153 offset:1024
	ds_read_b128 v[180:183], v153 offset:2048
	ds_read_b128 v[184:187], v153 offset:3072
	s_add_u32 s26, s24, 0xfff80080
	s_addc_u32 s27, s25, -1
	s_cmp_eq_u32 s55, 28
	s_cselect_b32 s29, s17, s27
	s_cselect_b32 s28, s51, s26
	s_cselect_b32 s27, s15, s54
	s_cselect_b32 s26, s52, s53
	v_lshl_add_u64 v[164:165], s[24:25], 0, v[138:139]
	s_add_i32 m0, s23, 0xc000
	ds_read_b128 v[188:191], v154
	ds_read_b128 v[192:195], v154 offset:1024
	ds_read_b128 v[196:199], v154 offset:2048
	ds_read_b128 v[200:203], v154 offset:3072
	ds_read_b128 v[204:207], v154 offset:4096
	ds_read_b128 v[208:211], v154 offset:5120
	ds_read_b128 v[212:215], v154 offset:6144
	ds_read_b128 v[216:219], v154 offset:7168
	global_load_lds_dwordx4 v[164:165], off
	v_lshl_add_u64 v[164:165], s[24:25], 0, v[136:137]
	s_add_i32 m0, s23, 0xe000
	s_nop 0
	global_load_lds_dwordx4 v[164:165], off
	s_waitcnt vmcnt(8)
	s_waitcnt lgkmcnt(0)
	s_barrier
	v_mfma_f32_16x16x32_bf16 v[124:127], v[144:147], v[188:191], v[124:127]
	v_mfma_f32_16x16x32_bf16 v[120:123], v[160:163], v[188:191], v[120:123]
	v_mfma_f32_16x16x32_bf16 v[108:111], v[144:147], v[196:199], v[108:111]
	v_mfma_f32_16x16x32_bf16 v[104:107], v[160:163], v[196:199], v[104:107]
	v_mfma_f32_16x16x32_bf16 v[92:95], v[144:147], v[204:207], v[92:95]
	v_mfma_f32_16x16x32_bf16 v[88:91], v[160:163], v[204:207], v[88:91]
	v_mfma_f32_16x16x32_bf16 v[76:79], v[144:147], v[212:215], v[76:79]
	v_mfma_f32_16x16x32_bf16 v[72:75], v[160:163], v[212:215], v[72:75]
	v_mfma_f32_16x16x32_bf16 v[124:127], v[156:159], v[192:195], v[124:127]
	v_mfma_f32_16x16x32_bf16 v[120:123], v[168:171], v[192:195], v[120:123]
	v_mfma_f32_16x16x32_bf16 v[108:111], v[156:159], v[200:203], v[108:111]
	v_mfma_f32_16x16x32_bf16 v[104:107], v[168:171], v[200:203], v[104:107]
	v_mfma_f32_16x16x32_bf16 v[92:95], v[156:159], v[208:211], v[92:95]
	v_mfma_f32_16x16x32_bf16 v[88:91], v[168:171], v[208:211], v[88:91]
	v_mfma_f32_16x16x32_bf16 v[76:79], v[156:159], v[216:219], v[76:79]
	v_mfma_f32_16x16x32_bf16 v[72:75], v[168:171], v[216:219], v[72:75]
	v_mfma_f32_16x16x32_bf16 v[116:119], v[172:175], v[188:191], v[116:119]
	v_mfma_f32_16x16x32_bf16 v[112:115], v[180:183], v[188:191], v[112:115]
	v_mfma_f32_16x16x32_bf16 v[100:103], v[172:175], v[196:199], v[100:103]
	v_mfma_f32_16x16x32_bf16 v[96:99], v[180:183], v[196:199], v[96:99]
	v_mfma_f32_16x16x32_bf16 v[84:87], v[172:175], v[204:207], v[84:87]
	v_mfma_f32_16x16x32_bf16 v[80:83], v[180:183], v[204:207], v[80:83]
	v_mfma_f32_16x16x32_bf16 v[68:71], v[172:175], v[212:215], v[68:71]
	v_mfma_f32_16x16x32_bf16 v[64:67], v[180:183], v[212:215], v[64:67]
	v_mfma_f32_16x16x32_bf16 v[116:119], v[176:179], v[192:195], v[116:119]
	v_mfma_f32_16x16x32_bf16 v[112:115], v[184:187], v[192:195], v[112:115]
	v_mfma_f32_16x16x32_bf16 v[100:103], v[176:179], v[200:203], v[100:103]
	v_mfma_f32_16x16x32_bf16 v[96:99], v[184:187], v[200:203], v[96:99]
	v_mfma_f32_16x16x32_bf16 v[84:87], v[176:179], v[208:211], v[84:87]
	v_mfma_f32_16x16x32_bf16 v[80:83], v[184:187], v[208:211], v[80:83]
	v_mfma_f32_16x16x32_bf16 v[68:71], v[176:179], v[216:219], v[68:71]
	v_mfma_f32_16x16x32_bf16 v[64:67], v[184:187], v[216:219], v[64:67]
	s_barrier
	s_add_i32 s56, s46, s35
	v_lshl_add_u64 v[164:165], s[26:27], 0, v[132:133]
	s_mov_b32 m0, s56
	ds_read_b128 v[188:191], v154 offset:16384
	ds_read_b128 v[192:195], v154 offset:17408
	ds_read_b128 v[196:199], v154 offset:18432
	ds_read_b128 v[200:203], v154 offset:19456
	ds_read_b128 v[204:207], v154 offset:20480
	ds_read_b128 v[208:211], v154 offset:21504
	ds_read_b128 v[212:215], v154 offset:22528
	ds_read_b128 v[216:219], v154 offset:23552
	global_load_lds_dwordx4 v[164:165], off
	s_add_i32 m0, s56, 0x2000
	s_add_u32 s56, s26, 0x80000
	v_lshl_add_u64 v[220:221], s[26:27], 0, v[128:129]
	s_addc_u32 s57, s27, 0
	s_add_i32 s58, s47, s35
	global_load_lds_dwordx4 v[220:221], off
	v_lshl_add_u64 v[222:223], s[56:57], 0, v[132:133]
	s_mov_b32 m0, s58
	v_lshl_add_u64 v[224:225], s[28:29], 0, v[130:131]
	global_load_lds_dwordx4 v[222:223], off
	v_lshl_add_u64 v[222:223], s[56:57], 0, v[128:129]
	s_add_i32 m0, s58, 0x2000
	s_nop 0
	global_load_lds_dwordx4 v[222:223], off
	v_lshl_add_u64 v[222:223], s[28:29], 0, v[134:135]
	s_mov_b32 m0, s23
	s_nop 0
	global_load_lds_dwordx4 v[222:223], off
	s_mov_b32 m0, s38
	s_nop 0
	global_load_lds_dwordx4 v[224:225], off
	s_waitcnt vmcnt(8)
	s_waitcnt lgkmcnt(0)
	s_barrier
; #define PG8_STAGE(bufoff, gbase, voff) do { _Pragma("unroll") for (int _i = 0; _i < 2; ++_i) \
;         __builtin_amdgcn_global_load_lds((const unsigned*)((const char*)(gbase) + (voff)[_i]), (LAS unsigned*)(lds + (bufoff) + ldsw + _i * 8192), 16, 0, 0); } while (0)
; #define PG8_LDA(dst, b, h) do { _Pragma("unroll") for (int m = 0; m < 4; ++m) _Pragma("unroll") for (int k = 0; k < 2; ++k) dst[m][k] = *(const LAS bf16x8*)(lds + PG8_SA(b, h) + aoff + m * 2048 + k * 1024); } while (0)
; #define PG8_LDB(dst, b, h) do { _Pragma("unroll") for (int n = 0; n < 2; ++n) _Pragma("unroll") for (int k = 0; k < 2; ++k) dst[n][k] = *(const LAS bf16x8*)(lds + PG8_SB(b, h) + boff + n * 2048 + k * 1024); } while (0)
; #define PG8_MMA(ai, bj, At, Bt) do { __builtin_amdgcn_s_setprio(1); _Pragma("unroll") for (int m = 0; m < 4; ++m) _Pragma("unroll") for (int n = 0; n < 2; ++n) _Pragma("unroll") for (int k = 0; k < 2; ++k) \
;         acc[ai][bj][m][n] = __builtin_amdgcn_mfma_f32_16x16x32_bf16(Bt[n][k], At[m][k], acc[ai][bj][m][n], 0, 0, 0); __builtin_amdgcn_s_setprio(0); } while (0)
; #define PG8_WAIT_V(n) asm volatile("s_waitcnt vmcnt(" #n ")" ::: "memory")
; #define PG8_WAIT_L(n) asm volatile("s_waitcnt lgkmcnt(" #n ")" ::: "memory")
; #define PG8_BAR __builtin_amdgcn_s_barrier()
; #define PG8_SCHED __builtin_amdgcn_sched_barrier(0)
; template <class Epi, bool ALIGN_EPI>
; __device__ __forceinline__ void gemm_phase(LAS unsigned char* lds, const Gemm g, const StaticOrder& S, const Epi& E) {
;     ...
;             PG8_WAIT_V(8); PG8_WAIT_L(0); PG8_BAR; PG8_MMA(1, 0, At, B0); PG8_MMA(1, 1, At, B1); PG8_BAR; PG8_SCHED;
;             PG8_LDB(B0, 1, 0); PG8_LDB(B1, 1, 1); PG8_SCHED; PG8_LDA(At, 1, 0); PG8_STAGE(PG8_SA(0, 1), a2 + hstepA, voffA);
;             PG8_WAIT_V(8); PG8_WAIT_L(0); PG8_BAR; PG8_MMA(0, 0, At, B0); PG8_MMA(0, 1, At, B1); PG8_BAR; PG8_SCHED;
;             PG8_LDA(At, 1, 1); PG8_STAGE(PG8_SB(1, 0), b3, voffB); PG8_STAGE(PG8_SB(1, 1), b3 + hstepB, voffB); PG8_STAGE(PG8_SA(1, 0), a3, voffA);
	v_mfma_f32_16x16x32_bf16 v[60:63], v[144:147], v[188:191], v[60:63]
	v_mfma_f32_16x16x32_bf16 v[56:59], v[160:163], v[188:191], v[56:59]
	v_mfma_f32_16x16x32_bf16 v[44:47], v[144:147], v[196:199], v[44:47]
	v_mfma_f32_16x16x32_bf16 v[40:43], v[160:163], v[196:199], v[40:43]
	v_mfma_f32_16x16x32_bf16 v[28:31], v[144:147], v[204:207], v[28:31]
	v_mfma_f32_16x16x32_bf16 v[24:27], v[160:163], v[204:207], v[24:27]
	v_mfma_f32_16x16x32_bf16 v[12:15], v[144:147], v[212:215], v[12:15]
	v_mfma_f32_16x16x32_bf16 v[8:11], v[160:163], v[212:215], v[8:11]
	v_mfma_f32_16x16x32_bf16 v[60:63], v[156:159], v[192:195], v[60:63]
	v_mfma_f32_16x16x32_bf16 v[56:59], v[168:171], v[192:195], v[56:59]
	v_mfma_f32_16x16x32_bf16 v[44:47], v[156:159], v[200:203], v[44:47]
	v_mfma_f32_16x16x32_bf16 v[40:43], v[168:171], v[200:203], v[40:43]
	v_mfma_f32_16x16x32_bf16 v[28:31], v[156:159], v[208:211], v[28:31]
	v_mfma_f32_16x16x32_bf16 v[24:27], v[168:171], v[208:211], v[24:27]
	v_mfma_f32_16x16x32_bf16 v[12:15], v[156:159], v[216:219], v[12:15]
	v_mfma_f32_16x16x32_bf16 v[8:11], v[168:171], v[216:219], v[8:11]
	v_mfma_f32_16x16x32_bf16 v[52:55], v[172:175], v[188:191], v[52:55]
	v_mfma_f32_16x16x32_bf16 v[48:51], v[180:183], v[188:191], v[48:51]
	v_mfma_f32_16x16x32_bf16 v[36:39], v[172:175], v[196:199], v[36:39]
	v_mfma_f32_16x16x32_bf16 v[32:35], v[180:183], v[196:199], v[32:35]
	v_mfma_f32_16x16x32_bf16 v[20:23], v[172:175], v[204:207], v[20:23]
	v_mfma_f32_16x16x32_bf16 v[16:19], v[180:183], v[204:207], v[16:19]
	v_mfma_f32_16x16x32_bf16 v[4:7], v[172:175], v[212:215], v[4:7]
	v_mfma_f32_16x16x32_bf16 v[0:3], v[180:183], v[212:215], v[0:3]
	v_mfma_f32_16x16x32_bf16 v[52:55], v[176:179], v[192:195], v[52:55]
	v_mfma_f32_16x16x32_bf16 v[48:51], v[184:187], v[192:195], v[48:51]
	v_mfma_f32_16x16x32_bf16 v[36:39], v[176:179], v[200:203], v[36:39]
	v_mfma_f32_16x16x32_bf16 v[32:35], v[184:187], v[200:203], v[32:35]
	v_mfma_f32_16x16x32_bf16 v[20:23], v[176:179], v[208:211], v[20:23]
	v_mfma_f32_16x16x32_bf16 v[16:19], v[184:187], v[208:211], v[16:19]
	v_mfma_f32_16x16x32_bf16 v[4:7], v[176:179], v[216:219], v[4:7]
	v_mfma_f32_16x16x32_bf16 v[0:3], v[184:187], v[216:219], v[0:3]
	s_barrier
	s_add_i32 s56, 0, 0x18000
	v_add_u32_e32 v155, s56, v150
	s_add_i32 s57, 0, 0x1c000
	ds_read_b128 v[144:147], v155
	ds_read_b128 v[156:159], v155 offset:1024
	ds_read_b128 v[160:163], v155 offset:2048
	ds_read_b128 v[168:171], v155 offset:3072
	v_add_u32_e32 v155, s57, v150
	ds_read_b128 v[172:175], v155
	ds_read_b128 v[176:179], v155 offset:1024
	ds_read_b128 v[180:183], v155 offset:2048
	ds_read_b128 v[184:187], v155 offset:3072
	s_add_u32 s28, s28, 0x80000
	s_addc_u32 s29, s29, 0
	s_mov_b32 m0, s39
	v_lshl_add_u64 v[226:227], s[28:29], 0, v[134:135]
	ds_read_b128 v[188:191], v154 offset:32768
	ds_read_b128 v[192:195], v154 offset:33792
	ds_read_b128 v[196:199], v154 offset:34816
	ds_read_b128 v[200:203], v154 offset:35840
	ds_read_b128 v[204:207], v154 offset:36864
	ds_read_b128 v[208:211], v154 offset:37888
	ds_read_b128 v[212:215], v154 offset:38912
	ds_read_b128 v[216:219], v154 offset:39936
	global_load_lds_dwordx4 v[226:227], off
	v_lshl_add_u64 v[226:227], s[28:29], 0, v[130:131]
	s_mov_b32 m0, s40
	s_nop 0
	global_load_lds_dwordx4 v[226:227], off
	s_waitcnt vmcnt(8)
	s_waitcnt lgkmcnt(0)
	s_barrier
	v_mfma_f32_16x16x32_bf16 v[124:127], v[144:147], v[188:191], v[124:127]
	v_mfma_f32_16x16x32_bf16 v[120:123], v[160:163], v[188:191], v[120:123]
	v_mfma_f32_16x16x32_bf16 v[108:111], v[144:147], v[196:199], v[108:111]
	v_mfma_f32_16x16x32_bf16 v[104:107], v[160:163], v[196:199], v[104:107]
	v_mfma_f32_16x16x32_bf16 v[92:95], v[144:147], v[204:207], v[92:95]
	v_mfma_f32_16x16x32_bf16 v[88:91], v[160:163], v[204:207], v[88:91]
	v_mfma_f32_16x16x32_bf16 v[76:79], v[144:147], v[212:215], v[76:79]
	v_mfma_f32_16x16x32_bf16 v[72:75], v[160:163], v[212:215], v[72:75]
	v_mfma_f32_16x16x32_bf16 v[124:127], v[156:159], v[192:195], v[124:127]
	v_mfma_f32_16x16x32_bf16 v[120:123], v[168:171], v[192:195], v[120:123]
	v_mfma_f32_16x16x32_bf16 v[108:111], v[156:159], v[200:203], v[108:111]
	v_mfma_f32_16x16x32_bf16 v[104:107], v[168:171], v[200:203], v[104:107]
	v_mfma_f32_16x16x32_bf16 v[92:95], v[156:159], v[208:211], v[92:95]
	v_mfma_f32_16x16x32_bf16 v[88:91], v[168:171], v[208:211], v[88:91]
	v_mfma_f32_16x16x32_bf16 v[76:79], v[156:159], v[216:219], v[76:79]
	v_mfma_f32_16x16x32_bf16 v[72:75], v[168:171], v[216:219], v[72:75]
	v_mfma_f32_16x16x32_bf16 v[116:119], v[172:175], v[188:191], v[116:119]
	v_mfma_f32_16x16x32_bf16 v[112:115], v[180:183], v[188:191], v[112:115]
	v_mfma_f32_16x16x32_bf16 v[100:103], v[172:175], v[196:199], v[100:103]
	v_mfma_f32_16x16x32_bf16 v[96:99], v[180:183], v[196:199], v[96:99]
	v_mfma_f32_16x16x32_bf16 v[84:87], v[172:175], v[204:207], v[84:87]
	v_mfma_f32_16x16x32_bf16 v[80:83], v[180:183], v[204:207], v[80:83]
	v_mfma_f32_16x16x32_bf16 v[68:71], v[172:175], v[212:215], v[68:71]
	v_mfma_f32_16x16x32_bf16 v[64:67], v[180:183], v[212:215], v[64:67]
	v_mfma_f32_16x16x32_bf16 v[116:119], v[176:179], v[192:195], v[116:119]
	v_mfma_f32_16x16x32_bf16 v[112:115], v[184:187], v[192:195], v[112:115]
	v_mfma_f32_16x16x32_bf16 v[100:103], v[176:179], v[200:203], v[100:103]
	v_mfma_f32_16x16x32_bf16 v[96:99], v[184:187], v[200:203], v[96:99]
	v_mfma_f32_16x16x32_bf16 v[84:87], v[176:179], v[208:211], v[84:87]
	v_mfma_f32_16x16x32_bf16 v[80:83], v[184:187], v[208:211], v[80:83]
	v_mfma_f32_16x16x32_bf16 v[68:71], v[176:179], v[216:219], v[68:71]
	v_mfma_f32_16x16x32_bf16 v[64:67], v[184:187], v[216:219], v[64:67]
	s_barrier
; #define PG8_STAGE(bufoff, gbase, voff) do { _Pragma("unroll") for (int _i = 0; _i < 2; ++_i) \
;         __builtin_amdgcn_global_load_lds((const unsigned*)((const char*)(gbase) + (voff)[_i]), (LAS unsigned*)(lds + (bufoff) + ldsw + _i * 8192), 16, 0, 0); } while (0)
; #define PG8_LDA(dst, b, h) do { _Pragma("unroll") for (int m = 0; m < 4; ++m) _Pragma("unroll") for (int k = 0; k < 2; ++k) dst[m][k] = *(const LAS bf16x8*)(lds + PG8_SA(b, h) + aoff + m * 2048 + k * 1024); } while (0)
; #define PG8_MMA(ai, bj, At, Bt) do { __builtin_amdgcn_s_setprio(1); _Pragma("unroll") for (int m = 0; m < 4; ++m) _Pragma("unroll") for (int n = 0; n < 2; ++n) _Pragma("unroll") for (int k = 0; k < 2; ++k) \
;         acc[ai][bj][m][n] = __builtin_amdgcn_mfma_f32_16x16x32_bf16(Bt[n][k], At[m][k], acc[ai][bj][m][n], 0, 0, 0); __builtin_amdgcn_s_setprio(0); } while (0)
; #define PG8_WAIT_V(n) asm volatile("s_waitcnt vmcnt(" #n ")" ::: "memory")
; #define PG8_WAIT_L(n) asm volatile("s_waitcnt lgkmcnt(" #n ")" ::: "memory")
; #define PG8_BAR __builtin_amdgcn_s_barrier()
; #define PG8_SCHED __builtin_amdgcn_sched_barrier(0)
; template <class Epi, bool ALIGN_EPI>
; __device__ __forceinline__ void gemm_phase(LAS unsigned char* lds, const Gemm g, const StaticOrder& S, const Epi& E) {
;     ...
;             PG8_LDA(At, 1, 1); PG8_STAGE(PG8_SB(1, 0), b3, voffB); PG8_STAGE(PG8_SB(1, 1), b3 + hstepB, voffB); PG8_STAGE(PG8_SA(1, 0), a3, voffA);
;             PG8_WAIT_V(8); PG8_WAIT_L(0); PG8_BAR; PG8_MMA(1, 0, At, B0); PG8_MMA(1, 1, At, B1); PG8_BAR; PG8_SCHED;
;         }
	s_add_i32 s28, s56, s35
	v_lshl_add_u64 v[164:165], v[164:165], 0, s[10:11]
	s_mov_b32 m0, s28
	ds_read_b128 v[188:191], v154 offset:49152
	ds_read_b128 v[192:195], v154 offset:50176
	ds_read_b128 v[196:199], v154 offset:51200
	ds_read_b128 v[200:203], v154 offset:52224
	ds_read_b128 v[204:207], v154 offset:53248
	ds_read_b128 v[208:211], v154 offset:54272
	ds_read_b128 v[212:215], v154 offset:55296
	ds_read_b128 v[216:219], v154 offset:56320
	global_load_lds_dwordx4 v[164:165], off
	s_add_i32 m0, s28, 0x2000
	s_add_u32 s26, s26, 0x80080
	v_lshl_add_u64 v[164:165], v[220:221], 0, s[10:11]
	s_addc_u32 s27, s27, 0
	s_add_i32 s28, s57, s35
	global_load_lds_dwordx4 v[164:165], off
	v_lshl_add_u64 v[164:165], s[26:27], 0, v[132:133]
	s_mov_b32 m0, s28
	s_nop 0
	global_load_lds_dwordx4 v[164:165], off
	v_lshl_add_u64 v[164:165], s[26:27], 0, v[128:129]
	s_add_i32 m0, s28, 0x2000
	s_nop 0
	global_load_lds_dwordx4 v[164:165], off
	v_lshl_add_u64 v[164:165], v[222:223], 0, s[10:11]
	s_mov_b32 m0, s41
	s_nop 0
	global_load_lds_dwordx4 v[164:165], off
	v_lshl_add_u64 v[164:165], v[224:225], 0, s[10:11]
	s_mov_b32 m0, s42
	s_nop 0
	global_load_lds_dwordx4 v[164:165], off
	s_waitcnt vmcnt(8)
	s_waitcnt lgkmcnt(0)
	s_barrier
	v_mfma_f32_16x16x32_bf16 v[60:63], v[144:147], v[188:191], v[60:63]
	v_mfma_f32_16x16x32_bf16 v[56:59], v[160:163], v[188:191], v[56:59]
	v_mfma_f32_16x16x32_bf16 v[44:47], v[144:147], v[196:199], v[44:47]
	v_mfma_f32_16x16x32_bf16 v[40:43], v[160:163], v[196:199], v[40:43]
	v_mfma_f32_16x16x32_bf16 v[28:31], v[144:147], v[204:207], v[28:31]
	v_mfma_f32_16x16x32_bf16 v[24:27], v[160:163], v[204:207], v[24:27]
	v_mfma_f32_16x16x32_bf16 v[12:15], v[144:147], v[212:215], v[12:15]
	v_mfma_f32_16x16x32_bf16 v[8:11], v[160:163], v[212:215], v[8:11]
	v_mfma_f32_16x16x32_bf16 v[60:63], v[156:159], v[192:195], v[60:63]
	v_mfma_f32_16x16x32_bf16 v[56:59], v[168:171], v[192:195], v[56:59]
	v_mfma_f32_16x16x32_bf16 v[44:47], v[156:159], v[200:203], v[44:47]
	v_mfma_f32_16x16x32_bf16 v[40:43], v[168:171], v[200:203], v[40:43]
	v_mfma_f32_16x16x32_bf16 v[28:31], v[156:159], v[208:211], v[28:31]
	v_mfma_f32_16x16x32_bf16 v[24:27], v[168:171], v[208:211], v[24:27]
	v_mfma_f32_16x16x32_bf16 v[12:15], v[156:159], v[216:219], v[12:15]
	v_mfma_f32_16x16x32_bf16 v[8:11], v[168:171], v[216:219], v[8:11]
	v_mfma_f32_16x16x32_bf16 v[52:55], v[172:175], v[188:191], v[52:55]
	v_mfma_f32_16x16x32_bf16 v[48:51], v[180:183], v[188:191], v[48:51]
	v_mfma_f32_16x16x32_bf16 v[36:39], v[172:175], v[196:199], v[36:39]
	v_mfma_f32_16x16x32_bf16 v[32:35], v[180:183], v[196:199], v[32:35]
	v_mfma_f32_16x16x32_bf16 v[20:23], v[172:175], v[204:207], v[20:23]
	v_mfma_f32_16x16x32_bf16 v[16:19], v[180:183], v[204:207], v[16:19]
	v_mfma_f32_16x16x32_bf16 v[4:7], v[172:175], v[212:215], v[4:7]
	v_mfma_f32_16x16x32_bf16 v[0:3], v[180:183], v[212:215], v[0:3]
	v_mfma_f32_16x16x32_bf16 v[52:55], v[176:179], v[192:195], v[52:55]
	v_mfma_f32_16x16x32_bf16 v[48:51], v[184:187], v[192:195], v[48:51]
	v_mfma_f32_16x16x32_bf16 v[36:39], v[176:179], v[200:203], v[36:39]
	v_mfma_f32_16x16x32_bf16 v[32:35], v[184:187], v[200:203], v[32:35]
	v_mfma_f32_16x16x32_bf16 v[20:23], v[176:179], v[208:211], v[20:23]
	v_mfma_f32_16x16x32_bf16 v[16:19], v[184:187], v[208:211], v[16:19]
	v_mfma_f32_16x16x32_bf16 v[4:7], v[176:179], v[216:219], v[4:7]
	v_mfma_f32_16x16x32_bf16 v[0:3], v[184:187], v[216:219], v[0:3]
	s_barrier
	s_add_i32 s55, s55, 2
	s_add_u32 s53, s53, 0x100
	s_addc_u32 s54, s54, 0
	s_add_u32 s24, s24, 0x100
	s_addc_u32 s25, s25, 0
	s_cmp_gt_u32 s55, 29
	s_cbranch_scc0 .LBB0_121
	s_and_b64 vcc, exec, s[12:13]
	s_cbranch_vccz .LBB0_124
	s_barrier

; __device__ __forceinline__ unsigned f2bf(float f) { return (__builtin_bit_cast(unsigned, f) + 0x8000u) >> 16; }
; #define INP(k) ((const float*)PTR(k))
; #define WSP(off) (PTR(29) + (off))
; __device__ __forceinline__ void s5_gen(LAS unsigned char* lds, const float* a_re, const float* a_im, const float* log_dt, const float* b_re, const float* b_im, ...
;     ...
;         const int dir = tid >> 8, p = (tid >> 2) & 63, dq = tid & 3;
;         const float are = a_re[dir * 4096 + g * 64 + p], aim = a_im[dir * 4096 + g * 64 + p], dt = __expf(log_dt[dir * 64 + g]);
;         const float xr = are * dt, xi = aim * dt;
;         for (int d = dq; d <= 32; d += 4) { const float mag = expf((float)d * xr); float sn, cs; sincosf((float)d * xi, &sn, &cs); PW(dir, 0, d, p) = mag * cs; PW(dir, 1, d, p) = mag * sn; }
;         if (dq == 0) {
;             float sn, cs, sh; sincosf(xi, &sn, &cs); sh = sinf(0.5f * xi);
;             const float nr = expm1f(xr) * cs - 2.f * sh * sh, ni = expf(xr) * sn;
;             const float den = 1.f / (are * are + aim * aim);
;             const float cr = (nr * are + ni * aim) * den, ci = (ni * are - nr * aim) * den;
;             const float* br = b_re + ((size_t)(dir * 64 + g) * 64 + p) * 16; const float* bi = b_im + ((size_t)(dir * 64 + g) * 64 + p) * 16;
;             for (int ch = 0; ch < 16; ++ch) { const float x = br[ch], y = bi[ch], zr = cr * x - ci * y, zi = cr * y + ci * x;
;                 BB(dir, 0, p, ch) = zr; BB(dir, 1, p, ch) = zi; bt[(dir * 16 + ch) * 136 + p] = (bf16_t)f2bf(zr); bt[(dir * 16 + ch) * 136 + 64 + p] = (bf16_t)f2bf(zi); }
; template <int K>
; __device__ __forceinline__ void run_phase(LAS unsigned char* lds, volatile LAS unsigned* ptab) {
;     ...
;         for (int u = bx; u < 256; u += G)
;             s5_gen(lds, INP(13), INP(14), INP(15), INP(16), INP(17), INP(18), INP(19), INP(20),
;                    (bf16_t*)WSP(WS_S5W1) + (size_t)(u >> 2) * 256 * 512, (bf16_t*)WSP(WS_S5W3) + (size_t)(u >> 2) * 512 * 768, u >> 2, u & 3, tid);
.Lprio_skip_1:
	v_mov_b32_e32 v9, v166
	s_cmpk_gt_i32 s3, 0xff
	s_waitcnt lgkmcnt(0)
	s_barrier
	s_cbranch_scc1 .LBB0_294
	s_add_i32 s8, 0, 0x2306c
	v_mov_b32_e32 v32, s8
	s_add_i32 s8, 0, 0x23068
	v_mov_b32_e32 v33, s8
	s_add_i32 s8, 0, 0x23074
	v_mov_b32_e32 v34, s8
	s_add_i32 s8, 0, 0x23070
	v_mov_b32_e32 v35, s8
	s_add_i32 s8, 0, 0x2307c
	v_mov_b32_e32 v36, s8
	s_add_i32 s8, 0, 0x23078
	v_mov_b32_e32 v37, s8
	s_add_i32 s8, 0, 0x23084
	v_mov_b32_e32 v38, s8
	s_add_i32 s8, 0, 0x23080
	v_mov_b32_e32 v39, s8
	s_add_i32 s8, 0, 0x2308c
	v_mov_b32_e32 v40, s8
	s_add_i32 s8, 0, 0x23088
	v_ashrrev_i32_e32 v1, 8, v9
	v_bfe_u32 v2, v9, 2, 6
	v_mov_b32_e32 v41, s8
	s_add_i32 s8, 0, 0x23094
	v_mul_i32_i24_e32 v0, 0x1100, v1
	s_add_i32 s2, 0, 0x1c400
	v_lshlrev_b32_e32 v5, 1, v2
	v_mov_b32_e32 v42, s8
	s_add_i32 s8, 0, 0x23090
	v_add3_u32 v24, s2, v0, v5
	v_bfe_u32 v5, v9, 4, 2
	v_mov_b32_e32 v43, s8
	s_add_i32 s8, 0, 0x2309c
	v_lshl_add_u32 v27, v5, 4, s2
	s_movk_i32 s2, 0x1000
	v_mov_b32_e32 v44, s8
	s_add_i32 s8, 0, 0x23098
	v_cmp_gt_i32_e64 s[4:5], s2, v9
	s_movk_i32 s2, 0x3000
	v_mov_b32_e32 v45, s8
	s_add_i32 s8, 0, 0x230a4
	v_and_b32_e32 v13, 3, v9
	v_cmp_gt_i32_e64 s[6:7], s2, v9
	s_movk_i32 s2, 0x42
	v_mov_b32_e32 v46, s8
	s_add_i32 s8, 0, 0x230a0
	v_lshl_or_b32 v17, v1, 12, v2
	v_lshlrev_b32_e32 v19, 6, v1
	v_lshlrev_b32_e32 v8, 4, v2
	v_lshl_add_u32 v3, v1, 13, 0
	v_lshlrev_b32_e32 v4, 6, v2
	v_and_b32_e32 v26, 15, v9
	v_mad_i32_i24 v1, v1, s2, v13
	v_lshlrev_b32_e32 v2, 2, v2
	v_mov_b32_e32 v47, s8
	s_add_i32 s8, 0, 0x230ec
	v_ashrrev_i32_e32 v25, 6, v9
	v_lshlrev_b32_e32 v0, 3, v5
	v_lshlrev_b32_e32 v6, 8, v5
	v_lshlrev_b32_e32 v7, 2, v26
	v_lshl_or_b32 v1, v1, 8, v2
	v_mov_b32_e32 v48, s8
	s_add_i32 s8, 0, 0x230e8
	v_cmp_eq_u32_e64 s[0:1], 0, v13
	v_mov_b32_e32 v11, 0
	v_cmp_gt_i32_e64 s[12:13], 40, v25
	v_lshlrev_b32_e32 v12, 6, v26
	v_add3_u32 v28, 0, v6, v7
	v_lshl_add_u32 v29, v5, 5, 0
	v_add_u32_e32 v30, 0, v1
	v_lshlrev_b32_e32 v31, 3, v9
	v_mov_b32_e32 v49, s8
	s_mov_b32 s33, 0x3fb8aa3b
	s_brev_b32 s36, 18
	s_mov_b32 s37, 0xfe5163ab
	s_mov_b32 s38, 0x3c439041
	s_mov_b32 s39, 0xdb629599
	s_mov_b32 s40, 0xf534ddc0
	s_mov_b32 s41, 0xfc2757d1
	s_mov_b32 s42, 0x4e441529
	s_mov_b32 s43, 0xa2f9836e
	s_mov_b32 s44, 0x3fc90fda
	s_mov_b32 s45, 0x3f22f983
	s_mov_b32 s46, 0xbfc90fda
	s_mov_b32 s47, 0xc2ce8ed0
	s_mov_b32 s48, 0x42b17218
	v_mov_b32_e32 v50, 0x3c0881c4
	v_mov_b32_e32 v51, 0xbab64f3b
	s_brev_b32 s49, 1
	s_movk_i32 s50, 0x1f8
	v_mov_b32_e32 v52, 0x3ab69700
	s_mov_b32 s51, 0x43000000
	s_mov_b32 s52, 0x42b17217
	s_mov_b32 s53, 0xc1880000
	v_add_u32_e32 v53, v3, v4
	v_lshlrev_b32_e32 v14, 2, v0
	s_movk_i32 s54, 0x110
	s_mov_b32 s55, 0x7060302
	s_movk_i32 s56, 0x80
	s_movk_i32 s57, 0xdff
	s_mov_b32 s58, 0x2aaaaaab
	s_movk_i32 s59, 0xffa0
	s_movk_i32 s60, 0xfd00
	s_mov_b32 s61, 0xc400
	s_movk_i32 s62, 0x600
	s_movk_i32 s63, 0x2dff
	v_not_b32_e32 v54, 63
	v_not_b32_e32 v55, 31
	v_mov_b32_e32 v56, 0x7f800000
	v_mov_b32_e32 v57, 0x7fc00000
	v_mov_b32_e32 v58, 0x7f000000
	v_mov_b32_e32 v59, 0x42
	s_mov_b32 s64, s3
	s_branch .LBB0_217

; #define PG8_STAGE(bufoff, gbase, voff) do { _Pragma("unroll") for (int _i = 0; _i < 2; ++_i) \
;         __builtin_amdgcn_global_load_lds((const unsigned*)((const char*)(gbase) + (voff)[_i]), (LAS unsigned*)(lds + (bufoff) + ldsw + _i * 8192), 16, 0, 0); } while (0)
; #define PG8_LDA(dst, b, h) do { _Pragma("unroll") for (int m = 0; m < 4; ++m) _Pragma("unroll") for (int k = 0; k < 2; ++k) dst[m][k] = *(const LAS bf16x8*)(lds + PG8_SA(b, h) + aoff + m * 2048 + k * 1024); } while (0)
; #define PG8_LDB(dst, b, h) do { _Pragma("unroll") for (int n = 0; n < 2; ++n) _Pragma("unroll") for (int k = 0; k < 2; ++k) dst[n][k] = *(const LAS bf16x8*)(lds + PG8_SB(b, h) + boff + n * 2048 + k * 1024); } while (0)
; #define PG8_MMA(ai, bj, At, Bt) do { __builtin_amdgcn_s_setprio(1); _Pragma("unroll") for (int m = 0; m < 4; ++m) _Pragma("unroll") for (int n = 0; n < 2; ++n) _Pragma("unroll") for (int k = 0; k < 2; ++k) \
;         acc[ai][bj][m][n] = __builtin_amdgcn_mfma_f32_16x16x32_bf16(Bt[n][k], At[m][k], acc[ai][bj][m][n], 0, 0, 0); __builtin_amdgcn_s_setprio(0); } while (0)
; #define PG8_WAIT_V(n) asm volatile("s_waitcnt vmcnt(" #n ")" ::: "memory")
; #define PG8_WAIT_L(n) asm volatile("s_waitcnt lgkmcnt(" #n ")" ::: "memory")
; #define PG8_BAR __builtin_amdgcn_s_barrier()
; #define PG8_SCHED __builtin_amdgcn_sched_barrier(0)
; template <class Epi, bool ALIGN_EPI>
; __device__ __forceinline__ void gemm_phase(LAS unsigned char* lds, const Gemm g, const StaticOrder& S, const Epi& E) {
;     ...
;             PG8_LDB(B0, 0, 0); PG8_LDB(B1, 0, 1); PG8_SCHED; PG8_LDA(At, 0, 0); PG8_STAGE(PG8_SA(1, 1), a1 + hstepA, voffA);
;             PG8_WAIT_V(8); PG8_WAIT_L(0); PG8_BAR; PG8_MMA(0, 0, At, B0); PG8_MMA(0, 1, At, B1); PG8_BAR; PG8_SCHED;
;             PG8_LDA(At, 0, 1); PG8_STAGE(PG8_SB(0, 0), b2, voffB); PG8_STAGE(PG8_SB(0, 1), b2 + hstepB, voffB); PG8_STAGE(PG8_SA(0, 0), a2, voffA);
;             PG8_WAIT_V(8); PG8_WAIT_L(0); PG8_BAR; PG8_MMA(1, 0, At, B0); PG8_MMA(1, 1, At, B1); PG8_BAR; PG8_SCHED;
.LBB0_309:
	ds_read_b128 v[64:67], v171
	ds_read_b128 v[72:75], v171 offset:1024
	ds_read_b128 v[80:83], v171 offset:2048
	ds_read_b128 v[84:87], v171 offset:3072
	ds_read_b128 v[156:159], v172
	ds_read_b128 v[160:163], v172 offset:1024
	ds_read_b128 v[176:179], v172 offset:2048
	ds_read_b128 v[180:183], v172 offset:3072
	s_add_u32 s4, s30, 0x100
	s_addc_u32 s5, s31, 0
	s_cmpk_eq_i32 s65, 0x54
	s_cselect_b32 s37, s27, s5
	s_cselect_b32 s36, s26, s4
	s_cselect_b32 s35, s29, s64
	s_cselect_b32 s34, s28, s63
	v_lshl_add_u64 v[164:165], s[30:31], 0, v[150:151]
	s_add_i32 m0, s43, 0xc000
	ds_read_b128 v[184:187], v173
	ds_read_b128 v[188:191], v173 offset:1024
	ds_read_b128 v[192:195], v173 offset:2048
	ds_read_b128 v[196:199], v173 offset:3072
	ds_read_b128 v[200:203], v173 offset:4096
	ds_read_b128 v[204:207], v173 offset:5120
	ds_read_b128 v[208:211], v173 offset:6144
	ds_read_b128 v[212:215], v173 offset:7168
	global_load_lds_dwordx4 v[164:165], off
	v_lshl_add_u64 v[164:165], s[30:31], 0, v[148:149]
	s_add_i32 m0, s43, 0xe000
	s_nop 0
	global_load_lds_dwordx4 v[164:165], off
	s_waitcnt vmcnt(8)
	s_waitcnt lgkmcnt(0)
	s_barrier
	v_mfma_f32_16x16x32_bf16 v[140:143], v[64:67], v[184:187], v[140:143]
	v_mfma_f32_16x16x32_bf16 v[136:139], v[80:83], v[184:187], v[136:139]
	v_mfma_f32_16x16x32_bf16 v[124:127], v[64:67], v[192:195], v[124:127]
	v_mfma_f32_16x16x32_bf16 v[120:123], v[80:83], v[192:195], v[120:123]
	v_mfma_f32_16x16x32_bf16 v[108:111], v[64:67], v[200:203], v[108:111]
	v_mfma_f32_16x16x32_bf16 v[104:107], v[80:83], v[200:203], v[104:107]
	v_mfma_f32_16x16x32_bf16 v[92:95], v[64:67], v[208:211], v[92:95]
	v_mfma_f32_16x16x32_bf16 v[88:91], v[80:83], v[208:211], v[88:91]
	v_mfma_f32_16x16x32_bf16 v[140:143], v[72:75], v[188:191], v[140:143]
	v_mfma_f32_16x16x32_bf16 v[136:139], v[84:87], v[188:191], v[136:139]
	v_mfma_f32_16x16x32_bf16 v[124:127], v[72:75], v[196:199], v[124:127]
	v_mfma_f32_16x16x32_bf16 v[120:123], v[84:87], v[196:199], v[120:123]
	v_mfma_f32_16x16x32_bf16 v[108:111], v[72:75], v[204:207], v[108:111]
	v_mfma_f32_16x16x32_bf16 v[104:107], v[84:87], v[204:207], v[104:107]
	v_mfma_f32_16x16x32_bf16 v[92:95], v[72:75], v[212:215], v[92:95]
	v_mfma_f32_16x16x32_bf16 v[88:91], v[84:87], v[212:215], v[88:91]
	v_mfma_f32_16x16x32_bf16 v[132:135], v[156:159], v[184:187], v[132:135]
	v_mfma_f32_16x16x32_bf16 v[128:131], v[176:179], v[184:187], v[128:131]
	v_mfma_f32_16x16x32_bf16 v[116:119], v[156:159], v[192:195], v[116:119]
	v_mfma_f32_16x16x32_bf16 v[112:115], v[176:179], v[192:195], v[112:115]
	v_mfma_f32_16x16x32_bf16 v[100:103], v[156:159], v[200:203], v[100:103]
	v_mfma_f32_16x16x32_bf16 v[96:99], v[176:179], v[200:203], v[96:99]
	v_mfma_f32_16x16x32_bf16 v[76:79], v[156:159], v[208:211], v[76:79]
	v_mfma_f32_16x16x32_bf16 v[68:71], v[176:179], v[208:211], v[68:71]
	v_mfma_f32_16x16x32_bf16 v[132:135], v[160:163], v[188:191], v[132:135]
	v_mfma_f32_16x16x32_bf16 v[128:131], v[180:183], v[188:191], v[128:131]
	v_mfma_f32_16x16x32_bf16 v[116:119], v[160:163], v[196:199], v[116:119]
	v_mfma_f32_16x16x32_bf16 v[112:115], v[180:183], v[196:199], v[112:115]
	v_mfma_f32_16x16x32_bf16 v[100:103], v[160:163], v[204:207], v[100:103]
	v_mfma_f32_16x16x32_bf16 v[96:99], v[180:183], v[204:207], v[96:99]
	v_mfma_f32_16x16x32_bf16 v[76:79], v[160:163], v[212:215], v[76:79]
	v_mfma_f32_16x16x32_bf16 v[68:71], v[180:183], v[212:215], v[68:71]
	s_barrier
	s_add_i32 s30, s56, s42
	v_lshl_add_u64 v[164:165], s[34:35], 0, v[144:145]
	s_mov_b32 m0, s30
	ds_read_b128 v[184:187], v173 offset:16384
	ds_read_b128 v[188:191], v173 offset:17408
	ds_read_b128 v[192:195], v173 offset:18432
	ds_read_b128 v[196:199], v173 offset:19456
	ds_read_b128 v[200:203], v173 offset:20480
	ds_read_b128 v[204:207], v173 offset:21504
	ds_read_b128 v[208:211], v173 offset:22528
	ds_read_b128 v[212:215], v173 offset:23552
	global_load_lds_dwordx4 v[164:165], off
	s_add_i32 m0, s30, 0x2000
	s_add_u32 s30, s34, 0x160000
	v_lshl_add_u64 v[216:217], s[34:35], 0, v[146:147]
	s_addc_u32 s31, s35, 0
	s_add_i32 s66, s57, s42
	global_load_lds_dwordx4 v[216:217], off
	v_lshl_add_u64 v[218:219], s[30:31], 0, v[144:145]
	s_mov_b32 m0, s66
	v_lshl_add_u64 v[220:221], s[36:37], 0, v[146:147]
	global_load_lds_dwordx4 v[218:219], off
	v_lshl_add_u64 v[218:219], s[30:31], 0, v[146:147]
	s_add_i32 m0, s66, 0x2000
	s_nop 0
	global_load_lds_dwordx4 v[218:219], off
	v_lshl_add_u64 v[218:219], s[36:37], 0, v[144:145]
	s_mov_b32 m0, s43
	s_nop 0
	global_load_lds_dwordx4 v[218:219], off
	s_mov_b32 m0, s44
	s_nop 0
	global_load_lds_dwordx4 v[220:221], off
	s_waitcnt vmcnt(8)
	s_waitcnt lgkmcnt(0)
	s_barrier
; #define PG8_STAGE(bufoff, gbase, voff) do { _Pragma("unroll") for (int _i = 0; _i < 2; ++_i) \
;         __builtin_amdgcn_global_load_lds((const unsigned*)((const char*)(gbase) + (voff)[_i]), (LAS unsigned*)(lds + (bufoff) + ldsw + _i * 8192), 16, 0, 0); } while (0)
; #define PG8_LDA(dst, b, h) do { _Pragma("unroll") for (int m = 0; m < 4; ++m) _Pragma("unroll") for (int k = 0; k < 2; ++k) dst[m][k] = *(const LAS bf16x8*)(lds + PG8_SA(b, h) + aoff + m * 2048 + k * 1024); } while (0)
; #define PG8_LDB(dst, b, h) do { _Pragma("unroll") for (int n = 0; n < 2; ++n) _Pragma("unroll") for (int k = 0; k < 2; ++k) dst[n][k] = *(const LAS bf16x8*)(lds + PG8_SB(b, h) + boff + n * 2048 + k * 1024); } while (0)
; #define PG8_MMA(ai, bj, At, Bt) do { __builtin_amdgcn_s_setprio(1); _Pragma("unroll") for (int m = 0; m < 4; ++m) _Pragma("unroll") for (int n = 0; n < 2; ++n) _Pragma("unroll") for (int k = 0; k < 2; ++k) \
;         acc[ai][bj][m][n] = __builtin_amdgcn_mfma_f32_16x16x32_bf16(Bt[n][k], At[m][k], acc[ai][bj][m][n], 0, 0, 0); __builtin_amdgcn_s_setprio(0); } while (0)
; #define PG8_WAIT_V(n) asm volatile("s_waitcnt vmcnt(" #n ")" ::: "memory")
; #define PG8_WAIT_L(n) asm volatile("s_waitcnt lgkmcnt(" #n ")" ::: "memory")
; #define PG8_BAR __builtin_amdgcn_s_barrier()
; #define PG8_SCHED __builtin_amdgcn_sched_barrier(0)
; template <class Epi, bool ALIGN_EPI>
; __device__ __forceinline__ void gemm_phase(LAS unsigned char* lds, const Gemm g, const StaticOrder& S, const Epi& E) {
;     ...
;             PG8_WAIT_V(8); PG8_WAIT_L(0); PG8_BAR; PG8_MMA(1, 0, At, B0); PG8_MMA(1, 1, At, B1); PG8_BAR; PG8_SCHED;
;             PG8_LDB(B0, 1, 0); PG8_LDB(B1, 1, 1); PG8_SCHED; PG8_LDA(At, 1, 0); PG8_STAGE(PG8_SA(0, 1), a2 + hstepA, voffA);
;             PG8_WAIT_V(8); PG8_WAIT_L(0); PG8_BAR; PG8_MMA(0, 0, At, B0); PG8_MMA(0, 1, At, B1); PG8_BAR; PG8_SCHED;
;             PG8_LDA(At, 1, 1); PG8_STAGE(PG8_SB(1, 0), b3, voffB); PG8_STAGE(PG8_SB(1, 1), b3 + hstepB, voffB); PG8_STAGE(PG8_SA(1, 0), a3, voffA);
	v_mfma_f32_16x16x32_bf16 v[60:63], v[64:67], v[184:187], v[60:63]
	v_mfma_f32_16x16x32_bf16 v[56:59], v[80:83], v[184:187], v[56:59]
	v_mfma_f32_16x16x32_bf16 v[44:47], v[64:67], v[192:195], v[44:47]
	v_mfma_f32_16x16x32_bf16 v[40:43], v[80:83], v[192:195], v[40:43]
	v_mfma_f32_16x16x32_bf16 v[28:31], v[64:67], v[200:203], v[28:31]
	v_mfma_f32_16x16x32_bf16 v[24:27], v[80:83], v[200:203], v[24:27]
	v_mfma_f32_16x16x32_bf16 v[12:15], v[64:67], v[208:211], v[12:15]
	v_mfma_f32_16x16x32_bf16 v[8:11], v[80:83], v[208:211], v[8:11]
	v_mfma_f32_16x16x32_bf16 v[60:63], v[72:75], v[188:191], v[60:63]
	v_mfma_f32_16x16x32_bf16 v[56:59], v[84:87], v[188:191], v[56:59]
	v_mfma_f32_16x16x32_bf16 v[44:47], v[72:75], v[196:199], v[44:47]
	v_mfma_f32_16x16x32_bf16 v[40:43], v[84:87], v[196:199], v[40:43]
	v_mfma_f32_16x16x32_bf16 v[28:31], v[72:75], v[204:207], v[28:31]
	v_mfma_f32_16x16x32_bf16 v[24:27], v[84:87], v[204:207], v[24:27]
	v_mfma_f32_16x16x32_bf16 v[12:15], v[72:75], v[212:215], v[12:15]
	v_mfma_f32_16x16x32_bf16 v[8:11], v[84:87], v[212:215], v[8:11]
	v_mfma_f32_16x16x32_bf16 v[52:55], v[156:159], v[184:187], v[52:55]
	v_mfma_f32_16x16x32_bf16 v[48:51], v[176:179], v[184:187], v[48:51]
	v_mfma_f32_16x16x32_bf16 v[36:39], v[156:159], v[192:195], v[36:39]
	v_mfma_f32_16x16x32_bf16 v[32:35], v[176:179], v[192:195], v[32:35]
	v_mfma_f32_16x16x32_bf16 v[20:23], v[156:159], v[200:203], v[20:23]
	v_mfma_f32_16x16x32_bf16 v[16:19], v[176:179], v[200:203], v[16:19]
	v_mfma_f32_16x16x32_bf16 v[4:7], v[156:159], v[208:211], v[4:7]
	v_mfma_f32_16x16x32_bf16 v[0:3], v[176:179], v[208:211], v[0:3]
	v_mfma_f32_16x16x32_bf16 v[52:55], v[160:163], v[188:191], v[52:55]
	v_mfma_f32_16x16x32_bf16 v[48:51], v[180:183], v[188:191], v[48:51]
	v_mfma_f32_16x16x32_bf16 v[36:39], v[160:163], v[196:199], v[36:39]
	v_mfma_f32_16x16x32_bf16 v[32:35], v[180:183], v[196:199], v[32:35]
	v_mfma_f32_16x16x32_bf16 v[20:23], v[160:163], v[204:207], v[20:23]
	v_mfma_f32_16x16x32_bf16 v[16:19], v[180:183], v[204:207], v[16:19]
	v_mfma_f32_16x16x32_bf16 v[4:7], v[160:163], v[212:215], v[4:7]
	v_mfma_f32_16x16x32_bf16 v[0:3], v[180:183], v[212:215], v[0:3]
	s_barrier
	s_add_i32 s66, 0, 0x18000
	s_add_i32 s67, 0, 0x1c000
	v_add_u32_e32 v84, s66, v169
	v_add_u32_e32 v175, s67, v169
	ds_read_b128 v[64:67], v84
	ds_read_b128 v[72:75], v84 offset:1024
	ds_read_b128 v[80:83], v84 offset:2048
	ds_read_b128 v[84:87], v84 offset:3072
	ds_read_b128 v[156:159], v175
	ds_read_b128 v[160:163], v175 offset:1024
	ds_read_b128 v[176:179], v175 offset:2048
	ds_read_b128 v[180:183], v175 offset:3072
	s_add_u32 s30, s36, 0x160000
	s_addc_u32 s31, s37, 0
	s_mov_b32 m0, s45
	v_lshl_add_u64 v[222:223], s[30:31], 0, v[144:145]
	ds_read_b128 v[184:187], v173 offset:32768
	ds_read_b128 v[188:191], v173 offset:33792
	ds_read_b128 v[192:195], v173 offset:34816
	ds_read_b128 v[196:199], v173 offset:35840
	ds_read_b128 v[200:203], v173 offset:36864
	ds_read_b128 v[204:207], v173 offset:37888
	ds_read_b128 v[208:211], v173 offset:38912
	ds_read_b128 v[212:215], v173 offset:39936
	global_load_lds_dwordx4 v[222:223], off
	v_lshl_add_u64 v[222:223], s[30:31], 0, v[146:147]
	s_mov_b32 m0, s46
	s_nop 0
	global_load_lds_dwordx4 v[222:223], off
	s_waitcnt vmcnt(8)
	s_waitcnt lgkmcnt(0)
	s_barrier
	v_mfma_f32_16x16x32_bf16 v[140:143], v[64:67], v[184:187], v[140:143]
	v_mfma_f32_16x16x32_bf16 v[136:139], v[80:83], v[184:187], v[136:139]
	v_mfma_f32_16x16x32_bf16 v[124:127], v[64:67], v[192:195], v[124:127]
	v_mfma_f32_16x16x32_bf16 v[120:123], v[80:83], v[192:195], v[120:123]
	v_mfma_f32_16x16x32_bf16 v[108:111], v[64:67], v[200:203], v[108:111]
	v_mfma_f32_16x16x32_bf16 v[104:107], v[80:83], v[200:203], v[104:107]
	v_mfma_f32_16x16x32_bf16 v[92:95], v[64:67], v[208:211], v[92:95]
	v_mfma_f32_16x16x32_bf16 v[88:91], v[80:83], v[208:211], v[88:91]
	v_mfma_f32_16x16x32_bf16 v[140:143], v[72:75], v[188:191], v[140:143]
	v_mfma_f32_16x16x32_bf16 v[136:139], v[84:87], v[188:191], v[136:139]
	v_mfma_f32_16x16x32_bf16 v[124:127], v[72:75], v[196:199], v[124:127]
	v_mfma_f32_16x16x32_bf16 v[120:123], v[84:87], v[196:199], v[120:123]
	v_mfma_f32_16x16x32_bf16 v[108:111], v[72:75], v[204:207], v[108:111]
	v_mfma_f32_16x16x32_bf16 v[104:107], v[84:87], v[204:207], v[104:107]
	v_mfma_f32_16x16x32_bf16 v[92:95], v[72:75], v[212:215], v[92:95]
	v_mfma_f32_16x16x32_bf16 v[88:91], v[84:87], v[212:215], v[88:91]
	v_mfma_f32_16x16x32_bf16 v[132:135], v[156:159], v[184:187], v[132:135]
	v_mfma_f32_16x16x32_bf16 v[128:131], v[176:179], v[184:187], v[128:131]
	v_mfma_f32_16x16x32_bf16 v[116:119], v[156:159], v[192:195], v[116:119]
	v_mfma_f32_16x16x32_bf16 v[112:115], v[176:179], v[192:195], v[112:115]
	v_mfma_f32_16x16x32_bf16 v[100:103], v[156:159], v[200:203], v[100:103]
	v_mfma_f32_16x16x32_bf16 v[96:99], v[176:179], v[200:203], v[96:99]
	v_mfma_f32_16x16x32_bf16 v[76:79], v[156:159], v[208:211], v[76:79]
	v_mfma_f32_16x16x32_bf16 v[68:71], v[176:179], v[208:211], v[68:71]
	v_mfma_f32_16x16x32_bf16 v[132:135], v[160:163], v[188:191], v[132:135]
	v_mfma_f32_16x16x32_bf16 v[128:131], v[180:183], v[188:191], v[128:131]
	v_mfma_f32_16x16x32_bf16 v[116:119], v[160:163], v[196:199], v[116:119]
	v_mfma_f32_16x16x32_bf16 v[112:115], v[180:183], v[196:199], v[112:115]
	v_mfma_f32_16x16x32_bf16 v[100:103], v[160:163], v[204:207], v[100:103]
	v_mfma_f32_16x16x32_bf16 v[96:99], v[180:183], v[204:207], v[96:99]
	v_mfma_f32_16x16x32_bf16 v[76:79], v[160:163], v[212:215], v[76:79]
	v_mfma_f32_16x16x32_bf16 v[68:71], v[180:183], v[212:215], v[68:71]
	s_barrier
; #define PG8_STAGE(bufoff, gbase, voff) do { _Pragma("unroll") for (int _i = 0; _i < 2; ++_i) \
;         __builtin_amdgcn_global_load_lds((const unsigned*)((const char*)(gbase) + (voff)[_i]), (LAS unsigned*)(lds + (bufoff) + ldsw + _i * 8192), 16, 0, 0); } while (0)
; #define PG8_LDA(dst, b, h) do { _Pragma("unroll") for (int m = 0; m < 4; ++m) _Pragma("unroll") for (int k = 0; k < 2; ++k) dst[m][k] = *(const LAS bf16x8*)(lds + PG8_SA(b, h) + aoff + m * 2048 + k * 1024); } while (0)
; #define PG8_MMA(ai, bj, At, Bt) do { __builtin_amdgcn_s_setprio(1); _Pragma("unroll") for (int m = 0; m < 4; ++m) _Pragma("unroll") for (int n = 0; n < 2; ++n) _Pragma("unroll") for (int k = 0; k < 2; ++k) \
;         acc[ai][bj][m][n] = __builtin_amdgcn_mfma_f32_16x16x32_bf16(Bt[n][k], At[m][k], acc[ai][bj][m][n], 0, 0, 0); __builtin_amdgcn_s_setprio(0); } while (0)
; #define PG8_WAIT_V(n) asm volatile("s_waitcnt vmcnt(" #n ")" ::: "memory")
; #define PG8_WAIT_L(n) asm volatile("s_waitcnt lgkmcnt(" #n ")" ::: "memory")
; #define PG8_BAR __builtin_amdgcn_s_barrier()
; #define PG8_SCHED __builtin_amdgcn_sched_barrier(0)
; template <class Epi, bool ALIGN_EPI>
; __device__ __forceinline__ void gemm_phase(LAS unsigned char* lds, const Gemm g, const StaticOrder& S, const Epi& E) {
;     ...
;             PG8_LDA(At, 1, 1); PG8_STAGE(PG8_SB(1, 0), b3, voffB); PG8_STAGE(PG8_SB(1, 1), b3 + hstepB, voffB); PG8_STAGE(PG8_SA(1, 0), a3, voffA);
;             PG8_WAIT_V(8); PG8_WAIT_L(0); PG8_BAR; PG8_MMA(1, 0, At, B0); PG8_MMA(1, 1, At, B1); PG8_BAR; PG8_SCHED;
;         }
	s_add_i32 s30, s66, s42
	v_lshl_add_u64 v[164:165], v[164:165], 0, s[20:21]
	s_mov_b32 m0, s30
	ds_read_b128 v[184:187], v173 offset:49152
	ds_read_b128 v[188:191], v173 offset:50176
	ds_read_b128 v[192:195], v173 offset:51200
	ds_read_b128 v[196:199], v173 offset:52224
	ds_read_b128 v[200:203], v173 offset:53248
	ds_read_b128 v[204:207], v173 offset:54272
	ds_read_b128 v[208:211], v173 offset:55296
	ds_read_b128 v[212:215], v173 offset:56320
	global_load_lds_dwordx4 v[164:165], off
	s_add_i32 m0, s30, 0x2000
	s_add_u32 s30, s34, 0x160080
	v_lshl_add_u64 v[164:165], v[216:217], 0, s[20:21]
	s_addc_u32 s31, s35, 0
	s_add_i32 s34, s67, s42
	global_load_lds_dwordx4 v[164:165], off
	v_lshl_add_u64 v[164:165], s[30:31], 0, v[144:145]
	s_mov_b32 m0, s34
	s_nop 0
	global_load_lds_dwordx4 v[164:165], off
	v_lshl_add_u64 v[164:165], s[30:31], 0, v[146:147]
	s_add_i32 m0, s34, 0x2000
	s_nop 0
	global_load_lds_dwordx4 v[164:165], off
	v_lshl_add_u64 v[164:165], v[218:219], 0, s[20:21]
	s_mov_b32 m0, s48
	s_nop 0
	global_load_lds_dwordx4 v[164:165], off
	v_lshl_add_u64 v[164:165], v[220:221], 0, s[20:21]
	s_mov_b32 m0, s49
	s_nop 0
	global_load_lds_dwordx4 v[164:165], off
	s_waitcnt vmcnt(8)
	s_waitcnt lgkmcnt(0)
	s_barrier
	v_mfma_f32_16x16x32_bf16 v[60:63], v[64:67], v[184:187], v[60:63]
	v_mfma_f32_16x16x32_bf16 v[56:59], v[80:83], v[184:187], v[56:59]
	v_mfma_f32_16x16x32_bf16 v[44:47], v[64:67], v[192:195], v[44:47]
	v_mfma_f32_16x16x32_bf16 v[40:43], v[80:83], v[192:195], v[40:43]
	v_mfma_f32_16x16x32_bf16 v[28:31], v[64:67], v[200:203], v[28:31]
	v_mfma_f32_16x16x32_bf16 v[24:27], v[80:83], v[200:203], v[24:27]
	v_mfma_f32_16x16x32_bf16 v[12:15], v[64:67], v[208:211], v[12:15]
	v_mfma_f32_16x16x32_bf16 v[8:11], v[80:83], v[208:211], v[8:11]
	v_mfma_f32_16x16x32_bf16 v[60:63], v[72:75], v[188:191], v[60:63]
	v_mfma_f32_16x16x32_bf16 v[56:59], v[84:87], v[188:191], v[56:59]
	v_mfma_f32_16x16x32_bf16 v[44:47], v[72:75], v[196:199], v[44:47]
	v_mfma_f32_16x16x32_bf16 v[40:43], v[84:87], v[196:199], v[40:43]
	v_mfma_f32_16x16x32_bf16 v[28:31], v[72:75], v[204:207], v[28:31]
	v_mfma_f32_16x16x32_bf16 v[24:27], v[84:87], v[204:207], v[24:27]
	v_mfma_f32_16x16x32_bf16 v[12:15], v[72:75], v[212:215], v[12:15]
	v_mfma_f32_16x16x32_bf16 v[8:11], v[84:87], v[212:215], v[8:11]
	v_mfma_f32_16x16x32_bf16 v[52:55], v[156:159], v[184:187], v[52:55]
	v_mfma_f32_16x16x32_bf16 v[48:51], v[176:179], v[184:187], v[48:51]
	v_mfma_f32_16x16x32_bf16 v[36:39], v[156:159], v[192:195], v[36:39]
	v_mfma_f32_16x16x32_bf16 v[32:35], v[176:179], v[192:195], v[32:35]
	v_mfma_f32_16x16x32_bf16 v[20:23], v[156:159], v[200:203], v[20:23]
	v_mfma_f32_16x16x32_bf16 v[16:19], v[176:179], v[200:203], v[16:19]
	v_mfma_f32_16x16x32_bf16 v[4:7], v[156:159], v[208:211], v[4:7]
	v_mfma_f32_16x16x32_bf16 v[0:3], v[176:179], v[208:211], v[0:3]
	v_mfma_f32_16x16x32_bf16 v[52:55], v[160:163], v[188:191], v[52:55]
	v_mfma_f32_16x16x32_bf16 v[48:51], v[180:183], v[188:191], v[48:51]
	v_mfma_f32_16x16x32_bf16 v[36:39], v[160:163], v[196:199], v[36:39]
	v_mfma_f32_16x16x32_bf16 v[32:35], v[180:183], v[196:199], v[32:35]
	v_mfma_f32_16x16x32_bf16 v[20:23], v[160:163], v[204:207], v[20:23]
	v_mfma_f32_16x16x32_bf16 v[16:19], v[180:183], v[204:207], v[16:19]
	v_mfma_f32_16x16x32_bf16 v[4:7], v[160:163], v[212:215], v[4:7]
	v_mfma_f32_16x16x32_bf16 v[0:3], v[180:183], v[212:215], v[0:3]
	s_barrier
	s_add_i32 s65, s65, 2
	s_add_u32 s63, s63, 0x100
	s_addc_u32 s64, s64, 0
	s_cmpk_gt_u32 s65, 0x55
	s_mov_b64 s[30:31], s[4:5]
	s_cbranch_scc0 .LBB0_309
	s_and_b64 vcc, exec, s[22:23]
	s_cbranch_vccz .LBB0_312
	s_barrier

; #define WSP(off) (PTR(29) + (off))
;     __device__ bool next(int i, Unit& u) const {
;         const long L = (long)i * G + c; if (L >= nwg) return false;
;         int wgid = (int)L; { const int q = nwg / NXCD, r = nwg % NXCD, xcd = wgid % NXCD, off = wgid / NXCD; wgid = (xcd < r ? xcd * (q + 1) : r * (q + 1) + (xcd - r) * q) + off; }
;         const int nig = WGM * nN, gid = wgid / nig, fm = gid * WGM, gsz = (nM - fm) < WGM ? (nM - fm) : WGM;
;         u.pm = fm + ((wgid % nig) % gsz); u.pn = (wgid % nig) / gsz; return true;
; template <int K>
; __device__ __forceinline__ void run_phase(LAS unsigned char* lds, volatile LAS unsigned* ptab) {
;     ...
;         pg8::Gemm g{(const bf16_t*)WSP(WS_XN), (const bf16_t*)WSP(WS_WIN), MROWS, NZ, DM, DM}; pg8::StaticOrder S; S.init(MROWS, NZ, G, bx);
;         pg8::EpiZ E{(bf16_t*)WSP(WS_BIG), LDZ, (float*)WSP(WS_GATES), 20, (const float*)WSP(WS_SS1), (bf16_t*)WSP(WS_UG)};
;         pg8::gemm_phase<pg8::EpiZ, true>(lds, g, S, E);
.Lprio_skip_2:
	s_add_i32 s0, 0, 0x230ec
	s_waitcnt lgkmcnt(0)
	v_mov_b32_e32 v0, s0
	s_add_i32 s0, 0, 0x230e8
	v_mov_b32_e32 v139, v166
	v_mov_b32_e32 v2, s0
	s_barrier
	ds_read_b32 v1, v0
	ds_read_b32 v3, v2
	v_mov_b32_e32 v8, v166
	s_cmpk_lt_i32 s3, 0x7e0
	v_readfirstlane_b32 s2, v139
	s_waitcnt lgkmcnt(1)
	v_readfirstlane_b32 s5, v1
	s_waitcnt lgkmcnt(0)
	v_readfirstlane_b32 s7, v3
	ds_read_b32 v1, v0
	ds_read_b32 v3, v2
	ds_read_b32 v4, v0
	ds_read_b32 v5, v2
	ds_read_b32 v6, v0
	s_waitcnt lgkmcnt(4)
	v_readfirstlane_b32 s11, v1
	s_waitcnt lgkmcnt(3)
	v_readfirstlane_b32 s12, v3
	s_waitcnt lgkmcnt(2)
	v_readfirstlane_b32 s15, v4
	ds_read_b32 v1, v2
	ds_read_b32 v3, v0
	ds_read_b32 v4, v2
	ds_read_b32 v0, v0
	ds_read_b32 v2, v2
	s_waitcnt lgkmcnt(6)
	v_readfirstlane_b32 s14, v5
	s_waitcnt lgkmcnt(5)
	v_readfirstlane_b32 s1, v6
	s_waitcnt lgkmcnt(4)
	v_readfirstlane_b32 s0, v1
	s_waitcnt lgkmcnt(3)
	v_readfirstlane_b32 s19, v3
	s_waitcnt lgkmcnt(2)
	v_readfirstlane_b32 s18, v4
	s_waitcnt lgkmcnt(1)
	v_readfirstlane_b32 s21, v0
	s_waitcnt lgkmcnt(0)
	v_readfirstlane_b32 s20, v2
	s_cselect_b64 s[8:9], -1, 0
	s_cmpk_gt_i32 s3, 0x7df
	v_readfirstlane_b32 s10, v8
	s_cbranch_scc1 .LBB0_450
	s_ashr_i32 s4, s3, 31
	s_lshr_b32 s4, s4, 29
	s_add_i32 s4, s3, s4
	s_ashr_i32 s6, s4, 3
	s_and_b32 s4, s4, -8
	s_sub_i32 s4, s3, s4
	s_cmp_lt_i32 s4, 0
	s_movk_i32 s13, 0xfd
	s_cselect_b32 s13, s13, 0xfc
	s_mul_i32 s4, s13, s4
	s_add_i32 s4, s4, s6
	s_mul_hi_i32 s6, s4, 0x30c30c31
	s_lshr_b32 s13, s6, 31
	s_ashr_i32 s6, s6, 5
	s_add_i32 s6, s6, s13
	s_lshl_b32 s13, s6, 3
	s_mulk_i32 s6, 0xa8
	s_sub_i32 s4, s4, s6
	s_sext_i32_i16 s6, s4
	s_bfe_u32 s6, s6, 0x3001c
	s_add_i32 s6, s4, s6
	s_sext_i32_i16 s22, s6
	s_and_b32 s6, s6, 0xfff8
	s_sub_i32 s4, s4, s6
	s_sext_i32_i16 s4, s4
	s_add_i32 s6, s13, s4
	s_ashr_i32 s4, s22, 3

; #define PG8_STAGE(bufoff, gbase, voff) do { _Pragma("unroll") for (int _i = 0; _i < 2; ++_i) \
;         __builtin_amdgcn_global_load_lds((const unsigned*)((const char*)(gbase) + (voff)[_i]), (LAS unsigned*)(lds + (bufoff) + ldsw + _i * 8192), 16, 0, 0); } while (0)
; #define PG8_LDA(dst, b, h) do { _Pragma("unroll") for (int m = 0; m < 4; ++m) _Pragma("unroll") for (int k = 0; k < 2; ++k) dst[m][k] = *(const LAS bf16x8*)(lds + PG8_SA(b, h) + aoff + m * 2048 + k * 1024); } while (0)
; #define PG8_LDB(dst, b, h) do { _Pragma("unroll") for (int n = 0; n < 2; ++n) _Pragma("unroll") for (int k = 0; k < 2; ++k) dst[n][k] = *(const LAS bf16x8*)(lds + PG8_SB(b, h) + boff + n * 2048 + k * 1024); } while (0)
; #define PG8_MMA(ai, bj, At, Bt) do { __builtin_amdgcn_s_setprio(1); _Pragma("unroll") for (int m = 0; m < 4; ++m) _Pragma("unroll") for (int n = 0; n < 2; ++n) _Pragma("unroll") for (int k = 0; k < 2; ++k) \
;         acc[ai][bj][m][n] = __builtin_amdgcn_mfma_f32_16x16x32_bf16(Bt[n][k], At[m][k], acc[ai][bj][m][n], 0, 0, 0); __builtin_amdgcn_s_setprio(0); } while (0)
; #define PG8_WAIT_V(n) asm volatile("s_waitcnt vmcnt(" #n ")" ::: "memory")
; #define PG8_WAIT_L(n) asm volatile("s_waitcnt lgkmcnt(" #n ")" ::: "memory")
; #define PG8_BAR __builtin_amdgcn_s_barrier()
; #define PG8_SCHED __builtin_amdgcn_sched_barrier(0)
; template <class Epi, bool ALIGN_EPI>
; __device__ __forceinline__ void gemm_phase(LAS unsigned char* lds, const Gemm g, const StaticOrder& S, const Epi& E) {
;     ...
;             PG8_LDB(B0, 0, 0); PG8_LDB(B1, 0, 1); PG8_SCHED; PG8_LDA(At, 0, 0); PG8_STAGE(PG8_SA(1, 1), a1 + hstepA, voffA);
;             PG8_WAIT_V(8); PG8_WAIT_L(0); PG8_BAR; PG8_MMA(0, 0, At, B0); PG8_MMA(0, 1, At, B1); PG8_BAR; PG8_SCHED;
;             PG8_LDA(At, 0, 1); PG8_STAGE(PG8_SB(0, 0), b2, voffB); PG8_STAGE(PG8_SB(0, 1), b2 + hstepB, voffB); PG8_STAGE(PG8_SA(0, 0), a2, voffA);
;             PG8_WAIT_V(8); PG8_WAIT_L(0); PG8_BAR; PG8_MMA(1, 0, At, B0); PG8_MMA(1, 1, At, B1); PG8_BAR; PG8_SCHED;
.LBB0_459:
	ds_read_b128 v[152:155], v165
	ds_read_b128 v[156:159], v165 offset:1024
	ds_read_b128 v[172:175], v165 offset:2048
	ds_read_b128 v[176:179], v165 offset:3072
	ds_read_b128 v[180:183], v168
	ds_read_b128 v[184:187], v168 offset:1024
	ds_read_b128 v[188:191], v168 offset:2048
	ds_read_b128 v[192:195], v168 offset:3072
	s_add_u32 s40, s8, 0xfff80080
	s_addc_u32 s41, s9, -1
	s_cmp_eq_u32 s45, 28
	s_cselect_b32 s43, s5, s41
	s_cselect_b32 s42, s7, s40
	s_cselect_b32 s41, s10, s44
	s_cselect_b32 s40, s31, s35
	v_lshl_add_u64 v[160:161], s[8:9], 0, v[146:147]
	s_add_i32 m0, s50, 0xc000
	ds_read_b128 v[196:199], v169
	ds_read_b128 v[200:203], v169 offset:1024
	ds_read_b128 v[204:207], v169 offset:2048
	ds_read_b128 v[208:211], v169 offset:3072
	ds_read_b128 v[212:215], v169 offset:4096
	ds_read_b128 v[216:219], v169 offset:5120
	ds_read_b128 v[220:223], v169 offset:6144
	ds_read_b128 v[224:227], v169 offset:7168
	global_load_lds_dwordx4 v[160:161], off
	v_lshl_add_u64 v[160:161], s[8:9], 0, v[144:145]
	s_add_i32 m0, s50, 0xe000
	s_nop 0
	global_load_lds_dwordx4 v[160:161], off
	s_waitcnt vmcnt(8)
	s_waitcnt lgkmcnt(0)
	s_barrier
	v_mfma_f32_16x16x32_bf16 v[120:123], v[152:155], v[196:199], v[120:123]
	v_mfma_f32_16x16x32_bf16 v[112:115], v[172:175], v[196:199], v[112:115]
	v_mfma_f32_16x16x32_bf16 v[104:107], v[152:155], v[204:207], v[104:107]
	v_mfma_f32_16x16x32_bf16 v[96:99], v[172:175], v[204:207], v[96:99]
	v_mfma_f32_16x16x32_bf16 v[88:91], v[152:155], v[212:215], v[88:91]
	v_mfma_f32_16x16x32_bf16 v[80:83], v[172:175], v[212:215], v[80:83]
	v_mfma_f32_16x16x32_bf16 v[72:75], v[152:155], v[220:223], v[72:75]
	v_mfma_f32_16x16x32_bf16 v[64:67], v[172:175], v[220:223], v[64:67]
	v_mfma_f32_16x16x32_bf16 v[120:123], v[156:159], v[200:203], v[120:123]
	v_mfma_f32_16x16x32_bf16 v[112:115], v[176:179], v[200:203], v[112:115]
	v_mfma_f32_16x16x32_bf16 v[104:107], v[156:159], v[208:211], v[104:107]
	v_mfma_f32_16x16x32_bf16 v[96:99], v[176:179], v[208:211], v[96:99]
	v_mfma_f32_16x16x32_bf16 v[88:91], v[156:159], v[216:219], v[88:91]
	v_mfma_f32_16x16x32_bf16 v[80:83], v[176:179], v[216:219], v[80:83]
	v_mfma_f32_16x16x32_bf16 v[72:75], v[156:159], v[224:227], v[72:75]
	v_mfma_f32_16x16x32_bf16 v[64:67], v[176:179], v[224:227], v[64:67]
	v_mfma_f32_16x16x32_bf16 v[124:127], v[180:183], v[196:199], v[124:127]
	v_mfma_f32_16x16x32_bf16 v[116:119], v[188:191], v[196:199], v[116:119]
	v_mfma_f32_16x16x32_bf16 v[108:111], v[180:183], v[204:207], v[108:111]
	v_mfma_f32_16x16x32_bf16 v[100:103], v[188:191], v[204:207], v[100:103]
	v_mfma_f32_16x16x32_bf16 v[92:95], v[180:183], v[212:215], v[92:95]
	v_mfma_f32_16x16x32_bf16 v[84:87], v[188:191], v[212:215], v[84:87]
	v_mfma_f32_16x16x32_bf16 v[76:79], v[180:183], v[220:223], v[76:79]
	v_mfma_f32_16x16x32_bf16 v[68:71], v[188:191], v[220:223], v[68:71]
	v_mfma_f32_16x16x32_bf16 v[124:127], v[184:187], v[200:203], v[124:127]
	v_mfma_f32_16x16x32_bf16 v[116:119], v[192:195], v[200:203], v[116:119]
	v_mfma_f32_16x16x32_bf16 v[108:111], v[184:187], v[208:211], v[108:111]
	v_mfma_f32_16x16x32_bf16 v[100:103], v[192:195], v[208:211], v[100:103]
	v_mfma_f32_16x16x32_bf16 v[92:95], v[184:187], v[216:219], v[92:95]
	v_mfma_f32_16x16x32_bf16 v[84:87], v[192:195], v[216:219], v[84:87]
	v_mfma_f32_16x16x32_bf16 v[76:79], v[184:187], v[224:227], v[76:79]
	v_mfma_f32_16x16x32_bf16 v[68:71], v[192:195], v[224:227], v[68:71]
	s_barrier
	s_add_i32 s71, s62, s49
	v_lshl_add_u64 v[160:161], s[40:41], 0, v[130:131]
	s_mov_b32 m0, s71
	ds_read_b128 v[196:199], v169 offset:16384
	ds_read_b128 v[200:203], v169 offset:17408
	ds_read_b128 v[204:207], v169 offset:18432
	ds_read_b128 v[208:211], v169 offset:19456
	ds_read_b128 v[212:215], v169 offset:20480
	ds_read_b128 v[216:219], v169 offset:21504
	ds_read_b128 v[220:223], v169 offset:22528
	ds_read_b128 v[224:227], v169 offset:23552
	global_load_lds_dwordx4 v[160:161], off
	s_add_i32 m0, s71, 0x2000
	s_add_u32 s78, s40, 0x80000
	v_lshl_add_u64 v[228:229], s[40:41], 0, v[134:135]
	s_addc_u32 s79, s41, 0
	s_add_i32 s71, s63, s49
	global_load_lds_dwordx4 v[228:229], off
	v_lshl_add_u64 v[230:231], s[78:79], 0, v[130:131]
	s_mov_b32 m0, s71
	v_lshl_add_u64 v[232:233], s[42:43], 0, v[132:133]
	global_load_lds_dwordx4 v[230:231], off
	v_lshl_add_u64 v[230:231], s[78:79], 0, v[134:135]
	s_add_i32 m0, s71, 0x2000
	s_nop 0
	global_load_lds_dwordx4 v[230:231], off
	v_lshl_add_u64 v[230:231], s[42:43], 0, v[128:129]
	s_mov_b32 m0, s50
	s_nop 0
	global_load_lds_dwordx4 v[230:231], off
	s_mov_b32 m0, s51
	s_nop 0
	global_load_lds_dwordx4 v[232:233], off
	s_waitcnt vmcnt(8)
	s_waitcnt lgkmcnt(0)
	s_barrier
; #define PG8_STAGE(bufoff, gbase, voff) do { _Pragma("unroll") for (int _i = 0; _i < 2; ++_i) \
;         __builtin_amdgcn_global_load_lds((const unsigned*)((const char*)(gbase) + (voff)[_i]), (LAS unsigned*)(lds + (bufoff) + ldsw + _i * 8192), 16, 0, 0); } while (0)
; #define PG8_LDA(dst, b, h) do { _Pragma("unroll") for (int m = 0; m < 4; ++m) _Pragma("unroll") for (int k = 0; k < 2; ++k) dst[m][k] = *(const LAS bf16x8*)(lds + PG8_SA(b, h) + aoff + m * 2048 + k * 1024); } while (0)
; #define PG8_LDB(dst, b, h) do { _Pragma("unroll") for (int n = 0; n < 2; ++n) _Pragma("unroll") for (int k = 0; k < 2; ++k) dst[n][k] = *(const LAS bf16x8*)(lds + PG8_SB(b, h) + boff + n * 2048 + k * 1024); } while (0)
; #define PG8_MMA(ai, bj, At, Bt) do { __builtin_amdgcn_s_setprio(1); _Pragma("unroll") for (int m = 0; m < 4; ++m) _Pragma("unroll") for (int n = 0; n < 2; ++n) _Pragma("unroll") for (int k = 0; k < 2; ++k) \
;         acc[ai][bj][m][n] = __builtin_amdgcn_mfma_f32_16x16x32_bf16(Bt[n][k], At[m][k], acc[ai][bj][m][n], 0, 0, 0); __builtin_amdgcn_s_setprio(0); } while (0)
; #define PG8_WAIT_V(n) asm volatile("s_waitcnt vmcnt(" #n ")" ::: "memory")
; #define PG8_WAIT_L(n) asm volatile("s_waitcnt lgkmcnt(" #n ")" ::: "memory")
; #define PG8_BAR __builtin_amdgcn_s_barrier()
; #define PG8_SCHED __builtin_amdgcn_sched_barrier(0)
; template <class Epi, bool ALIGN_EPI>
; __device__ __forceinline__ void gemm_phase(LAS unsigned char* lds, const Gemm g, const StaticOrder& S, const Epi& E) {
;     ...
;             PG8_WAIT_V(8); PG8_WAIT_L(0); PG8_BAR; PG8_MMA(1, 0, At, B0); PG8_MMA(1, 1, At, B1); PG8_BAR; PG8_SCHED;
;             PG8_LDB(B0, 1, 0); PG8_LDB(B1, 1, 1); PG8_SCHED; PG8_LDA(At, 1, 0); PG8_STAGE(PG8_SA(0, 1), a2 + hstepA, voffA);
;             PG8_WAIT_V(8); PG8_WAIT_L(0); PG8_BAR; PG8_MMA(0, 0, At, B0); PG8_MMA(0, 1, At, B1); PG8_BAR; PG8_SCHED;
;             PG8_LDA(At, 1, 1); PG8_STAGE(PG8_SB(1, 0), b3, voffB); PG8_STAGE(PG8_SB(1, 1), b3 + hstepB, voffB); PG8_STAGE(PG8_SA(1, 0), a3, voffA);
	v_mfma_f32_16x16x32_bf16 v[56:59], v[152:155], v[196:199], v[56:59]
	v_mfma_f32_16x16x32_bf16 v[48:51], v[172:175], v[196:199], v[48:51]
	v_mfma_f32_16x16x32_bf16 v[40:43], v[152:155], v[204:207], v[40:43]
	v_mfma_f32_16x16x32_bf16 v[32:35], v[172:175], v[204:207], v[32:35]
	v_mfma_f32_16x16x32_bf16 v[24:27], v[152:155], v[212:215], v[24:27]
	v_mfma_f32_16x16x32_bf16 v[16:19], v[172:175], v[212:215], v[16:19]
	v_mfma_f32_16x16x32_bf16 v[8:11], v[152:155], v[220:223], v[8:11]
	v_mfma_f32_16x16x32_bf16 v[0:3], v[172:175], v[220:223], v[0:3]
	v_mfma_f32_16x16x32_bf16 v[56:59], v[156:159], v[200:203], v[56:59]
	v_mfma_f32_16x16x32_bf16 v[48:51], v[176:179], v[200:203], v[48:51]
	v_mfma_f32_16x16x32_bf16 v[40:43], v[156:159], v[208:211], v[40:43]
	v_mfma_f32_16x16x32_bf16 v[32:35], v[176:179], v[208:211], v[32:35]
	v_mfma_f32_16x16x32_bf16 v[24:27], v[156:159], v[216:219], v[24:27]
	v_mfma_f32_16x16x32_bf16 v[16:19], v[176:179], v[216:219], v[16:19]
	v_mfma_f32_16x16x32_bf16 v[8:11], v[156:159], v[224:227], v[8:11]
	v_mfma_f32_16x16x32_bf16 v[0:3], v[176:179], v[224:227], v[0:3]
	v_mfma_f32_16x16x32_bf16 v[60:63], v[180:183], v[196:199], v[60:63]
	v_mfma_f32_16x16x32_bf16 v[52:55], v[188:191], v[196:199], v[52:55]
	v_mfma_f32_16x16x32_bf16 v[44:47], v[180:183], v[204:207], v[44:47]
	v_mfma_f32_16x16x32_bf16 v[36:39], v[188:191], v[204:207], v[36:39]
	v_mfma_f32_16x16x32_bf16 v[28:31], v[180:183], v[212:215], v[28:31]
	v_mfma_f32_16x16x32_bf16 v[20:23], v[188:191], v[212:215], v[20:23]
	v_mfma_f32_16x16x32_bf16 v[12:15], v[180:183], v[220:223], v[12:15]
	v_mfma_f32_16x16x32_bf16 v[4:7], v[188:191], v[220:223], v[4:7]
	v_mfma_f32_16x16x32_bf16 v[60:63], v[184:187], v[200:203], v[60:63]
	v_mfma_f32_16x16x32_bf16 v[52:55], v[192:195], v[200:203], v[52:55]
	v_mfma_f32_16x16x32_bf16 v[44:47], v[184:187], v[208:211], v[44:47]
	v_mfma_f32_16x16x32_bf16 v[36:39], v[192:195], v[208:211], v[36:39]
	v_mfma_f32_16x16x32_bf16 v[28:31], v[184:187], v[216:219], v[28:31]
	v_mfma_f32_16x16x32_bf16 v[20:23], v[192:195], v[216:219], v[20:23]
	v_mfma_f32_16x16x32_bf16 v[12:15], v[184:187], v[224:227], v[12:15]
	v_mfma_f32_16x16x32_bf16 v[4:7], v[192:195], v[224:227], v[4:7]
	s_barrier
	s_add_i32 s71, 0, 0x18000
	v_add_u32_e32 v136, s71, v162
	s_add_i32 s73, 0, 0x1c000
	ds_read_b128 v[152:155], v136
	ds_read_b128 v[156:159], v136 offset:1024
	ds_read_b128 v[172:175], v136 offset:2048
	ds_read_b128 v[176:179], v136 offset:3072
	v_add_u32_e32 v136, s73, v162
	ds_read_b128 v[180:183], v136
	ds_read_b128 v[184:187], v136 offset:1024
	ds_read_b128 v[188:191], v136 offset:2048
	ds_read_b128 v[192:195], v136 offset:3072
	s_add_u32 s42, s42, 0x80000
	s_addc_u32 s43, s43, 0
	s_mov_b32 m0, s52
	v_lshl_add_u64 v[234:235], s[42:43], 0, v[128:129]
	ds_read_b128 v[196:199], v169 offset:32768
	ds_read_b128 v[200:203], v169 offset:33792
	ds_read_b128 v[204:207], v169 offset:34816
	ds_read_b128 v[208:211], v169 offset:35840
	ds_read_b128 v[212:215], v169 offset:36864
	ds_read_b128 v[216:219], v169 offset:37888
	ds_read_b128 v[220:223], v169 offset:38912
	ds_read_b128 v[224:227], v169 offset:39936
	global_load_lds_dwordx4 v[234:235], off
	v_lshl_add_u64 v[234:235], s[42:43], 0, v[132:133]
	s_mov_b32 m0, s53
	s_nop 0
	global_load_lds_dwordx4 v[234:235], off
	s_waitcnt vmcnt(8)
	s_waitcnt lgkmcnt(0)
	s_barrier
	v_mfma_f32_16x16x32_bf16 v[120:123], v[152:155], v[196:199], v[120:123]
	v_mfma_f32_16x16x32_bf16 v[112:115], v[172:175], v[196:199], v[112:115]
	v_mfma_f32_16x16x32_bf16 v[104:107], v[152:155], v[204:207], v[104:107]
	v_mfma_f32_16x16x32_bf16 v[96:99], v[172:175], v[204:207], v[96:99]
	v_mfma_f32_16x16x32_bf16 v[88:91], v[152:155], v[212:215], v[88:91]
	v_mfma_f32_16x16x32_bf16 v[80:83], v[172:175], v[212:215], v[80:83]
	v_mfma_f32_16x16x32_bf16 v[72:75], v[152:155], v[220:223], v[72:75]
	v_mfma_f32_16x16x32_bf16 v[64:67], v[172:175], v[220:223], v[64:67]
	v_mfma_f32_16x16x32_bf16 v[120:123], v[156:159], v[200:203], v[120:123]
	v_mfma_f32_16x16x32_bf16 v[112:115], v[176:179], v[200:203], v[112:115]
	v_mfma_f32_16x16x32_bf16 v[104:107], v[156:159], v[208:211], v[104:107]
	v_mfma_f32_16x16x32_bf16 v[96:99], v[176:179], v[208:211], v[96:99]
	v_mfma_f32_16x16x32_bf16 v[88:91], v[156:159], v[216:219], v[88:91]
	v_mfma_f32_16x16x32_bf16 v[80:83], v[176:179], v[216:219], v[80:83]
	v_mfma_f32_16x16x32_bf16 v[72:75], v[156:159], v[224:227], v[72:75]
	v_mfma_f32_16x16x32_bf16 v[64:67], v[176:179], v[224:227], v[64:67]
	v_mfma_f32_16x16x32_bf16 v[124:127], v[180:183], v[196:199], v[124:127]
	v_mfma_f32_16x16x32_bf16 v[116:119], v[188:191], v[196:199], v[116:119]
	v_mfma_f32_16x16x32_bf16 v[108:111], v[180:183], v[204:207], v[108:111]
	v_mfma_f32_16x16x32_bf16 v[100:103], v[188:191], v[204:207], v[100:103]
	v_mfma_f32_16x16x32_bf16 v[92:95], v[180:183], v[212:215], v[92:95]
	v_mfma_f32_16x16x32_bf16 v[84:87], v[188:191], v[212:215], v[84:87]
	v_mfma_f32_16x16x32_bf16 v[76:79], v[180:183], v[220:223], v[76:79]
	v_mfma_f32_16x16x32_bf16 v[68:71], v[188:191], v[220:223], v[68:71]
	v_mfma_f32_16x16x32_bf16 v[124:127], v[184:187], v[200:203], v[124:127]
	v_mfma_f32_16x16x32_bf16 v[116:119], v[192:195], v[200:203], v[116:119]
	v_mfma_f32_16x16x32_bf16 v[108:111], v[184:187], v[208:211], v[108:111]
	v_mfma_f32_16x16x32_bf16 v[100:103], v[192:195], v[208:211], v[100:103]
	v_mfma_f32_16x16x32_bf16 v[92:95], v[184:187], v[216:219], v[92:95]
	v_mfma_f32_16x16x32_bf16 v[84:87], v[192:195], v[216:219], v[84:87]
	v_mfma_f32_16x16x32_bf16 v[76:79], v[184:187], v[224:227], v[76:79]
	v_mfma_f32_16x16x32_bf16 v[68:71], v[192:195], v[224:227], v[68:71]
	s_barrier
; #define PG8_STAGE(bufoff, gbase, voff) do { _Pragma("unroll") for (int _i = 0; _i < 2; ++_i) \
;         __builtin_amdgcn_global_load_lds((const unsigned*)((const char*)(gbase) + (voff)[_i]), (LAS unsigned*)(lds + (bufoff) + ldsw + _i * 8192), 16, 0, 0); } while (0)
; #define PG8_LDA(dst, b, h) do { _Pragma("unroll") for (int m = 0; m < 4; ++m) _Pragma("unroll") for (int k = 0; k < 2; ++k) dst[m][k] = *(const LAS bf16x8*)(lds + PG8_SA(b, h) + aoff + m * 2048 + k * 1024); } while (0)
; #define PG8_MMA(ai, bj, At, Bt) do { __builtin_amdgcn_s_setprio(1); _Pragma("unroll") for (int m = 0; m < 4; ++m) _Pragma("unroll") for (int n = 0; n < 2; ++n) _Pragma("unroll") for (int k = 0; k < 2; ++k) \
;         acc[ai][bj][m][n] = __builtin_amdgcn_mfma_f32_16x16x32_bf16(Bt[n][k], At[m][k], acc[ai][bj][m][n], 0, 0, 0); __builtin_amdgcn_s_setprio(0); } while (0)
; #define PG8_WAIT_V(n) asm volatile("s_waitcnt vmcnt(" #n ")" ::: "memory")
; #define PG8_WAIT_L(n) asm volatile("s_waitcnt lgkmcnt(" #n ")" ::: "memory")
; #define PG8_BAR __builtin_amdgcn_s_barrier()
; #define PG8_SCHED __builtin_amdgcn_sched_barrier(0)
; template <class Epi, bool ALIGN_EPI>
; __device__ __forceinline__ void gemm_phase(LAS unsigned char* lds, const Gemm g, const StaticOrder& S, const Epi& E) {
;     ...
;             PG8_LDA(At, 1, 1); PG8_STAGE(PG8_SB(1, 0), b3, voffB); PG8_STAGE(PG8_SB(1, 1), b3 + hstepB, voffB); PG8_STAGE(PG8_SA(1, 0), a3, voffA);
;             PG8_WAIT_V(8); PG8_WAIT_L(0); PG8_BAR; PG8_MMA(1, 0, At, B0); PG8_MMA(1, 1, At, B1); PG8_BAR; PG8_SCHED;
;         }
	s_add_i32 s42, s71, s49
	v_lshl_add_u64 v[160:161], v[160:161], 0, s[22:23]
	s_mov_b32 m0, s42
	ds_read_b128 v[196:199], v169 offset:49152
	ds_read_b128 v[200:203], v169 offset:50176
	ds_read_b128 v[204:207], v169 offset:51200
	ds_read_b128 v[208:211], v169 offset:52224
	ds_read_b128 v[212:215], v169 offset:53248
	ds_read_b128 v[216:219], v169 offset:54272
	ds_read_b128 v[220:223], v169 offset:55296
	ds_read_b128 v[224:227], v169 offset:56320
	global_load_lds_dwordx4 v[160:161], off
	s_add_i32 m0, s42, 0x2000
	s_add_u32 s40, s40, 0x80080
	v_lshl_add_u64 v[160:161], v[228:229], 0, s[22:23]
	s_addc_u32 s41, s41, 0
	s_add_i32 s42, s73, s49
	global_load_lds_dwordx4 v[160:161], off
	v_lshl_add_u64 v[160:161], s[40:41], 0, v[130:131]
	s_mov_b32 m0, s42
	s_nop 0
	global_load_lds_dwordx4 v[160:161], off
	v_lshl_add_u64 v[160:161], s[40:41], 0, v[134:135]
	s_add_i32 m0, s42, 0x2000
	s_nop 0
	global_load_lds_dwordx4 v[160:161], off
	v_lshl_add_u64 v[160:161], v[230:231], 0, s[22:23]
	s_mov_b32 m0, s56
	s_nop 0
	global_load_lds_dwordx4 v[160:161], off
	v_lshl_add_u64 v[160:161], v[232:233], 0, s[22:23]
	s_mov_b32 m0, s57
	s_nop 0
	global_load_lds_dwordx4 v[160:161], off
	s_waitcnt vmcnt(8)
	s_waitcnt lgkmcnt(0)
	s_barrier
	v_mfma_f32_16x16x32_bf16 v[56:59], v[152:155], v[196:199], v[56:59]
	v_mfma_f32_16x16x32_bf16 v[48:51], v[172:175], v[196:199], v[48:51]
	v_mfma_f32_16x16x32_bf16 v[40:43], v[152:155], v[204:207], v[40:43]
	v_mfma_f32_16x16x32_bf16 v[32:35], v[172:175], v[204:207], v[32:35]
	v_mfma_f32_16x16x32_bf16 v[24:27], v[152:155], v[212:215], v[24:27]
	v_mfma_f32_16x16x32_bf16 v[16:19], v[172:175], v[212:215], v[16:19]
	v_mfma_f32_16x16x32_bf16 v[8:11], v[152:155], v[220:223], v[8:11]
	v_mfma_f32_16x16x32_bf16 v[0:3], v[172:175], v[220:223], v[0:3]
	v_mfma_f32_16x16x32_bf16 v[56:59], v[156:159], v[200:203], v[56:59]
	v_mfma_f32_16x16x32_bf16 v[48:51], v[176:179], v[200:203], v[48:51]
	v_mfma_f32_16x16x32_bf16 v[40:43], v[156:159], v[208:211], v[40:43]
	v_mfma_f32_16x16x32_bf16 v[32:35], v[176:179], v[208:211], v[32:35]
	v_mfma_f32_16x16x32_bf16 v[24:27], v[156:159], v[216:219], v[24:27]
	v_mfma_f32_16x16x32_bf16 v[16:19], v[176:179], v[216:219], v[16:19]
	v_mfma_f32_16x16x32_bf16 v[8:11], v[156:159], v[224:227], v[8:11]
	v_mfma_f32_16x16x32_bf16 v[0:3], v[176:179], v[224:227], v[0:3]
	v_mfma_f32_16x16x32_bf16 v[60:63], v[180:183], v[196:199], v[60:63]
	v_mfma_f32_16x16x32_bf16 v[52:55], v[188:191], v[196:199], v[52:55]
	v_mfma_f32_16x16x32_bf16 v[44:47], v[180:183], v[204:207], v[44:47]
	v_mfma_f32_16x16x32_bf16 v[36:39], v[188:191], v[204:207], v[36:39]
	v_mfma_f32_16x16x32_bf16 v[28:31], v[180:183], v[212:215], v[28:31]
	v_mfma_f32_16x16x32_bf16 v[20:23], v[188:191], v[212:215], v[20:23]
	v_mfma_f32_16x16x32_bf16 v[12:15], v[180:183], v[220:223], v[12:15]
	v_mfma_f32_16x16x32_bf16 v[4:7], v[188:191], v[220:223], v[4:7]
	v_mfma_f32_16x16x32_bf16 v[60:63], v[184:187], v[200:203], v[60:63]
	v_mfma_f32_16x16x32_bf16 v[52:55], v[192:195], v[200:203], v[52:55]
	v_mfma_f32_16x16x32_bf16 v[44:47], v[184:187], v[208:211], v[44:47]
	v_mfma_f32_16x16x32_bf16 v[36:39], v[192:195], v[208:211], v[36:39]
	v_mfma_f32_16x16x32_bf16 v[28:31], v[184:187], v[216:219], v[28:31]
	v_mfma_f32_16x16x32_bf16 v[20:23], v[192:195], v[216:219], v[20:23]
	v_mfma_f32_16x16x32_bf16 v[12:15], v[184:187], v[224:227], v[12:15]
	v_mfma_f32_16x16x32_bf16 v[4:7], v[192:195], v[224:227], v[4:7]
	s_barrier
	s_add_i32 s45, s45, 2
	s_add_u32 s35, s35, 0x100
	s_addc_u32 s44, s44, 0
	s_add_u32 s8, s8, 0x100
	s_addc_u32 s9, s9, 0
	s_cmp_gt_u32 s45, 29
	s_cbranch_scc0 .LBB0_459
	s_and_b64 vcc, exec, s[24:25]
	s_cbranch_vccz .LBB0_462
	s_barrier

; #define LAS __attribute__((address_space(3)))
; __device__ __forceinline__ void s5_egemm(LAS unsigned char* lds, const bf16_t* Z, const bf16_t* W1, float* E, int unit, int tid) {
;     const int nh = unit & 3, mb3 = (unit >> 2) % 3, g = unit / 12;
;     const int wid = tid >> 6, lane = tid & 63, fr = lane & 15, fq = lane >> 4;
;     const int cbase = mb3 * 256 + wid * 32;
;     f32x4 acc[2][4];
; #pragma unroll
;     for (int m = 0; m < 2; ++m)
; #pragma unroll
;         for (int n = 0; n < 4; ++n) acc[m][n] = (f32x4){0.f, 0.f, 0.f, 0.f};
;     const bf16_t* Ab = Z + ((size_t)(g * S5NCB + (cbase >> 4)) * 32 + (fq >> 1)) * 256 + fr * 16 + (fq & 1) * 8;
;     const bf16_t* Bsrc = W1 + (size_t)g * 256 * 512 + (size_t)(nh * 64 + (tid >> 3)) * 512 + (tid & 7) * 8;
;     constexpr int ROWB = 144, BUFB = 64 * ROWB;
;     LAS unsigned char* bdst = lds + (tid >> 3) * ROWB + (tid & 7) * 16;
;     const LAS unsigned char* brd = lds + fr * ROWB + fq * 16;
;     u32x4 rb[5]; bf16x8 af[5][4];
.LBB0_637:
	s_or_b64 exec, exec, s[0:1]
	s_setprio 0
	s_add_i32 s0, 0, 0x230ec
	v_mov_b32_e32 v4, v166
	s_waitcnt lgkmcnt(0)
	v_mov_b32_e32 v0, s0
	s_barrier
	ds_read_b32 v1, v0
	s_add_i32 s0, 0, 0x230e8
	v_mov_b32_e32 v2, s0
	ds_read_b32 v3, v2
	v_readlane_b32 s8, v252, 14
	s_waitcnt lgkmcnt(1)
	v_readfirstlane_b32 s1, v1
	ds_read_b32 v1, v0
	ds_read_b32 v5, v2
	ds_read_b32 v0, v0
	ds_read_b32 v2, v2
	v_readlane_b32 s9, v252, 15
	s_waitcnt lgkmcnt(4)
	v_readfirstlane_b32 s0, v3
	s_waitcnt lgkmcnt(3)
	v_readfirstlane_b32 s4, v1
	s_waitcnt lgkmcnt(2)
	v_readfirstlane_b32 s2, v5
	s_waitcnt lgkmcnt(1)
	v_readfirstlane_b32 s6, v0
	s_and_b64 vcc, exec, s[8:9]
	s_waitcnt lgkmcnt(0)
	v_readfirstlane_b32 s5, v2
	s_cbranch_vccnz .LBB0_640
	v_ashrrev_i32_e32 v0, 1, v4
	v_and_b32_e32 v8, 0xffffffe0, v0
	v_lshlrev_b32_e32 v0, 4, v4
	v_and_b32_e32 v9, 15, v4
	v_and_b32_e32 v0, 0x200, v0
	v_mov_b32_e32 v1, 0
	v_lshl_add_u64 v[2:3], s[0:1], 0, v[0:1]
	v_lshlrev_b32_e32 v0, 5, v9
	v_lshl_add_u64 v[2:3], v[2:3], 0, v[0:1]
	v_and_b32_e32 v0, 16, v4
	v_lshl_add_u64 v[2:3], v[2:3], 0, v[0:1]
	s_mov_b64 s[0:1], 0x14200000
	s_add_u32 s2, s2, 0x1b100000
	v_lshl_add_u64 v[2:3], v[2:3], 0, s[0:1]
	v_ashrrev_i32_e32 v10, 3, v4
	s_movk_i32 s0, 0x90
	s_addc_u32 s4, s4, 0
	v_bfe_u32 v5, v4, 4, 2
	v_and_b32_e32 v4, 7, v4
	v_mul_lo_u32 v6, v10, s0
	s_add_u32 s5, s5, 0x18100000
	v_lshlrev_b32_e32 v0, 3, v4
	v_lshlrev_b32_e32 v7, 4, v4
	v_lshlrev_b32_e32 v12, 4, v5
	v_add_u32_e32 v6, 0, v6
	v_mad_u32_u24 v13, v9, s0, 0
	v_lshlrev_b32_e32 v4, 2, v5
	s_addc_u32 s6, s6, 0
	s_lshl_b32 s8, s76, 6
	v_lshlrev_b32_e32 v0, 1, v0
	s_movk_i32 s9, 0x4000
	s_movk_i32 s10, 0x1000
	s_movk_i32 s11, 0x5000
	v_add_u32_e32 v11, v6, v7
	s_movk_i32 s12, 0x2000
	s_movk_i32 s13, 0x6000
	v_add_u32_e32 v12, v13, v12
	s_movk_i32 s14, 0x3000
	s_movk_i32 s15, 0x7000
	v_lshlrev_b32_e32 v4, 2, v4
	v_mov_b32_e32 v5, v1
	s_and_b32 s16, s3, 7
	s_lshl_b32 s16, s16, 5
	s_lshr_b32 s7, s3, 3
	s_or_b32 s16, s16, s7
	s_cmp_eq_u32 s76, 0x100
	s_cselect_b32 s16, s16, s3
	s_lshl_b32 s7, s16, 6

; #define PG8_STAGE(bufoff, gbase, voff) do { _Pragma("unroll") for (int _i = 0; _i < 2; ++_i) \
;         __builtin_amdgcn_global_load_lds((const unsigned*)((const char*)(gbase) + (voff)[_i]), (LAS unsigned*)(lds + (bufoff) + ldsw + _i * 8192), 16, 0, 0); } while (0)
; #define PG8_WAIT_V(n) asm volatile("s_waitcnt vmcnt(" #n ")" ::: "memory")
; #define PG8_BAR __builtin_amdgcn_s_barrier()
; template <class Epi, bool ALIGN_EPI>
; __device__ __forceinline__ void gemm_phase(LAS unsigned char* lds, const Gemm g, const StaticOrder& S, const Epi& E) {
;     int tid_ = threadIdx.x; asm volatile("" : "+v"(tid_));
;     const int tid = tid_, wid = __builtin_amdgcn_readfirstlane(tid >> 6), lane = tid & 63, wr = wid >> 2, wc = wid & 3, fr = lane & 15, fq = lane >> 4;
;     const int K = g.K, nt = K / BK, lda = g.lda;
;     unsigned voffA[2], voffB[2];
; #pragma unroll
;     for (int i = 0; i < 2; ++i) { int R, C; stage_rc(tid * 16 + i * 8192, R, C); const int Rb = Epi::PERM ? ((R & ~31) + perm32(R & 31)) : R;
;         voffA[i] = (unsigned)(R * lda + C) * 2u; voffB[i] = (unsigned)(Rb * K + C) * 2u; }
;     const size_t kstep = (size_t)(BK * 2);
;     const size_t hstepA = (size_t)HALF * lda * 2, hstepB = (size_t)HALF * K * 2;
;     const size_t tstepA = 2 * hstepA, tstepB = 2 * hstepB;
;     const unsigned ldsw = (unsigned)wid * 1024u;
;     const int aoff = lds_byte(wr * 64 + fr, fq * 8), boff = lds_byte(wc * 32 + fr, fq * 8);
;     ...
;     Unit cur, nxt; int ui = 0;
;     if (!S.next(0, cur)) return;
;     f32x4 acc[2][2][4][2];
; #pragma unroll
;     for (int a = 0; a < 2; ++a)
; #pragma unroll
;         for (int b = 0; b < 2; ++b)
; #pragma unroll
;             for (int m = 0; m < 4; ++m)
; #pragma unroll
;                 for (int n = 0; n < 2; ++n) acc[a][b][m][n] = (f32x4){0.f, 0.f, 0.f, 0.f};
;     bf16x8 At[4][2], B0[2][2], B1[2][2];
;     const char* cA = (const char*)g.A + (size_t)cur.pm * tstepA; const char* cB = (const char*)g.Bt + (size_t)cur.pn * tstepB;
;     PG8_STAGE(PG8_SB(0, 0), cB, voffB); PG8_STAGE(PG8_SB(0, 1), cB + hstepB, voffB); PG8_STAGE(PG8_SA(0, 0), cA, voffA); PG8_STAGE(PG8_SA(0, 1), cA + hstepA, voffA);
;     if (wr == 1) PG8_BAR;
;     PG8_WAIT_V(2); PG8_BAR;
;     PG8_STAGE(PG8_SB(1, 0), cB + kstep, voffB); PG8_STAGE(PG8_SA(1, 0), cA + kstep, voffA); PG8_STAGE(PG8_SB(1, 1), cB + hstepB + kstep, voffB);
;     PG8_WAIT_V(6); PG8_BAR;
.Lprio_skip_3:
	s_waitcnt lgkmcnt(0)
	v_mov_b32_e32 v0, v166
	s_barrier
	s_add_i32 s2, 0, 0x230ec
	s_add_i32 s28, 0, 0x230e8
	v_mov_b32_e32 v0, s2
	v_mov_b32_e32 v2, s28
	ds_read_b32 v1, v0
	ds_read_b32 v3, v2
	ds_read_b32 v0, v0
	ds_read_b32 v2, v2
	v_readlane_b32 s8, v252, 14
	v_mov_b32_e32 v8, v166
	v_readlane_b32 s9, v252, 15
	s_waitcnt lgkmcnt(3)
	v_readfirstlane_b32 s7, v1
	s_waitcnt lgkmcnt(2)
	v_readfirstlane_b32 s6, v3
	s_waitcnt lgkmcnt(1)
	v_readfirstlane_b32 s0, v0
	s_waitcnt lgkmcnt(0)
	v_readfirstlane_b32 s4, v2
	s_and_b64 vcc, exec, s[8:9]
	v_readfirstlane_b32 s1, v8
	s_cbranch_vccnz .LBB0_824
	v_lshlrev_b32_e32 v0, 4, v8
	v_add_u32_e32 v1, 0x2000, v0
	v_ashrrev_i32_e32 v2, 31, v1
	v_lshrrev_b32_e32 v2, 22, v2
	v_add_u32_e32 v2, v1, v2
	v_ashrrev_i32_e32 v9, 10, v2
	v_mul_i32_i24_e32 v2, 0x400, v9
	v_sub_u32_e32 v1, v1, v2
	v_lshrrev_b32_e32 v2, 4, v1
	v_bitop3_b32 v1, v2, v1, 32 bitop3:0x6c
	v_ashrrev_i32_e32 v2, 31, v1
	v_lshrrev_b32_e32 v2, 26, v2
	s_add_u32 s29, s6, 0x2200000
	v_add_u32_e32 v2, v1, v2
	v_lshlrev_b32_e32 v3, 3, v9
	s_addc_u32 s30, s7, 0
	v_ashrrev_i32_e32 v10, 6, v2
	v_and_b32_e32 v3, -16, v3
	s_add_u32 s31, s4, 0x1600000
	v_add_u32_e32 v3, v10, v3
	s_addc_u32 s33, s0, 0
	v_and_b32_e32 v4, 3, v10
	s_mov_b32 s0, 0x1fffe0
	v_lshrrev_b32_e32 v5, 2, v3
	v_lshlrev_b32_e32 v6, 1, v3
	v_and_b32_e32 v2, 0xc0, v2
	v_and_or_b32 v4, v3, s0, v4
	v_and_b32_e32 v5, 4, v5
	v_and_b32_e32 v6, 24, v6
	v_sub_u32_e32 v1, v1, v2
	v_mov_b32_e32 v2, 1
	v_or3_b32 v4, v4, v5, v6
	v_lshlrev_b32_e32 v5, 5, v9
	v_ashrrev_i16_sdwa v1, v2, sext(v1) dst_sel:DWORD dst_unused:UNUSED_PAD src0_sel:DWORD src1_sel:BYTE_0
	v_and_b32_e32 v5, 32, v5
	v_bfe_i32 v11, v1, 0, 16
	v_add_lshl_u32 v1, v5, v11, 1
	v_lshl_add_u32 v128, v4, 11, v1
	v_lshl_add_u32 v130, v3, 12, v1
	v_bfe_i32 v1, v8, 27, 1
	v_lshrrev_b32_e32 v1, 22, v1
	v_add_u32_e32 v1, v0, v1
	v_and_b32_e32 v1, 0xfffffc00, v1
	v_sub_u32_e32 v0, v0, v1
	v_lshrrev_b32_e32 v1, 4, v0
	v_ashrrev_i32_e32 v3, 31, v8
	v_bitop3_b32 v0, v1, v0, 32 bitop3:0x6c
	v_lshrrev_b32_e32 v3, 26, v3
	v_ashrrev_i32_e32 v1, 31, v0
	v_add_u32_e32 v3, v8, v3
	v_lshrrev_b32_e32 v1, 26, v1
	v_ashrrev_i32_e32 v13, 6, v3
	v_add_u32_e32 v1, v0, v1
	v_lshlrev_b32_e32 v3, 3, v13
	v_ashrrev_i32_e32 v12, 6, v1
	v_and_b32_e32 v3, -16, v3
	v_add_u32_e32 v3, v12, v3
	v_and_b32_e32 v4, 3, v12
	s_ashr_i32 s35, s3, 31
	v_and_or_b32 v4, v3, s0, v4
	s_lshr_b32 s0, s35, 29
	s_add_i32 s0, s3, s0
	s_ashr_i32 s8, s1, 6
	s_ashr_i32 s4, s0, 3
	s_and_b32 s0, s0, -8
	s_ashr_i32 s10, s1, 8
	s_lshl_b32 s34, s8, 10
	s_sub_i32 s0, s3, s0
	s_cmp_lt_i32 s0, 0
	s_movk_i32 s36, 0x61
	s_cselect_b32 s5, s36, 0x60
	s_mul_i32 s0, s5, s0
	s_add_i32 s0, s0, s4
	s_ashr_i32 s4, s0, 31
	s_lshr_b32 s4, s4, 26
	s_add_i32 s4, s0, s4
	s_ashr_i32 s5, s4, 6
	s_andn2_b32 s4, s4, 63
	s_sub_i32 s4, s0, s4
	s_bfe_i32 s0, s4, 0x80000
	s_bfe_u32 s0, s0, 0x3000c
	s_add_i32 s9, s4, s0
	s_bfe_i32 s0, s9, 0x80000
	s_and_b32 s9, s9, 0xf8
	s_sub_i32 s4, s4, s9
	s_lshl_b32 s5, s5, 3
	s_sext_i32_i16 s0, s0
	s_sext_i32_i8 s4, s4
	v_lshrrev_b32_e32 v5, 2, v3
	v_lshlrev_b32_e32 v6, 1, v3
	v_and_b32_e32 v1, 0xc0, v1
	s_lshr_b32 s0, s0, 3
	s_add_i32 s20, s5, s4
	v_and_b32_e32 v5, 4, v5
	v_and_b32_e32 v6, 24, v6
	v_sub_u32_e32 v0, v0, v1
	s_ashr_i32 s21, s20, 31
	s_bfe_i64 s[12:13], s[0:1], 0x100000
	v_or3_b32 v4, v4, v5, v6
	v_lshlrev_b32_e32 v5, 5, v13
	v_ashrrev_i16_sdwa v0, v2, sext(v0) dst_sel:DWORD dst_unused:UNUSED_PAD src0_sel:DWORD src1_sel:BYTE_0
	s_lshl_b64 s[4:5], s[20:21], 20
	s_lshl_b64 s[12:13], s[12:13], 19
	v_and_b32_e32 v5, 32, v5
	v_bfe_i32 v14, v0, 0, 16
	s_add_u32 s22, s31, s12
	v_add_lshl_u32 v0, v5, v14, 1
	s_addc_u32 s23, s33, s13
	s_add_i32 s21, s34, 0
	v_lshl_add_u32 v132, v4, 11, v0
	s_add_i32 m0, s21, 0x10000
	v_lshl_add_u32 v134, v3, 12, v0
	global_load_lds_dwordx4 v132, s[22:23]
	s_add_i32 m0, s21, 0x12000
	s_add_u32 s12, s22, 0x40000
	global_load_lds_dwordx4 v128, s[22:23]
	s_addc_u32 s13, s23, 0
	s_add_i32 m0, s21, 0x14000
	v_mov_b32_e32 v133, 0
	global_load_lds_dwordx4 v132, s[12:13]
	s_add_i32 m0, s21, 0x16000
	s_add_u32 s24, s29, s4
	s_addc_u32 s25, s30, s5
	s_add_i32 s37, s21, 0x2000
	global_load_lds_dwordx4 v128, s[12:13]
	s_mov_b32 m0, s21
	s_add_u32 s4, s24, 0x80000
	global_load_lds_dwordx4 v134, s[24:25]
	s_mov_b32 m0, s37
	s_addc_u32 s5, s25, 0
	s_add_i32 s38, s21, 0x4000
	global_load_lds_dwordx4 v130, s[24:25]
	s_mov_b32 m0, s38
	s_add_i32 s39, s21, 0x6000
	global_load_lds_dwordx4 v134, s[4:5]
	s_mov_b32 m0, s39
	v_mov_b32_e32 v129, v133
	global_load_lds_dwordx4 v130, s[4:5]
	v_mov_b32_e32 v135, v133
	v_mov_b32_e32 v131, v133
	s_cmp_eq_u32 s10, 1
	v_lshl_add_u64 v[6:7], s[22:23], 0, v[132:133]
	v_lshl_add_u64 v[4:5], s[22:23], 0, v[128:129]
	v_lshl_add_u64 v[0:1], s[24:25], 0, v[134:135]
	s_cselect_b64 s[4:5], -1, 0
	s_cmp_lg_u32 s10, 1
	v_lshl_add_u64 v[2:3], s[24:25], 0, v[130:131]
	s_cbranch_scc1 .LBB0_811
	s_barrier

; #define PG8_STAGE(bufoff, gbase, voff) do { _Pragma("unroll") for (int _i = 0; _i < 2; ++_i) \
;         __builtin_amdgcn_global_load_lds((const unsigned*)((const char*)(gbase) + (voff)[_i]), (LAS unsigned*)(lds + (bufoff) + ldsw + _i * 8192), 16, 0, 0); } while (0)
; #define PG8_LDA(dst, b, h) do { _Pragma("unroll") for (int m = 0; m < 4; ++m) _Pragma("unroll") for (int k = 0; k < 2; ++k) dst[m][k] = *(const LAS bf16x8*)(lds + PG8_SA(b, h) + aoff + m * 2048 + k * 1024); } while (0)
; #define PG8_LDB(dst, b, h) do { _Pragma("unroll") for (int n = 0; n < 2; ++n) _Pragma("unroll") for (int k = 0; k < 2; ++k) dst[n][k] = *(const LAS bf16x8*)(lds + PG8_SB(b, h) + boff + n * 2048 + k * 1024); } while (0)
; #define PG8_MMA(ai, bj, At, Bt) do { __builtin_amdgcn_s_setprio(1); _Pragma("unroll") for (int m = 0; m < 4; ++m) _Pragma("unroll") for (int n = 0; n < 2; ++n) _Pragma("unroll") for (int k = 0; k < 2; ++k) \
;         acc[ai][bj][m][n] = __builtin_amdgcn_mfma_f32_16x16x32_bf16(Bt[n][k], At[m][k], acc[ai][bj][m][n], 0, 0, 0); __builtin_amdgcn_s_setprio(0); } while (0)
; #define PG8_WAIT_V(n) asm volatile("s_waitcnt vmcnt(" #n ")" ::: "memory")
; #define PG8_WAIT_L(n) asm volatile("s_waitcnt lgkmcnt(" #n ")" ::: "memory")
; #define PG8_BAR __builtin_amdgcn_s_barrier()
; #define PG8_SCHED __builtin_amdgcn_sched_barrier(0)
; template <class Epi, bool ALIGN_EPI>
; __device__ __forceinline__ void gemm_phase(LAS unsigned char* lds, const Gemm g, const StaticOrder& S, const Epi& E) {
;     ...
;             const bool last = (t == nt - 2);
;             const char* a1 = cA + (size_t)(t + 1) * kstep;
;             const char* a2 = last ? nA : cA + (size_t)(t + 2) * kstep; const char* b2 = last ? nB : cB + (size_t)(t + 2) * kstep;
;             const char* a3 = a2 + kstep; const char* b3 = b2 + kstep;
;             PG8_LDB(B0, 0, 0); PG8_LDB(B1, 0, 1); PG8_SCHED; PG8_LDA(At, 0, 0); PG8_STAGE(PG8_SA(1, 1), a1 + hstepA, voffA);
;             PG8_WAIT_V(8); PG8_WAIT_L(0); PG8_BAR; PG8_MMA(0, 0, At, B0); PG8_MMA(0, 1, At, B1); PG8_BAR; PG8_SCHED;
;             PG8_LDA(At, 0, 1); PG8_STAGE(PG8_SB(0, 0), b2, voffB); PG8_STAGE(PG8_SB(0, 1), b2 + hstepB, voffB); PG8_STAGE(PG8_SA(0, 0), a2, voffA);
;             PG8_WAIT_V(8); PG8_WAIT_L(0); PG8_BAR; PG8_MMA(1, 0, At, B0); PG8_MMA(1, 1, At, B1); PG8_BAR; PG8_SCHED;
.LBB0_817:
	ds_read_b128 v[152:155], v149
	ds_read_b128 v[156:159], v149 offset:1024
	ds_read_b128 v[160:163], v149 offset:2048
	ds_read_b128 v[168:171], v149 offset:3072
	ds_read_b128 v[172:175], v150
	ds_read_b128 v[176:179], v150 offset:1024
	ds_read_b128 v[180:183], v150 offset:2048
	ds_read_b128 v[184:187], v150 offset:3072
	s_add_u32 s24, s22, 0xfff80080
	s_addc_u32 s25, s23, -1
	s_cmp_eq_u32 s56, 12
	s_cselect_b32 s27, s15, s25
	s_cselect_b32 s26, s52, s24
	s_cselect_b32 s25, s13, s55
	s_cselect_b32 s24, s53, s54
	v_lshl_add_u64 v[144:145], s[22:23], 0, v[138:139]
	s_add_i32 m0, s21, 0xc000
	ds_read_b128 v[188:191], v151
	ds_read_b128 v[192:195], v151 offset:1024
	ds_read_b128 v[196:199], v151 offset:2048
	ds_read_b128 v[200:203], v151 offset:3072
	ds_read_b128 v[204:207], v151 offset:4096
	ds_read_b128 v[208:211], v151 offset:5120
	ds_read_b128 v[212:215], v151 offset:6144
	ds_read_b128 v[216:219], v151 offset:7168
	global_load_lds_dwordx4 v[144:145], off
	v_lshl_add_u64 v[144:145], s[22:23], 0, v[136:137]
	s_add_i32 m0, s21, 0xe000
	s_nop 0
	global_load_lds_dwordx4 v[144:145], off
	s_waitcnt vmcnt(8)
	s_waitcnt lgkmcnt(0)
	s_barrier
	v_mfma_f32_16x16x32_bf16 v[124:127], v[152:155], v[188:191], v[124:127]
	v_mfma_f32_16x16x32_bf16 v[120:123], v[160:163], v[188:191], v[120:123]
	v_mfma_f32_16x16x32_bf16 v[108:111], v[152:155], v[196:199], v[108:111]
	v_mfma_f32_16x16x32_bf16 v[104:107], v[160:163], v[196:199], v[104:107]
	v_mfma_f32_16x16x32_bf16 v[92:95], v[152:155], v[204:207], v[92:95]
	v_mfma_f32_16x16x32_bf16 v[88:91], v[160:163], v[204:207], v[88:91]
	v_mfma_f32_16x16x32_bf16 v[76:79], v[152:155], v[212:215], v[76:79]
	v_mfma_f32_16x16x32_bf16 v[72:75], v[160:163], v[212:215], v[72:75]
	v_mfma_f32_16x16x32_bf16 v[124:127], v[156:159], v[192:195], v[124:127]
	v_mfma_f32_16x16x32_bf16 v[120:123], v[168:171], v[192:195], v[120:123]
	v_mfma_f32_16x16x32_bf16 v[108:111], v[156:159], v[200:203], v[108:111]
	v_mfma_f32_16x16x32_bf16 v[104:107], v[168:171], v[200:203], v[104:107]
	v_mfma_f32_16x16x32_bf16 v[92:95], v[156:159], v[208:211], v[92:95]
	v_mfma_f32_16x16x32_bf16 v[88:91], v[168:171], v[208:211], v[88:91]
	v_mfma_f32_16x16x32_bf16 v[76:79], v[156:159], v[216:219], v[76:79]
	v_mfma_f32_16x16x32_bf16 v[72:75], v[168:171], v[216:219], v[72:75]
	v_mfma_f32_16x16x32_bf16 v[116:119], v[172:175], v[188:191], v[116:119]
	v_mfma_f32_16x16x32_bf16 v[112:115], v[180:183], v[188:191], v[112:115]
	v_mfma_f32_16x16x32_bf16 v[100:103], v[172:175], v[196:199], v[100:103]
	v_mfma_f32_16x16x32_bf16 v[96:99], v[180:183], v[196:199], v[96:99]
	v_mfma_f32_16x16x32_bf16 v[84:87], v[172:175], v[204:207], v[84:87]
	v_mfma_f32_16x16x32_bf16 v[80:83], v[180:183], v[204:207], v[80:83]
	v_mfma_f32_16x16x32_bf16 v[68:71], v[172:175], v[212:215], v[68:71]
	v_mfma_f32_16x16x32_bf16 v[64:67], v[180:183], v[212:215], v[64:67]
	v_mfma_f32_16x16x32_bf16 v[116:119], v[176:179], v[192:195], v[116:119]
	v_mfma_f32_16x16x32_bf16 v[112:115], v[184:187], v[192:195], v[112:115]
	v_mfma_f32_16x16x32_bf16 v[100:103], v[176:179], v[200:203], v[100:103]
	v_mfma_f32_16x16x32_bf16 v[96:99], v[184:187], v[200:203], v[96:99]
	v_mfma_f32_16x16x32_bf16 v[84:87], v[176:179], v[208:211], v[84:87]
	v_mfma_f32_16x16x32_bf16 v[80:83], v[184:187], v[208:211], v[80:83]
	v_mfma_f32_16x16x32_bf16 v[68:71], v[176:179], v[216:219], v[68:71]
	v_mfma_f32_16x16x32_bf16 v[64:67], v[184:187], v[216:219], v[64:67]
	s_barrier
	s_add_i32 s57, s45, s34
	v_lshl_add_u64 v[144:145], s[24:25], 0, v[132:133]
	s_mov_b32 m0, s57
	ds_read_b128 v[188:191], v151 offset:16384
	ds_read_b128 v[192:195], v151 offset:17408
	ds_read_b128 v[196:199], v151 offset:18432
	ds_read_b128 v[200:203], v151 offset:19456
	ds_read_b128 v[204:207], v151 offset:20480
	ds_read_b128 v[208:211], v151 offset:21504
	ds_read_b128 v[212:215], v151 offset:22528
	ds_read_b128 v[216:219], v151 offset:23552
	global_load_lds_dwordx4 v[144:145], off
	s_add_i32 m0, s57, 0x2000
	s_add_u32 s58, s24, 0x40000
	v_lshl_add_u64 v[164:165], s[24:25], 0, v[128:129]
	s_addc_u32 s59, s25, 0
	s_add_i32 s57, s46, s34
	global_load_lds_dwordx4 v[164:165], off
	v_lshl_add_u64 v[220:221], s[58:59], 0, v[132:133]
	s_mov_b32 m0, s57
	v_lshl_add_u64 v[222:223], s[26:27], 0, v[130:131]
	global_load_lds_dwordx4 v[220:221], off
	v_lshl_add_u64 v[220:221], s[58:59], 0, v[128:129]
	s_add_i32 m0, s57, 0x2000
	s_nop 0
	global_load_lds_dwordx4 v[220:221], off
	v_lshl_add_u64 v[220:221], s[26:27], 0, v[134:135]
	s_mov_b32 m0, s21
	s_nop 0
	global_load_lds_dwordx4 v[220:221], off
	s_mov_b32 m0, s37
	s_nop 0
	global_load_lds_dwordx4 v[222:223], off
	s_waitcnt vmcnt(8)
	s_waitcnt lgkmcnt(0)
	s_barrier
; #define PG8_STAGE(bufoff, gbase, voff) do { _Pragma("unroll") for (int _i = 0; _i < 2; ++_i) \
;         __builtin_amdgcn_global_load_lds((const unsigned*)((const char*)(gbase) + (voff)[_i]), (LAS unsigned*)(lds + (bufoff) + ldsw + _i * 8192), 16, 0, 0); } while (0)
; #define PG8_LDA(dst, b, h) do { _Pragma("unroll") for (int m = 0; m < 4; ++m) _Pragma("unroll") for (int k = 0; k < 2; ++k) dst[m][k] = *(const LAS bf16x8*)(lds + PG8_SA(b, h) + aoff + m * 2048 + k * 1024); } while (0)
; #define PG8_LDB(dst, b, h) do { _Pragma("unroll") for (int n = 0; n < 2; ++n) _Pragma("unroll") for (int k = 0; k < 2; ++k) dst[n][k] = *(const LAS bf16x8*)(lds + PG8_SB(b, h) + boff + n * 2048 + k * 1024); } while (0)
; #define PG8_MMA(ai, bj, At, Bt) do { __builtin_amdgcn_s_setprio(1); _Pragma("unroll") for (int m = 0; m < 4; ++m) _Pragma("unroll") for (int n = 0; n < 2; ++n) _Pragma("unroll") for (int k = 0; k < 2; ++k) \
;         acc[ai][bj][m][n] = __builtin_amdgcn_mfma_f32_16x16x32_bf16(Bt[n][k], At[m][k], acc[ai][bj][m][n], 0, 0, 0); __builtin_amdgcn_s_setprio(0); } while (0)
; #define PG8_WAIT_V(n) asm volatile("s_waitcnt vmcnt(" #n ")" ::: "memory")
; #define PG8_WAIT_L(n) asm volatile("s_waitcnt lgkmcnt(" #n ")" ::: "memory")
; #define PG8_BAR __builtin_amdgcn_s_barrier()
; #define PG8_SCHED __builtin_amdgcn_sched_barrier(0)
; template <class Epi, bool ALIGN_EPI>
; __device__ __forceinline__ void gemm_phase(LAS unsigned char* lds, const Gemm g, const StaticOrder& S, const Epi& E) {
;     ...
;             PG8_WAIT_V(8); PG8_WAIT_L(0); PG8_BAR; PG8_MMA(1, 0, At, B0); PG8_MMA(1, 1, At, B1); PG8_BAR; PG8_SCHED;
;             PG8_LDB(B0, 1, 0); PG8_LDB(B1, 1, 1); PG8_SCHED; PG8_LDA(At, 1, 0); PG8_STAGE(PG8_SA(0, 1), a2 + hstepA, voffA);
;             PG8_WAIT_V(8); PG8_WAIT_L(0); PG8_BAR; PG8_MMA(0, 0, At, B0); PG8_MMA(0, 1, At, B1); PG8_BAR; PG8_SCHED;
	v_mfma_f32_16x16x32_bf16 v[60:63], v[152:155], v[188:191], v[60:63]
	v_mfma_f32_16x16x32_bf16 v[56:59], v[160:163], v[188:191], v[56:59]
	v_mfma_f32_16x16x32_bf16 v[44:47], v[152:155], v[196:199], v[44:47]
	v_mfma_f32_16x16x32_bf16 v[40:43], v[160:163], v[196:199], v[40:43]
	v_mfma_f32_16x16x32_bf16 v[28:31], v[152:155], v[204:207], v[28:31]
	v_mfma_f32_16x16x32_bf16 v[24:27], v[160:163], v[204:207], v[24:27]
	v_mfma_f32_16x16x32_bf16 v[12:15], v[152:155], v[212:215], v[12:15]
	v_mfma_f32_16x16x32_bf16 v[8:11], v[160:163], v[212:215], v[8:11]
	v_mfma_f32_16x16x32_bf16 v[60:63], v[156:159], v[192:195], v[60:63]
	v_mfma_f32_16x16x32_bf16 v[56:59], v[168:171], v[192:195], v[56:59]
	v_mfma_f32_16x16x32_bf16 v[44:47], v[156:159], v[200:203], v[44:47]
	v_mfma_f32_16x16x32_bf16 v[40:43], v[168:171], v[200:203], v[40:43]
	v_mfma_f32_16x16x32_bf16 v[28:31], v[156:159], v[208:211], v[28:31]
	v_mfma_f32_16x16x32_bf16 v[24:27], v[168:171], v[208:211], v[24:27]
	v_mfma_f32_16x16x32_bf16 v[12:15], v[156:159], v[216:219], v[12:15]
	v_mfma_f32_16x16x32_bf16 v[8:11], v[168:171], v[216:219], v[8:11]
	v_mfma_f32_16x16x32_bf16 v[52:55], v[172:175], v[188:191], v[52:55]
	v_mfma_f32_16x16x32_bf16 v[48:51], v[180:183], v[188:191], v[48:51]
	v_mfma_f32_16x16x32_bf16 v[36:39], v[172:175], v[196:199], v[36:39]
	v_mfma_f32_16x16x32_bf16 v[32:35], v[180:183], v[196:199], v[32:35]
	v_mfma_f32_16x16x32_bf16 v[20:23], v[172:175], v[204:207], v[20:23]
	v_mfma_f32_16x16x32_bf16 v[16:19], v[180:183], v[204:207], v[16:19]
	v_mfma_f32_16x16x32_bf16 v[4:7], v[172:175], v[212:215], v[4:7]
	v_mfma_f32_16x16x32_bf16 v[0:3], v[180:183], v[212:215], v[0:3]
	v_mfma_f32_16x16x32_bf16 v[52:55], v[176:179], v[192:195], v[52:55]
	v_mfma_f32_16x16x32_bf16 v[48:51], v[184:187], v[192:195], v[48:51]
	v_mfma_f32_16x16x32_bf16 v[36:39], v[176:179], v[200:203], v[36:39]
	v_mfma_f32_16x16x32_bf16 v[32:35], v[184:187], v[200:203], v[32:35]
	v_mfma_f32_16x16x32_bf16 v[20:23], v[176:179], v[208:211], v[20:23]
	v_mfma_f32_16x16x32_bf16 v[16:19], v[184:187], v[208:211], v[16:19]
	v_mfma_f32_16x16x32_bf16 v[4:7], v[176:179], v[216:219], v[4:7]
	v_mfma_f32_16x16x32_bf16 v[0:3], v[184:187], v[216:219], v[0:3]
	s_barrier
	s_add_i32 s57, 0, 0x18000
	s_add_i32 s58, 0, 0x1c000
	v_add_u32_e32 v168, s57, v147
	v_add_u32_e32 v184, s58, v147
	ds_read_b128 v[152:155], v168
	ds_read_b128 v[156:159], v168 offset:1024
	ds_read_b128 v[160:163], v168 offset:2048
	ds_read_b128 v[168:171], v168 offset:3072
	ds_read_b128 v[172:175], v184
	ds_read_b128 v[176:179], v184 offset:1024
	ds_read_b128 v[180:183], v184 offset:2048
	ds_read_b128 v[184:187], v184 offset:3072
	s_add_u32 s26, s26, 0x80000
	s_addc_u32 s27, s27, 0
	s_mov_b32 m0, s38
	v_lshl_add_u64 v[224:225], s[26:27], 0, v[134:135]
	ds_read_b128 v[188:191], v151 offset:32768
	ds_read_b128 v[192:195], v151 offset:33792
	ds_read_b128 v[196:199], v151 offset:34816
	ds_read_b128 v[200:203], v151 offset:35840
	ds_read_b128 v[204:207], v151 offset:36864
	ds_read_b128 v[208:211], v151 offset:37888
	ds_read_b128 v[212:215], v151 offset:38912
	ds_read_b128 v[216:219], v151 offset:39936
	global_load_lds_dwordx4 v[224:225], off
	v_lshl_add_u64 v[224:225], s[26:27], 0, v[130:131]
	s_mov_b32 m0, s39
	s_nop 0
	global_load_lds_dwordx4 v[224:225], off
	s_waitcnt vmcnt(8)
	s_waitcnt lgkmcnt(0)
	s_barrier
	v_mfma_f32_16x16x32_bf16 v[124:127], v[152:155], v[188:191], v[124:127]
	v_mfma_f32_16x16x32_bf16 v[120:123], v[160:163], v[188:191], v[120:123]
	v_mfma_f32_16x16x32_bf16 v[108:111], v[152:155], v[196:199], v[108:111]
	v_mfma_f32_16x16x32_bf16 v[104:107], v[160:163], v[196:199], v[104:107]
	v_mfma_f32_16x16x32_bf16 v[92:95], v[152:155], v[204:207], v[92:95]
	v_mfma_f32_16x16x32_bf16 v[88:91], v[160:163], v[204:207], v[88:91]
	v_mfma_f32_16x16x32_bf16 v[76:79], v[152:155], v[212:215], v[76:79]
	v_mfma_f32_16x16x32_bf16 v[72:75], v[160:163], v[212:215], v[72:75]
	v_mfma_f32_16x16x32_bf16 v[124:127], v[156:159], v[192:195], v[124:127]
	v_mfma_f32_16x16x32_bf16 v[120:123], v[168:171], v[192:195], v[120:123]
	v_mfma_f32_16x16x32_bf16 v[108:111], v[156:159], v[200:203], v[108:111]
	v_mfma_f32_16x16x32_bf16 v[104:107], v[168:171], v[200:203], v[104:107]
	v_mfma_f32_16x16x32_bf16 v[92:95], v[156:159], v[208:211], v[92:95]
	v_mfma_f32_16x16x32_bf16 v[88:91], v[168:171], v[208:211], v[88:91]
	v_mfma_f32_16x16x32_bf16 v[76:79], v[156:159], v[216:219], v[76:79]
	v_mfma_f32_16x16x32_bf16 v[72:75], v[168:171], v[216:219], v[72:75]
	v_mfma_f32_16x16x32_bf16 v[116:119], v[172:175], v[188:191], v[116:119]
	v_mfma_f32_16x16x32_bf16 v[112:115], v[180:183], v[188:191], v[112:115]
	v_mfma_f32_16x16x32_bf16 v[100:103], v[172:175], v[196:199], v[100:103]
	v_mfma_f32_16x16x32_bf16 v[96:99], v[180:183], v[196:199], v[96:99]
	v_mfma_f32_16x16x32_bf16 v[84:87], v[172:175], v[204:207], v[84:87]
	v_mfma_f32_16x16x32_bf16 v[80:83], v[180:183], v[204:207], v[80:83]
	v_mfma_f32_16x16x32_bf16 v[68:71], v[172:175], v[212:215], v[68:71]
	v_mfma_f32_16x16x32_bf16 v[64:67], v[180:183], v[212:215], v[64:67]
	v_mfma_f32_16x16x32_bf16 v[116:119], v[176:179], v[192:195], v[116:119]
	v_mfma_f32_16x16x32_bf16 v[112:115], v[184:187], v[192:195], v[112:115]
	v_mfma_f32_16x16x32_bf16 v[100:103], v[176:179], v[200:203], v[100:103]
	v_mfma_f32_16x16x32_bf16 v[96:99], v[184:187], v[200:203], v[96:99]
	v_mfma_f32_16x16x32_bf16 v[84:87], v[176:179], v[208:211], v[84:87]
	v_mfma_f32_16x16x32_bf16 v[80:83], v[184:187], v[208:211], v[80:83]
	v_mfma_f32_16x16x32_bf16 v[68:71], v[176:179], v[216:219], v[68:71]
	v_mfma_f32_16x16x32_bf16 v[64:67], v[184:187], v[216:219], v[64:67]
	s_barrier
; #define PG8_STAGE(bufoff, gbase, voff) do { _Pragma("unroll") for (int _i = 0; _i < 2; ++_i) \
;         __builtin_amdgcn_global_load_lds((const unsigned*)((const char*)(gbase) + (voff)[_i]), (LAS unsigned*)(lds + (bufoff) + ldsw + _i * 8192), 16, 0, 0); } while (0)
; #define PG8_LDA(dst, b, h) do { _Pragma("unroll") for (int m = 0; m < 4; ++m) _Pragma("unroll") for (int k = 0; k < 2; ++k) dst[m][k] = *(const LAS bf16x8*)(lds + PG8_SA(b, h) + aoff + m * 2048 + k * 1024); } while (0)
; #define PG8_MMA(ai, bj, At, Bt) do { __builtin_amdgcn_s_setprio(1); _Pragma("unroll") for (int m = 0; m < 4; ++m) _Pragma("unroll") for (int n = 0; n < 2; ++n) _Pragma("unroll") for (int k = 0; k < 2; ++k) \
;         acc[ai][bj][m][n] = __builtin_amdgcn_mfma_f32_16x16x32_bf16(Bt[n][k], At[m][k], acc[ai][bj][m][n], 0, 0, 0); __builtin_amdgcn_s_setprio(0); } while (0)
; #define PG8_WAIT_V(n) asm volatile("s_waitcnt vmcnt(" #n ")" ::: "memory")
; #define PG8_WAIT_L(n) asm volatile("s_waitcnt lgkmcnt(" #n ")" ::: "memory")
; #define PG8_BAR __builtin_amdgcn_s_barrier()
; #define PG8_SCHED __builtin_amdgcn_sched_barrier(0)
; template <class Epi, bool ALIGN_EPI>
; __device__ __forceinline__ void gemm_phase(LAS unsigned char* lds, const Gemm g, const StaticOrder& S, const Epi& E) {
;     ...
;             PG8_LDA(At, 1, 1); PG8_STAGE(PG8_SB(1, 0), b3, voffB); PG8_STAGE(PG8_SB(1, 1), b3 + hstepB, voffB); PG8_STAGE(PG8_SA(1, 0), a3, voffA);
;             PG8_WAIT_V(8); PG8_WAIT_L(0); PG8_BAR; PG8_MMA(1, 0, At, B0); PG8_MMA(1, 1, At, B1); PG8_BAR; PG8_SCHED;
;         }
	s_add_i32 s26, s57, s34
	v_lshl_add_u64 v[144:145], v[144:145], 0, s[8:9]
	s_mov_b32 m0, s26
	ds_read_b128 v[188:191], v151 offset:49152
	ds_read_b128 v[192:195], v151 offset:50176
	ds_read_b128 v[196:199], v151 offset:51200
	ds_read_b128 v[200:203], v151 offset:52224
	ds_read_b128 v[204:207], v151 offset:53248
	ds_read_b128 v[208:211], v151 offset:54272
	ds_read_b128 v[212:215], v151 offset:55296
	ds_read_b128 v[216:219], v151 offset:56320
	global_load_lds_dwordx4 v[144:145], off
	s_add_i32 m0, s26, 0x2000
	s_add_u32 s24, s24, 0x40080
	v_lshl_add_u64 v[144:145], v[164:165], 0, s[8:9]
	s_addc_u32 s25, s25, 0
	s_add_i32 s26, s58, s34
	global_load_lds_dwordx4 v[144:145], off
	v_lshl_add_u64 v[144:145], s[24:25], 0, v[132:133]
	s_mov_b32 m0, s26
	s_nop 0
	global_load_lds_dwordx4 v[144:145], off
	v_lshl_add_u64 v[144:145], s[24:25], 0, v[128:129]
	s_add_i32 m0, s26, 0x2000
	s_nop 0
	global_load_lds_dwordx4 v[144:145], off
	v_lshl_add_u64 v[144:145], v[220:221], 0, s[8:9]
	s_mov_b32 m0, s40
	s_nop 0
	global_load_lds_dwordx4 v[144:145], off
	v_lshl_add_u64 v[144:145], v[222:223], 0, s[8:9]
	s_mov_b32 m0, s41
	s_nop 0
	global_load_lds_dwordx4 v[144:145], off
	s_waitcnt vmcnt(8)
	s_waitcnt lgkmcnt(0)
	s_barrier
	v_mfma_f32_16x16x32_bf16 v[60:63], v[152:155], v[188:191], v[60:63]
	v_mfma_f32_16x16x32_bf16 v[56:59], v[160:163], v[188:191], v[56:59]
	v_mfma_f32_16x16x32_bf16 v[44:47], v[152:155], v[196:199], v[44:47]
	v_mfma_f32_16x16x32_bf16 v[40:43], v[160:163], v[196:199], v[40:43]
	v_mfma_f32_16x16x32_bf16 v[28:31], v[152:155], v[204:207], v[28:31]
	v_mfma_f32_16x16x32_bf16 v[24:27], v[160:163], v[204:207], v[24:27]
	v_mfma_f32_16x16x32_bf16 v[12:15], v[152:155], v[212:215], v[12:15]
	v_mfma_f32_16x16x32_bf16 v[8:11], v[160:163], v[212:215], v[8:11]
	v_mfma_f32_16x16x32_bf16 v[60:63], v[156:159], v[192:195], v[60:63]
	v_mfma_f32_16x16x32_bf16 v[56:59], v[168:171], v[192:195], v[56:59]
	v_mfma_f32_16x16x32_bf16 v[44:47], v[156:159], v[200:203], v[44:47]
	v_mfma_f32_16x16x32_bf16 v[40:43], v[168:171], v[200:203], v[40:43]
	v_mfma_f32_16x16x32_bf16 v[28:31], v[156:159], v[208:211], v[28:31]
	v_mfma_f32_16x16x32_bf16 v[24:27], v[168:171], v[208:211], v[24:27]
	v_mfma_f32_16x16x32_bf16 v[12:15], v[156:159], v[216:219], v[12:15]
	v_mfma_f32_16x16x32_bf16 v[8:11], v[168:171], v[216:219], v[8:11]
	v_mfma_f32_16x16x32_bf16 v[52:55], v[172:175], v[188:191], v[52:55]
	v_mfma_f32_16x16x32_bf16 v[48:51], v[180:183], v[188:191], v[48:51]
	v_mfma_f32_16x16x32_bf16 v[36:39], v[172:175], v[196:199], v[36:39]
	v_mfma_f32_16x16x32_bf16 v[32:35], v[180:183], v[196:199], v[32:35]
	v_mfma_f32_16x16x32_bf16 v[20:23], v[172:175], v[204:207], v[20:23]
	v_mfma_f32_16x16x32_bf16 v[16:19], v[180:183], v[204:207], v[16:19]
	v_mfma_f32_16x16x32_bf16 v[4:7], v[172:175], v[212:215], v[4:7]
	v_mfma_f32_16x16x32_bf16 v[0:3], v[180:183], v[212:215], v[0:3]
	v_mfma_f32_16x16x32_bf16 v[52:55], v[176:179], v[192:195], v[52:55]
	v_mfma_f32_16x16x32_bf16 v[48:51], v[184:187], v[192:195], v[48:51]
	v_mfma_f32_16x16x32_bf16 v[36:39], v[176:179], v[200:203], v[36:39]
	v_mfma_f32_16x16x32_bf16 v[32:35], v[184:187], v[200:203], v[32:35]
	v_mfma_f32_16x16x32_bf16 v[20:23], v[176:179], v[208:211], v[20:23]
	v_mfma_f32_16x16x32_bf16 v[16:19], v[184:187], v[208:211], v[16:19]
	v_mfma_f32_16x16x32_bf16 v[4:7], v[176:179], v[216:219], v[4:7]
	v_mfma_f32_16x16x32_bf16 v[0:3], v[184:187], v[216:219], v[0:3]
	s_barrier
	s_add_i32 s56, s56, 2
	s_add_u32 s54, s54, 0x100
	s_addc_u32 s55, s55, 0
	s_add_u32 s22, s22, 0x100
	s_addc_u32 s23, s23, 0
	s_cmp_gt_u32 s56, 13
	s_cbranch_scc0 .LBB0_817
	s_and_b64 vcc, exec, s[10:11]
	s_cbranch_vccz .LBB0_820
	s_barrier

; #define WSP(off) (PTR(29) + (off))
; __device__ __forceinline__ void mlstm_scan(bf16_t* ST, float* NST, const float* DEC, int task) {
;     if (task < 131072) {
;         const int piece = task & 4095, chain = task >> 12, h = chain & 7, dir = (chain >> 3) & 1, seq = chain >> 4;
;         const int clo = seq ? 64 : 0, chi = seq ? 192 : 64, nc = chi - clo;
;         float run[4] = {0.f, 0.f, 0.f, 0.f};
; #pragma unroll 8
;         for (int i = 0; i < nc; ++i) {
;             const int c = dir ? (chi - 1 - i) : (clo + i);
;             u32x2* q = (u32x2*)(ST + (size_t)((c * 2 + dir) * 8 + h) * 16384 + piece * 4);
; template <int K>
; __device__ __forceinline__ void run_phase(LAS unsigned char* lds, volatile LAS unsigned* ptab) {
;     ...
;     if constexpr (K == 10) { bf16_t* ST = (bf16_t*)WSP(WS_ST); float* NST = (float*)WSP(WS_NST); const float* DEC = (const float*)WSP(WS_DEC);
;         for (int t = bx * 512 + tid; t < 131072 + 4096; t += G * 512) mlstm_scan(ST, NST, DEC, t); }
.LBB0_915:
	s_or_b64 exec, exec, s[0:1]
	s_setprio 0
	s_add_i32 s0, 0, 0x230ec
	s_waitcnt lgkmcnt(0)
	v_mov_b32_e32 v0, v166
	v_mov_b32_e32 v1, s0
	s_barrier
	ds_read_b32 v2, v1
	s_add_i32 s0, 0, 0x230e8
	v_add_u32_e32 v10, s82, v0
	s_mov_b32 s4, 0x21000
	v_cmp_gt_i32_e32 vcc, s4, v10
	s_waitcnt lgkmcnt(0)
	v_readfirstlane_b32 s2, v2
	v_mov_b32_e32 v2, s0
	ds_read_b32 v3, v2
	ds_read_b32 v4, v1
	ds_read_b32 v5, v2
	ds_read_b32 v1, v1
	ds_read_b32 v2, v2
	s_waitcnt lgkmcnt(4)
	v_readfirstlane_b32 s6, v3
	s_waitcnt lgkmcnt(3)
	v_readfirstlane_b32 s1, v4
	s_waitcnt lgkmcnt(2)
	v_readfirstlane_b32 s0, v5
	s_waitcnt lgkmcnt(1)
	v_readfirstlane_b32 s9, v1
	s_waitcnt lgkmcnt(0)
	v_readfirstlane_b32 s8, v2
	s_and_saveexec_b64 s[4:5], vcc
	s_cbranch_execz .LBB0_926
	s_add_u32 s6, s6, 0x18100000
	v_and_b32_e32 v0, 0x7f, v0
	s_addc_u32 s7, s2, 0
	v_lshlrev_b32_e32 v0, 2, v0
	v_mov_b32_e32 v1, 0
	s_add_u32 s8, s8, 0x1e300000
	v_lshl_add_u64 v[2:3], s[0:1], 0, v[0:1]
	s_mov_b64 s[0:1], 0x1e100000
	s_addc_u32 s9, s9, 0
	s_lshl_b32 s2, s76, 9
	v_lshl_add_u64 v[2:3], v[2:3], 0, s[0:1]
	s_mov_b64 s[10:11], 0
	s_mov_b32 s16, 0x1ffff
	s_mov_b32 s17, 0x20000
	s_mov_b32 s18, 0x10000
	s_mov_b32 s19, 0x7060302
	s_mov_b32 s20, 0x20fff
	v_mov_b32_e32 v11, 0x47
	v_mov_b32_e32 v12, 0xffffff80
	v_not_b32_e32 v13, 63
	v_mov_b32_e32 v14, 0xbf
	s_branch .LBB0_918

; #define INP(k) ((const float*)PTR(k))
; #define WSP(off) (PTR(29) + (off))
;     __device__ bool next(int i, Unit& u) const {
;         const long L = (long)i * G + c; if (L >= nwg) return false;
;         int wgid = (int)L; { const int q = nwg / NXCD, r = nwg % NXCD, xcd = wgid % NXCD, off = wgid / NXCD; wgid = (xcd < r ? xcd * (q + 1) : r * (q + 1) + (xcd - r) * q) + off; }
;         const int nig = WGM * nN, gid = wgid / nig, fm = gid * WGM, gsz = (nM - fm) < WGM ? (nM - fm) : WGM;
;         u.pm = fm + ((wgid % nig) % gsz); u.pn = (wgid % nig) / gsz; return true;
; template <int K>
; __device__ __forceinline__ void run_phase(LAS unsigned char* lds, volatile LAS unsigned* ptab) {
;     ...
;         float* out = OUTP;
;         pg8::Gemm g{(const bf16_t*)WSP(WS_XN), (const bf16_t*)WSP(WS_WOUT), MROWS, DM, DM, DM}; pg8::StaticOrder S; S.init(MROWS, DM, G, bx);
;         pg8::EpiResid E{out, out + (size_t)SEQ_P * DM, out, DM, 1.0f, (bf16_t*)WSP(WS_XN2), INP(23), (float*)WSP(WS_SS2)};
.Lprio_skip_4:
	s_waitcnt lgkmcnt(0)
	v_mov_b32_e32 v0, v166
	s_barrier
	s_add_i32 s0, 0, 0x230e4
	v_mov_b32_e32 v0, s0
	s_add_i32 s0, 0, 0x230e0
	ds_read_b32 v0, v0
	v_mov_b32_e32 v1, s0
	ds_read_b32 v1, v1
	s_add_i32 s0, 0, 0x230ec
	v_readlane_b32 s16, v252, 14
	s_waitcnt lgkmcnt(1)
	v_readfirstlane_b32 s9, v0
	v_mov_b32_e32 v0, s0
	s_add_i32 s0, 0, 0x230e8
	s_waitcnt lgkmcnt(0)
	v_readfirstlane_b32 s8, v1
	ds_read_b32 v1, v0
	v_mov_b32_e32 v2, s0
	ds_read_b32 v3, v2
	ds_read_b32 v4, v0
	ds_read_b32 v5, v2
	ds_read_b32 v6, v0
	s_add_i32 s0, 0, 0x230bc
	s_waitcnt lgkmcnt(3)
	v_readfirstlane_b32 s2, v3
	v_mov_b32_e32 v3, s0
	s_add_i32 s0, 0, 0x230b8
	s_waitcnt lgkmcnt(2)
	v_readfirstlane_b32 s12, v4
	v_mov_b32_e32 v4, s0
	v_readfirstlane_b32 s5, v1
	ds_read_b32 v1, v2
	ds_read_b32 v3, v3
	ds_read_b32 v4, v4
	ds_read_b32 v0, v0
	ds_read_b32 v2, v2
	v_mov_b32_e32 v8, v166
	v_readlane_b32 s17, v252, 15
	s_waitcnt lgkmcnt(6)
	v_readfirstlane_b32 s13, v5
	s_waitcnt lgkmcnt(5)
	v_readfirstlane_b32 s1, v6
	s_waitcnt lgkmcnt(4)
	v_readfirstlane_b32 s14, v1
	s_waitcnt lgkmcnt(3)
	v_readfirstlane_b32 s11, v3
	s_waitcnt lgkmcnt(2)
	v_readfirstlane_b32 s10, v4
	s_waitcnt lgkmcnt(1)
	v_readfirstlane_b32 s6, v0
	s_waitcnt lgkmcnt(0)
	v_readfirstlane_b32 s7, v2
	s_and_b64 vcc, exec, s[16:17]
	v_readfirstlane_b32 s0, v8
	s_cbranch_vccnz .LBB0_1073
	s_ashr_i32 s4, s3, 31
	s_lshr_b32 s4, s4, 29
	s_add_i32 s4, s3, s4
	s_ashr_i32 s15, s4, 3
	s_and_b32 s4, s4, -8
	s_sub_i32 s4, s3, s4
	s_cmp_lt_i32 s4, 0
	s_movk_i32 s16, 0x61
	s_cselect_b32 s16, s16, 0x60
	s_mul_i32 s4, s16, s4
	s_add_i32 s4, s4, s15
	s_ashr_i32 s15, s4, 31
	s_lshr_b32 s15, s15, 26
	s_add_i32 s15, s4, s15
	s_ashr_i32 s16, s15, 6
	s_andn2_b32 s15, s15, 63
	s_sub_i32 s4, s4, s15
	s_bfe_i32 s15, s4, 0x80000
	s_bfe_u32 s15, s15, 0x3000c
	s_add_i32 s15, s4, s15
	s_bfe_i32 s17, s15, 0x80000
	s_and_b32 s15, s15, 0xf8
	s_sub_i32 s4, s4, s15
	s_lshl_b32 s16, s16, 3
	s_sext_i32_i16 s17, s17
	s_sext_i32_i8 s4, s4
	s_add_i32 s34, s16, s4
	s_ashr_i32 s4, s17, 3

; #define PG8_STAGE(bufoff, gbase, voff) do { _Pragma("unroll") for (int _i = 0; _i < 2; ++_i) \
;         __builtin_amdgcn_global_load_lds((const unsigned*)((const char*)(gbase) + (voff)[_i]), (LAS unsigned*)(lds + (bufoff) + ldsw + _i * 8192), 16, 0, 0); } while (0)
; #define PG8_LDA(dst, b, h) do { _Pragma("unroll") for (int m = 0; m < 4; ++m) _Pragma("unroll") for (int k = 0; k < 2; ++k) dst[m][k] = *(const LAS bf16x8*)(lds + PG8_SA(b, h) + aoff + m * 2048 + k * 1024); } while (0)
; #define PG8_LDB(dst, b, h) do { _Pragma("unroll") for (int n = 0; n < 2; ++n) _Pragma("unroll") for (int k = 0; k < 2; ++k) dst[n][k] = *(const LAS bf16x8*)(lds + PG8_SB(b, h) + boff + n * 2048 + k * 1024); } while (0)
; #define PG8_MMA(ai, bj, At, Bt) do { __builtin_amdgcn_s_setprio(1); _Pragma("unroll") for (int m = 0; m < 4; ++m) _Pragma("unroll") for (int n = 0; n < 2; ++n) _Pragma("unroll") for (int k = 0; k < 2; ++k) \
;         acc[ai][bj][m][n] = __builtin_amdgcn_mfma_f32_16x16x32_bf16(Bt[n][k], At[m][k], acc[ai][bj][m][n], 0, 0, 0); __builtin_amdgcn_s_setprio(0); } while (0)
; #define PG8_WAIT_V(n) asm volatile("s_waitcnt vmcnt(" #n ")" ::: "memory")
; #define PG8_WAIT_L(n) asm volatile("s_waitcnt lgkmcnt(" #n ")" ::: "memory")
; #define PG8_BAR __builtin_amdgcn_s_barrier()
; #define PG8_SCHED __builtin_amdgcn_sched_barrier(0)
; template <class Epi, bool ALIGN_EPI>
; __device__ __forceinline__ void gemm_phase(LAS unsigned char* lds, const Gemm g, const StaticOrder& S, const Epi& E) {
;     ...
;             const bool last = (t == nt - 2);
;             const char* a1 = cA + (size_t)(t + 1) * kstep;
;             const char* a2 = last ? nA : cA + (size_t)(t + 2) * kstep; const char* b2 = last ? nB : cB + (size_t)(t + 2) * kstep;
;             const char* a3 = a2 + kstep; const char* b3 = b2 + kstep;
;             PG8_LDB(B0, 0, 0); PG8_LDB(B1, 0, 1); PG8_SCHED; PG8_LDA(At, 0, 0); PG8_STAGE(PG8_SA(1, 1), a1 + hstepA, voffA);
;             PG8_WAIT_V(8); PG8_WAIT_L(0); PG8_BAR; PG8_MMA(0, 0, At, B0); PG8_MMA(0, 1, At, B1); PG8_BAR; PG8_SCHED;
;             PG8_LDA(At, 0, 1); PG8_STAGE(PG8_SB(0, 0), b2, voffB); PG8_STAGE(PG8_SB(0, 1), b2 + hstepB, voffB); PG8_STAGE(PG8_SA(0, 0), a2, voffA);
;             PG8_WAIT_V(8); PG8_WAIT_L(0); PG8_BAR; PG8_MMA(1, 0, At, B0); PG8_MMA(1, 1, At, B1); PG8_BAR; PG8_SCHED;
.LBB0_1082:
	ds_read_b128 v[64:67], v169
	ds_read_b128 v[72:75], v169 offset:1024
	ds_read_b128 v[76:79], v169 offset:2048
	ds_read_b128 v[84:87], v169 offset:3072
	ds_read_b128 v[156:159], v170
	ds_read_b128 v[160:163], v170 offset:1024
	ds_read_b128 v[174:177], v170 offset:2048
	ds_read_b128 v[178:181], v170 offset:3072
	s_add_u32 s38, s36, 0xfff80080
	s_addc_u32 s39, s37, -1
	s_cmp_eq_u32 s61, 28
	s_cselect_b32 s41, s5, s39
	s_cselect_b32 s40, s27, s38
	s_cselect_b32 s39, s25, s60
	s_cselect_b32 s38, s35, s59
	v_lshl_add_u64 v[214:215], s[36:37], 0, v[150:151]
	s_add_i32 m0, s45, 0xc000
	ds_read_b128 v[182:185], v171
	ds_read_b128 v[186:189], v171 offset:1024
	ds_read_b128 v[190:193], v171 offset:2048
	ds_read_b128 v[194:197], v171 offset:3072
	ds_read_b128 v[198:201], v171 offset:4096
	ds_read_b128 v[202:205], v171 offset:5120
	ds_read_b128 v[206:209], v171 offset:6144
	ds_read_b128 v[210:213], v171 offset:7168
	global_load_lds_dwordx4 v[214:215], off
	v_lshl_add_u64 v[214:215], s[36:37], 0, v[148:149]
	s_add_i32 m0, s45, 0xe000
	s_nop 0
	global_load_lds_dwordx4 v[214:215], off
	s_waitcnt vmcnt(8)
	s_waitcnt lgkmcnt(0)
	s_barrier
	v_mfma_f32_16x16x32_bf16 v[140:143], v[64:67], v[182:185], v[140:143]
	v_mfma_f32_16x16x32_bf16 v[136:139], v[76:79], v[182:185], v[136:139]
	v_mfma_f32_16x16x32_bf16 v[124:127], v[64:67], v[190:193], v[124:127]
	v_mfma_f32_16x16x32_bf16 v[120:123], v[76:79], v[190:193], v[120:123]
	v_mfma_f32_16x16x32_bf16 v[108:111], v[64:67], v[198:201], v[108:111]
	v_mfma_f32_16x16x32_bf16 v[104:107], v[76:79], v[198:201], v[104:107]
	v_mfma_f32_16x16x32_bf16 v[92:95], v[64:67], v[206:209], v[92:95]
	v_mfma_f32_16x16x32_bf16 v[88:91], v[76:79], v[206:209], v[88:91]
	v_mfma_f32_16x16x32_bf16 v[140:143], v[72:75], v[186:189], v[140:143]
	v_mfma_f32_16x16x32_bf16 v[136:139], v[84:87], v[186:189], v[136:139]
	v_mfma_f32_16x16x32_bf16 v[124:127], v[72:75], v[194:197], v[124:127]
	v_mfma_f32_16x16x32_bf16 v[120:123], v[84:87], v[194:197], v[120:123]
	v_mfma_f32_16x16x32_bf16 v[108:111], v[72:75], v[202:205], v[108:111]
	v_mfma_f32_16x16x32_bf16 v[104:107], v[84:87], v[202:205], v[104:107]
	v_mfma_f32_16x16x32_bf16 v[92:95], v[72:75], v[210:213], v[92:95]
	v_mfma_f32_16x16x32_bf16 v[88:91], v[84:87], v[210:213], v[88:91]
	v_mfma_f32_16x16x32_bf16 v[132:135], v[156:159], v[182:185], v[132:135]
	v_mfma_f32_16x16x32_bf16 v[128:131], v[174:177], v[182:185], v[128:131]
	v_mfma_f32_16x16x32_bf16 v[116:119], v[156:159], v[190:193], v[116:119]
	v_mfma_f32_16x16x32_bf16 v[112:115], v[174:177], v[190:193], v[112:115]
	v_mfma_f32_16x16x32_bf16 v[100:103], v[156:159], v[198:201], v[100:103]
	v_mfma_f32_16x16x32_bf16 v[96:99], v[174:177], v[198:201], v[96:99]
	v_mfma_f32_16x16x32_bf16 v[80:83], v[156:159], v[206:209], v[80:83]
	v_mfma_f32_16x16x32_bf16 v[68:71], v[174:177], v[206:209], v[68:71]
	v_mfma_f32_16x16x32_bf16 v[132:135], v[160:163], v[186:189], v[132:135]
	v_mfma_f32_16x16x32_bf16 v[128:131], v[178:181], v[186:189], v[128:131]
	v_mfma_f32_16x16x32_bf16 v[116:119], v[160:163], v[194:197], v[116:119]
	v_mfma_f32_16x16x32_bf16 v[112:115], v[178:181], v[194:197], v[112:115]
	v_mfma_f32_16x16x32_bf16 v[100:103], v[160:163], v[202:205], v[100:103]
	v_mfma_f32_16x16x32_bf16 v[96:99], v[178:181], v[202:205], v[96:99]
	v_mfma_f32_16x16x32_bf16 v[80:83], v[160:163], v[210:213], v[80:83]
	v_mfma_f32_16x16x32_bf16 v[68:71], v[178:181], v[210:213], v[68:71]
	s_barrier
	s_add_i32 s62, s56, s44
	v_lshl_add_u64 v[214:215], s[38:39], 0, v[144:145]
	s_mov_b32 m0, s62
	ds_read_b128 v[182:185], v171 offset:16384
	ds_read_b128 v[186:189], v171 offset:17408
	ds_read_b128 v[190:193], v171 offset:18432
	ds_read_b128 v[194:197], v171 offset:19456
	ds_read_b128 v[198:201], v171 offset:20480
	ds_read_b128 v[202:205], v171 offset:21504
	ds_read_b128 v[206:209], v171 offset:22528
	ds_read_b128 v[210:213], v171 offset:23552
	global_load_lds_dwordx4 v[214:215], off
	s_add_i32 m0, s62, 0x2000
	s_add_u32 s62, s38, 0x80000
	v_lshl_add_u64 v[216:217], s[38:39], 0, v[146:147]
	s_addc_u32 s63, s39, 0
	s_add_i32 s64, s57, s44
	global_load_lds_dwordx4 v[216:217], off
	v_lshl_add_u64 v[218:219], s[62:63], 0, v[144:145]
	s_mov_b32 m0, s64
	v_lshl_add_u64 v[220:221], s[40:41], 0, v[146:147]
	global_load_lds_dwordx4 v[218:219], off
	v_lshl_add_u64 v[218:219], s[62:63], 0, v[146:147]
	s_add_i32 m0, s64, 0x2000
	s_nop 0
	global_load_lds_dwordx4 v[218:219], off
	v_lshl_add_u64 v[218:219], s[40:41], 0, v[144:145]
	s_mov_b32 m0, s45
	s_nop 0
	global_load_lds_dwordx4 v[218:219], off
	s_mov_b32 m0, s46
	s_nop 0
	global_load_lds_dwordx4 v[220:221], off
	s_waitcnt vmcnt(8)
	s_waitcnt lgkmcnt(0)
	s_barrier
; #define PG8_STAGE(bufoff, gbase, voff) do { _Pragma("unroll") for (int _i = 0; _i < 2; ++_i) \
;         __builtin_amdgcn_global_load_lds((const unsigned*)((const char*)(gbase) + (voff)[_i]), (LAS unsigned*)(lds + (bufoff) + ldsw + _i * 8192), 16, 0, 0); } while (0)
; #define PG8_LDA(dst, b, h) do { _Pragma("unroll") for (int m = 0; m < 4; ++m) _Pragma("unroll") for (int k = 0; k < 2; ++k) dst[m][k] = *(const LAS bf16x8*)(lds + PG8_SA(b, h) + aoff + m * 2048 + k * 1024); } while (0)
; #define PG8_LDB(dst, b, h) do { _Pragma("unroll") for (int n = 0; n < 2; ++n) _Pragma("unroll") for (int k = 0; k < 2; ++k) dst[n][k] = *(const LAS bf16x8*)(lds + PG8_SB(b, h) + boff + n * 2048 + k * 1024); } while (0)
; #define PG8_MMA(ai, bj, At, Bt) do { __builtin_amdgcn_s_setprio(1); _Pragma("unroll") for (int m = 0; m < 4; ++m) _Pragma("unroll") for (int n = 0; n < 2; ++n) _Pragma("unroll") for (int k = 0; k < 2; ++k) \
;         acc[ai][bj][m][n] = __builtin_amdgcn_mfma_f32_16x16x32_bf16(Bt[n][k], At[m][k], acc[ai][bj][m][n], 0, 0, 0); __builtin_amdgcn_s_setprio(0); } while (0)
; #define PG8_WAIT_V(n) asm volatile("s_waitcnt vmcnt(" #n ")" ::: "memory")
; #define PG8_WAIT_L(n) asm volatile("s_waitcnt lgkmcnt(" #n ")" ::: "memory")
; #define PG8_BAR __builtin_amdgcn_s_barrier()
; #define PG8_SCHED __builtin_amdgcn_sched_barrier(0)
; template <class Epi, bool ALIGN_EPI>
; __device__ __forceinline__ void gemm_phase(LAS unsigned char* lds, const Gemm g, const StaticOrder& S, const Epi& E) {
;     ...
;             PG8_WAIT_V(8); PG8_WAIT_L(0); PG8_BAR; PG8_MMA(1, 0, At, B0); PG8_MMA(1, 1, At, B1); PG8_BAR; PG8_SCHED;
;             PG8_LDB(B0, 1, 0); PG8_LDB(B1, 1, 1); PG8_SCHED; PG8_LDA(At, 1, 0); PG8_STAGE(PG8_SA(0, 1), a2 + hstepA, voffA);
;             PG8_WAIT_V(8); PG8_WAIT_L(0); PG8_BAR; PG8_MMA(0, 0, At, B0); PG8_MMA(0, 1, At, B1); PG8_BAR; PG8_SCHED;
	v_mfma_f32_16x16x32_bf16 v[60:63], v[64:67], v[182:185], v[60:63]
	v_mfma_f32_16x16x32_bf16 v[56:59], v[76:79], v[182:185], v[56:59]
	v_mfma_f32_16x16x32_bf16 v[44:47], v[64:67], v[190:193], v[44:47]
	v_mfma_f32_16x16x32_bf16 v[40:43], v[76:79], v[190:193], v[40:43]
	v_mfma_f32_16x16x32_bf16 v[28:31], v[64:67], v[198:201], v[28:31]
	v_mfma_f32_16x16x32_bf16 v[24:27], v[76:79], v[198:201], v[24:27]
	v_mfma_f32_16x16x32_bf16 v[12:15], v[64:67], v[206:209], v[12:15]
	v_mfma_f32_16x16x32_bf16 v[8:11], v[76:79], v[206:209], v[8:11]
	v_mfma_f32_16x16x32_bf16 v[60:63], v[72:75], v[186:189], v[60:63]
	v_mfma_f32_16x16x32_bf16 v[56:59], v[84:87], v[186:189], v[56:59]
	v_mfma_f32_16x16x32_bf16 v[44:47], v[72:75], v[194:197], v[44:47]
	v_mfma_f32_16x16x32_bf16 v[40:43], v[84:87], v[194:197], v[40:43]
	v_mfma_f32_16x16x32_bf16 v[28:31], v[72:75], v[202:205], v[28:31]
	v_mfma_f32_16x16x32_bf16 v[24:27], v[84:87], v[202:205], v[24:27]
	v_mfma_f32_16x16x32_bf16 v[12:15], v[72:75], v[210:213], v[12:15]
	v_mfma_f32_16x16x32_bf16 v[8:11], v[84:87], v[210:213], v[8:11]
	v_mfma_f32_16x16x32_bf16 v[52:55], v[156:159], v[182:185], v[52:55]
	v_mfma_f32_16x16x32_bf16 v[48:51], v[174:177], v[182:185], v[48:51]
	v_mfma_f32_16x16x32_bf16 v[36:39], v[156:159], v[190:193], v[36:39]
	v_mfma_f32_16x16x32_bf16 v[32:35], v[174:177], v[190:193], v[32:35]
	v_mfma_f32_16x16x32_bf16 v[20:23], v[156:159], v[198:201], v[20:23]
	v_mfma_f32_16x16x32_bf16 v[16:19], v[174:177], v[198:201], v[16:19]
	v_mfma_f32_16x16x32_bf16 v[4:7], v[156:159], v[206:209], v[4:7]
	v_mfma_f32_16x16x32_bf16 v[0:3], v[174:177], v[206:209], v[0:3]
	v_mfma_f32_16x16x32_bf16 v[52:55], v[160:163], v[186:189], v[52:55]
	v_mfma_f32_16x16x32_bf16 v[48:51], v[178:181], v[186:189], v[48:51]
	v_mfma_f32_16x16x32_bf16 v[36:39], v[160:163], v[194:197], v[36:39]
	v_mfma_f32_16x16x32_bf16 v[32:35], v[178:181], v[194:197], v[32:35]
	v_mfma_f32_16x16x32_bf16 v[20:23], v[160:163], v[202:205], v[20:23]
	v_mfma_f32_16x16x32_bf16 v[16:19], v[178:181], v[202:205], v[16:19]
	v_mfma_f32_16x16x32_bf16 v[4:7], v[160:163], v[210:213], v[4:7]
	v_mfma_f32_16x16x32_bf16 v[0:3], v[178:181], v[210:213], v[0:3]
	s_barrier
	s_add_i32 s62, 0, 0x18000
	s_add_i32 s63, 0, 0x1c000
	v_add_u32_e32 v84, s62, v165
	v_add_u32_e32 v173, s63, v165
	ds_read_b128 v[64:67], v84
	ds_read_b128 v[72:75], v84 offset:1024
	ds_read_b128 v[76:79], v84 offset:2048
	ds_read_b128 v[84:87], v84 offset:3072
	ds_read_b128 v[156:159], v173
	ds_read_b128 v[160:163], v173 offset:1024
	ds_read_b128 v[174:177], v173 offset:2048
	ds_read_b128 v[178:181], v173 offset:3072
	s_add_u32 s40, s40, 0x80000
	s_addc_u32 s41, s41, 0
	s_mov_b32 m0, s47
	v_lshl_add_u64 v[222:223], s[40:41], 0, v[144:145]
	ds_read_b128 v[182:185], v171 offset:32768
	ds_read_b128 v[186:189], v171 offset:33792
	ds_read_b128 v[190:193], v171 offset:34816
	ds_read_b128 v[194:197], v171 offset:35840
	ds_read_b128 v[198:201], v171 offset:36864
	ds_read_b128 v[202:205], v171 offset:37888
	ds_read_b128 v[206:209], v171 offset:38912
	ds_read_b128 v[210:213], v171 offset:39936
	global_load_lds_dwordx4 v[222:223], off
	v_lshl_add_u64 v[222:223], s[40:41], 0, v[146:147]
	s_mov_b32 m0, s48
	s_nop 0
	global_load_lds_dwordx4 v[222:223], off
	s_waitcnt vmcnt(8)
	s_waitcnt lgkmcnt(0)
	s_barrier
	v_mfma_f32_16x16x32_bf16 v[140:143], v[64:67], v[182:185], v[140:143]
	v_mfma_f32_16x16x32_bf16 v[136:139], v[76:79], v[182:185], v[136:139]
	v_mfma_f32_16x16x32_bf16 v[124:127], v[64:67], v[190:193], v[124:127]
	v_mfma_f32_16x16x32_bf16 v[120:123], v[76:79], v[190:193], v[120:123]
	v_mfma_f32_16x16x32_bf16 v[108:111], v[64:67], v[198:201], v[108:111]
	v_mfma_f32_16x16x32_bf16 v[104:107], v[76:79], v[198:201], v[104:107]
	v_mfma_f32_16x16x32_bf16 v[92:95], v[64:67], v[206:209], v[92:95]
	v_mfma_f32_16x16x32_bf16 v[88:91], v[76:79], v[206:209], v[88:91]
	v_mfma_f32_16x16x32_bf16 v[140:143], v[72:75], v[186:189], v[140:143]
	v_mfma_f32_16x16x32_bf16 v[136:139], v[84:87], v[186:189], v[136:139]
	v_mfma_f32_16x16x32_bf16 v[124:127], v[72:75], v[194:197], v[124:127]
	v_mfma_f32_16x16x32_bf16 v[120:123], v[84:87], v[194:197], v[120:123]
	v_mfma_f32_16x16x32_bf16 v[108:111], v[72:75], v[202:205], v[108:111]
	v_mfma_f32_16x16x32_bf16 v[104:107], v[84:87], v[202:205], v[104:107]
	v_mfma_f32_16x16x32_bf16 v[92:95], v[72:75], v[210:213], v[92:95]
	v_mfma_f32_16x16x32_bf16 v[88:91], v[84:87], v[210:213], v[88:91]
	v_mfma_f32_16x16x32_bf16 v[132:135], v[156:159], v[182:185], v[132:135]
	v_mfma_f32_16x16x32_bf16 v[128:131], v[174:177], v[182:185], v[128:131]
	v_mfma_f32_16x16x32_bf16 v[116:119], v[156:159], v[190:193], v[116:119]
	v_mfma_f32_16x16x32_bf16 v[112:115], v[174:177], v[190:193], v[112:115]
	v_mfma_f32_16x16x32_bf16 v[100:103], v[156:159], v[198:201], v[100:103]
	v_mfma_f32_16x16x32_bf16 v[96:99], v[174:177], v[198:201], v[96:99]
	v_mfma_f32_16x16x32_bf16 v[80:83], v[156:159], v[206:209], v[80:83]
	v_mfma_f32_16x16x32_bf16 v[68:71], v[174:177], v[206:209], v[68:71]
	v_mfma_f32_16x16x32_bf16 v[132:135], v[160:163], v[186:189], v[132:135]
	v_mfma_f32_16x16x32_bf16 v[128:131], v[178:181], v[186:189], v[128:131]
	v_mfma_f32_16x16x32_bf16 v[116:119], v[160:163], v[194:197], v[116:119]
	v_mfma_f32_16x16x32_bf16 v[112:115], v[178:181], v[194:197], v[112:115]
	v_mfma_f32_16x16x32_bf16 v[100:103], v[160:163], v[202:205], v[100:103]
	v_mfma_f32_16x16x32_bf16 v[96:99], v[178:181], v[202:205], v[96:99]
	v_mfma_f32_16x16x32_bf16 v[80:83], v[160:163], v[210:213], v[80:83]
	v_mfma_f32_16x16x32_bf16 v[68:71], v[178:181], v[210:213], v[68:71]
	s_barrier
; #define PG8_STAGE(bufoff, gbase, voff) do { _Pragma("unroll") for (int _i = 0; _i < 2; ++_i) \
;         __builtin_amdgcn_global_load_lds((const unsigned*)((const char*)(gbase) + (voff)[_i]), (LAS unsigned*)(lds + (bufoff) + ldsw + _i * 8192), 16, 0, 0); } while (0)
; #define PG8_LDA(dst, b, h) do { _Pragma("unroll") for (int m = 0; m < 4; ++m) _Pragma("unroll") for (int k = 0; k < 2; ++k) dst[m][k] = *(const LAS bf16x8*)(lds + PG8_SA(b, h) + aoff + m * 2048 + k * 1024); } while (0)
; #define PG8_MMA(ai, bj, At, Bt) do { __builtin_amdgcn_s_setprio(1); _Pragma("unroll") for (int m = 0; m < 4; ++m) _Pragma("unroll") for (int n = 0; n < 2; ++n) _Pragma("unroll") for (int k = 0; k < 2; ++k) \
;         acc[ai][bj][m][n] = __builtin_amdgcn_mfma_f32_16x16x32_bf16(Bt[n][k], At[m][k], acc[ai][bj][m][n], 0, 0, 0); __builtin_amdgcn_s_setprio(0); } while (0)
; #define PG8_WAIT_V(n) asm volatile("s_waitcnt vmcnt(" #n ")" ::: "memory")
; #define PG8_WAIT_L(n) asm volatile("s_waitcnt lgkmcnt(" #n ")" ::: "memory")
; #define PG8_BAR __builtin_amdgcn_s_barrier()
; #define PG8_SCHED __builtin_amdgcn_sched_barrier(0)
; template <class Epi, bool ALIGN_EPI>
; __device__ __forceinline__ void gemm_phase(LAS unsigned char* lds, const Gemm g, const StaticOrder& S, const Epi& E) {
;     ...
;             PG8_LDA(At, 1, 1); PG8_STAGE(PG8_SB(1, 0), b3, voffB); PG8_STAGE(PG8_SB(1, 1), b3 + hstepB, voffB); PG8_STAGE(PG8_SA(1, 0), a3, voffA);
;             PG8_WAIT_V(8); PG8_WAIT_L(0); PG8_BAR; PG8_MMA(1, 0, At, B0); PG8_MMA(1, 1, At, B1); PG8_BAR; PG8_SCHED;
;         }
	s_add_i32 s40, s62, s44
	v_lshl_add_u64 v[214:215], v[214:215], 0, s[18:19]
	s_mov_b32 m0, s40
	ds_read_b128 v[182:185], v171 offset:49152
	ds_read_b128 v[186:189], v171 offset:50176
	ds_read_b128 v[190:193], v171 offset:51200
	ds_read_b128 v[194:197], v171 offset:52224
	ds_read_b128 v[198:201], v171 offset:53248
	ds_read_b128 v[202:205], v171 offset:54272
	ds_read_b128 v[206:209], v171 offset:55296
	ds_read_b128 v[210:213], v171 offset:56320
	global_load_lds_dwordx4 v[214:215], off
	s_add_i32 m0, s40, 0x2000
	s_add_u32 s38, s38, 0x80080
	v_lshl_add_u64 v[214:215], v[216:217], 0, s[18:19]
	s_addc_u32 s39, s39, 0
	s_add_i32 s40, s63, s44
	global_load_lds_dwordx4 v[214:215], off
	v_lshl_add_u64 v[214:215], s[38:39], 0, v[144:145]
	s_mov_b32 m0, s40
	s_nop 0
	global_load_lds_dwordx4 v[214:215], off
	v_lshl_add_u64 v[214:215], s[38:39], 0, v[146:147]
	s_add_i32 m0, s40, 0x2000
	s_nop 0
	global_load_lds_dwordx4 v[214:215], off
	v_lshl_add_u64 v[214:215], v[218:219], 0, s[18:19]
	s_mov_b32 m0, s50
	s_nop 0
	global_load_lds_dwordx4 v[214:215], off
	v_lshl_add_u64 v[214:215], v[220:221], 0, s[18:19]
	s_mov_b32 m0, s51
	s_nop 0
	global_load_lds_dwordx4 v[214:215], off
	s_waitcnt vmcnt(8)
	s_waitcnt lgkmcnt(0)
	s_barrier
	v_mfma_f32_16x16x32_bf16 v[60:63], v[64:67], v[182:185], v[60:63]
	v_mfma_f32_16x16x32_bf16 v[56:59], v[76:79], v[182:185], v[56:59]
	v_mfma_f32_16x16x32_bf16 v[44:47], v[64:67], v[190:193], v[44:47]
	v_mfma_f32_16x16x32_bf16 v[40:43], v[76:79], v[190:193], v[40:43]
	v_mfma_f32_16x16x32_bf16 v[28:31], v[64:67], v[198:201], v[28:31]
	v_mfma_f32_16x16x32_bf16 v[24:27], v[76:79], v[198:201], v[24:27]
	v_mfma_f32_16x16x32_bf16 v[12:15], v[64:67], v[206:209], v[12:15]
	v_mfma_f32_16x16x32_bf16 v[8:11], v[76:79], v[206:209], v[8:11]
	v_mfma_f32_16x16x32_bf16 v[60:63], v[72:75], v[186:189], v[60:63]
	v_mfma_f32_16x16x32_bf16 v[56:59], v[84:87], v[186:189], v[56:59]
	v_mfma_f32_16x16x32_bf16 v[44:47], v[72:75], v[194:197], v[44:47]
	v_mfma_f32_16x16x32_bf16 v[40:43], v[84:87], v[194:197], v[40:43]
	v_mfma_f32_16x16x32_bf16 v[28:31], v[72:75], v[202:205], v[28:31]
	v_mfma_f32_16x16x32_bf16 v[24:27], v[84:87], v[202:205], v[24:27]
	v_mfma_f32_16x16x32_bf16 v[12:15], v[72:75], v[210:213], v[12:15]
	v_mfma_f32_16x16x32_bf16 v[8:11], v[84:87], v[210:213], v[8:11]
	v_mfma_f32_16x16x32_bf16 v[52:55], v[156:159], v[182:185], v[52:55]
	v_mfma_f32_16x16x32_bf16 v[48:51], v[174:177], v[182:185], v[48:51]
	v_mfma_f32_16x16x32_bf16 v[36:39], v[156:159], v[190:193], v[36:39]
	v_mfma_f32_16x16x32_bf16 v[32:35], v[174:177], v[190:193], v[32:35]
	v_mfma_f32_16x16x32_bf16 v[20:23], v[156:159], v[198:201], v[20:23]
	v_mfma_f32_16x16x32_bf16 v[16:19], v[174:177], v[198:201], v[16:19]
	v_mfma_f32_16x16x32_bf16 v[4:7], v[156:159], v[206:209], v[4:7]
	v_mfma_f32_16x16x32_bf16 v[0:3], v[174:177], v[206:209], v[0:3]
	v_mfma_f32_16x16x32_bf16 v[52:55], v[160:163], v[186:189], v[52:55]
	v_mfma_f32_16x16x32_bf16 v[48:51], v[178:181], v[186:189], v[48:51]
	v_mfma_f32_16x16x32_bf16 v[36:39], v[160:163], v[194:197], v[36:39]
	v_mfma_f32_16x16x32_bf16 v[32:35], v[178:181], v[194:197], v[32:35]
	v_mfma_f32_16x16x32_bf16 v[20:23], v[160:163], v[202:205], v[20:23]
	v_mfma_f32_16x16x32_bf16 v[16:19], v[178:181], v[202:205], v[16:19]
	v_mfma_f32_16x16x32_bf16 v[4:7], v[160:163], v[210:213], v[4:7]
	v_mfma_f32_16x16x32_bf16 v[0:3], v[178:181], v[210:213], v[0:3]
	s_barrier
	s_add_i32 s61, s61, 2
	s_add_u32 s59, s59, 0x100
	s_addc_u32 s60, s60, 0
	s_add_u32 s36, s36, 0x100
	s_addc_u32 s37, s37, 0
	s_cmp_gt_u32 s61, 29
	s_cbranch_scc0 .LBB0_1082
	s_and_b64 vcc, exec, s[20:21]
	s_cbranch_vccz .LBB0_1085
	s_barrier

; #define INP(k) ((const float*)PTR(k))
; #define WSP(off) (PTR(29) + (off))
;     constexpr int I_G = (DM / 128) * (DFF / 32), I_D = (DFF / 128) * (DM / 32);
;     const int lo = (parts & 1) ? 0 : 2 * I_G, hi = (parts & 2) ? 2 * I_G + I_D : 2 * I_G;
;     for (int it = lo + gw; it < hi; it += NGW) {
;         int r = it;
;         if (r < I_G) { transpose_item(wg, DM, DFF, WAgu, 1, r, lane); continue; } r -= I_G;
;         if (r < I_G) { transpose_item(wu, DM, DFF, WAgu, 2, r, lane); continue; } r -= I_G;
;         transpose_item(wd, DFF, DM, WAd, 0, r, lane);
;     }
; template <int K>
; __device__ __forceinline__ void run_phase(LAS unsigned char* lds, volatile LAS unsigned* ptab) {
;     ...
;     if constexpr (K == 13) {
;         const int nwg1 = (MROWS / 256) * (2 * DFF / 256), nidle = ((nwg1 + G - 1) / G) * G - nwg1;
;         convert_ffn(INP(24), INP(25), INP(26), (bf16_t*)WSP(WS_WAGU2), (bf16_t*)WSP(WS_WAD2), gw, NGW, lane, nidle >= 64 ? 1 : 3);
;     }
.LBB0_1221:
	s_or_b64 exec, exec, s[0:1]
	s_setprio 0
	s_waitcnt lgkmcnt(0)
	v_mov_b32_e32 v0, v166
	s_barrier
	v_readlane_b32 s12, v252, 7
	v_readfirstlane_b32 s0, v0
	s_ashr_i32 s0, s0, 6
	s_add_i32 s2, s0, s95
	s_add_i32 s0, 0, 0x230c4
	v_mov_b32_e32 v1, s0
	ds_read_b32 v1, v1
	s_add_i32 s0, 0, 0x230c0
	v_mov_b32_e32 v2, s0
	s_add_i32 s0, 0, 0x230cc
	v_mov_b32_e32 v3, s0
	s_add_i32 s0, 0, 0x230c8
	v_mov_b32_e32 v4, s0
	s_add_i32 s0, 0, 0x230d4
	ds_read_b32 v2, v2
	v_mov_b32_e32 v5, s0
	s_add_i32 s0, 0, 0x230d0
	ds_read_b32 v3, v3
	ds_read_b32 v4, v4
	s_waitcnt lgkmcnt(3)
	v_readfirstlane_b32 s5, v1
	v_mov_b32_e32 v1, s0
	ds_read_b32 v5, v5
	ds_read_b32 v1, v1
	s_add_i32 s0, 0, 0x230ec
	s_waitcnt lgkmcnt(4)
	v_readfirstlane_b32 s4, v2
	v_mov_b32_e32 v2, s0
	s_add_i32 s0, 0, 0x230e8
	s_waitcnt lgkmcnt(2)
	v_readfirstlane_b32 s6, v4
	v_mov_b32_e32 v4, s0
	v_readfirstlane_b32 s7, v3
	s_waitcnt lgkmcnt(1)
	v_readfirstlane_b32 s9, v5
	ds_read_b32 v3, v2
	ds_read_b32 v5, v4
	ds_read_b32 v2, v2
	s_waitcnt lgkmcnt(3)
	v_readfirstlane_b32 s8, v1
	ds_read_b32 v1, v4
	s_mov_b32 s1, 0
	s_waitcnt lgkmcnt(3)
	v_readfirstlane_b32 s11, v3
	s_waitcnt lgkmcnt(2)
	v_readfirstlane_b32 s10, v5
	s_waitcnt lgkmcnt(1)
	v_readfirstlane_b32 s0, v2
	s_cmp_ge_i32 s2, s12
	s_waitcnt lgkmcnt(0)
	v_readfirstlane_b32 s12, v1
	s_cbranch_scc1 .LBB0_1232
	s_add_u32 s10, s10, 0x100000
	s_addc_u32 s11, s11, 0
	v_and_b32_e32 v64, 56, v0
	v_lshlrev_b32_e32 v0, 2, v0
	s_add_u32 s12, s12, 0x2d00000
	v_and_b32_e32 v66, 28, v0
	s_addc_u32 s13, s0, 0
	v_mov_b32_e32 v69, 0
	s_lshl_b32 s33, s2, 5
	s_lshl_b32 s73, s72, 5
	s_lshl_b32 s80, s2, 6
	s_lshl_b32 s81, s72, 6
	s_lshl_b32 s82, s2, 1
	s_lshl_b32 s83, s72, 1
	s_mov_b64 s[14:15], 0x80000
	s_mov_b64 s[16:17], 0xa000
	s_mov_b64 s[18:19], 0x8a000
	s_mov_b64 s[20:21], 0xc000
	s_mov_b64 s[22:23], 0x8c000
	s_mov_b64 s[24:25], 0xe000
	s_mov_b64 s[26:27], 0x8e000
	s_mov_b64 s[28:29], 0x160000
	s_mov_b64 s[30:31], 0x5800
	s_mov_b64 s[34:35], 0x165800
	s_mov_b64 s[36:37], 0xb000
	s_mov_b64 s[38:39], 0x16b000
	s_mov_b64 s[40:41], 0x10800
	s_mov_b64 s[42:43], 0x170800
	s_mov_b64 s[44:45], 0x16000
	s_mov_b64 s[46:47], 0x176000
	s_mov_b64 s[48:49], 0x1b800
	s_mov_b64 s[50:51], 0x17b800
	s_mov_b64 s[52:53], 0x21000
	s_mov_b64 s[54:55], 0x181000
	s_mov_b64 s[56:57], 0x26800
	s_mov_b64 s[58:59], 0x186800
	s_movk_i32 s84, 0x5800
	s_mov_b32 s85, 0x7060302
	v_lshlrev_b32_e32 v70, 2, v66
	s_branch .LBB0_1224

; #define PG8_BAR __builtin_amdgcn_s_barrier()
; template <class Epi, bool ALIGN_EPI>
; __device__ __forceinline__ void gemm_phase(LAS unsigned char* lds, const Gemm g, const StaticOrder& S, const Epi& E) {
;     ...
;     const int tid = tid_, wid = __builtin_amdgcn_readfirstlane(tid >> 6), lane = tid & 63, wr = wid >> 2, wc = wid & 3, fr = lane & 15, fq = lane >> 4;
;     const int K = g.K, nt = K / BK, lda = g.lda;
;     unsigned voffA[2], voffB[2];
; #pragma unroll
;     for (int i = 0; i < 2; ++i) { int R, C; stage_rc(tid * 16 + i * 8192, R, C); const int Rb = Epi::PERM ? ((R & ~31) + perm32(R & 31)) : R;
;         voffA[i] = (unsigned)(R * lda + C) * 2u; voffB[i] = (unsigned)(Rb * K + C) * 2u; }
;     const size_t kstep = (size_t)(BK * 2);
;     const size_t hstepA = (size_t)HALF * lda * 2, hstepB = (size_t)HALF * K * 2;
;     const size_t tstepA = 2 * hstepA, tstepB = 2 * hstepB;
;     const unsigned ldsw = (unsigned)wid * 1024u;
;     const int aoff = lds_byte(wr * 64 + fr, fq * 8), boff = lds_byte(wc * 32 + fr, fq * 8);
;     ...
;     Unit cur, nxt; int ui = 0;
;     if (!S.next(0, cur)) return;
;     f32x4 acc[2][2][4][2];
; #pragma unroll
;     for (int a = 0; a < 2; ++a)
; #pragma unroll
;         for (int b = 0; b < 2; ++b)
; #pragma unroll
;             for (int m = 0; m < 4; ++m)
; #pragma unroll
;                 for (int n = 0; n < 2; ++n) acc[a][b][m][n] = (f32x4){0.f, 0.f, 0.f, 0.f};
;     bf16x8 At[4][2], B0[2][2], B1[2][2];
;     const char* cA = (const char*)g.A + (size_t)cur.pm * tstepA; const char* cB = (const char*)g.Bt + (size_t)cur.pn * tstepB;
;     PG8_STAGE(PG8_SB(0, 0), cB, voffB); PG8_STAGE(PG8_SB(0, 1), cB + hstepB, voffB); PG8_STAGE(PG8_SA(0, 0), cA, voffA); PG8_STAGE(PG8_SA(0, 1), cA + hstepA, voffA);
;     if (wr == 1) PG8_BAR;
;     PG8_WAIT_V(2); PG8_BAR;
;     PG8_STAGE(PG8_SB(1, 0), cB + kstep, voffB); PG8_STAGE(PG8_SA(1, 0), cA + kstep, voffA); PG8_STAGE(PG8_SB(1, 1), cB + hstepB + kstep, voffB);
; template <int K>
; __device__ __forceinline__ void run_phase(LAS unsigned char* lds, volatile LAS unsigned* ptab) {
;     ...
;         pg8::Gemm g{(const bf16_t*)WSP(WS_XN2), (const bf16_t*)WSP(WS_WAGU2), MROWS, 2 * DFF, DM, DM}; pg8::StaticOrder S; S.init(MROWS, 2 * DFF, G, bx);
;         pg8::EpiSwiglu E{(bf16_t*)WSP(WS_H2), DFF, 0, (const float*)WSP(WS_SS2)};
;         pg8::gemm_phase<pg8::EpiSwiglu, true>(lds, g, S, E);
.Lprio_skip_5:
	s_add_i32 s0, 0, 0x230ec
	s_waitcnt lgkmcnt(0)
	v_mov_b32_e32 v0, s0
	s_add_i32 s0, 0, 0x230e8
	v_mov_b32_e32 v152, v166
	v_mov_b32_e32 v2, s0
	s_barrier
	ds_read_b32 v1, v0
	ds_read_b32 v3, v2
	ds_read_b32 v4, v0
	v_readlane_b32 s12, v252, 8
	v_mov_b32_e32 v8, v166
	v_readlane_b32 s13, v252, 9
	s_waitcnt lgkmcnt(2)
	v_readfirstlane_b32 s0, v1
	s_waitcnt lgkmcnt(1)
	v_readfirstlane_b32 s5, v3
	s_waitcnt lgkmcnt(0)
	v_readfirstlane_b32 s4, v4
	ds_read_b32 v1, v2
	ds_read_b32 v3, v0
	ds_read_b32 v4, v2
	ds_read_b32 v0, v0
	ds_read_b32 v2, v2
	v_readfirstlane_b32 s2, v152
	s_waitcnt lgkmcnt(4)
	v_readfirstlane_b32 s6, v1
	s_waitcnt lgkmcnt(3)
	v_readfirstlane_b32 s9, v3
	s_waitcnt lgkmcnt(2)
	v_readfirstlane_b32 s8, v4
	s_waitcnt lgkmcnt(1)
	v_readfirstlane_b32 s11, v0
	s_waitcnt lgkmcnt(0)
	v_readfirstlane_b32 s10, v2
	s_andn2_b64 vcc, exec, s[12:13]
	v_readfirstlane_b32 s1, v8
	s_cbranch_vccnz .LBB0_1300
	v_lshlrev_b32_e32 v0, 4, v8
	v_add_u32_e32 v1, 0x2000, v0
	v_ashrrev_i32_e32 v2, 31, v1
	v_lshrrev_b32_e32 v2, 22, v2
	v_add_u32_e32 v2, v1, v2
	v_ashrrev_i32_e32 v9, 10, v2
	v_mul_i32_i24_e32 v2, 0x400, v9
	v_sub_u32_e32 v1, v1, v2
	v_lshrrev_b32_e32 v2, 4, v1
	v_bitop3_b32 v1, v2, v1, 32 bitop3:0x6c
	v_ashrrev_i32_e32 v2, 31, v1
	v_lshrrev_b32_e32 v2, 26, v2
	v_add_u32_e32 v2, v1, v2
	v_lshlrev_b32_e32 v3, 3, v9
	v_ashrrev_i32_e32 v10, 6, v2
	v_and_b32_e32 v3, -16, v3
	s_add_u32 s30, s5, 0x8200000
	v_add_u32_e32 v3, v10, v3
	s_addc_u32 s31, s0, 0
	v_and_b32_e32 v4, 3, v10
	s_mov_b32 s0, 0xfffe0
	v_lshrrev_b32_e32 v5, 2, v3
	v_lshlrev_b32_e32 v6, 1, v3
	v_and_b32_e32 v2, 0xc0, v2
	v_and_or_b32 v4, v3, s0, v4
	v_and_b32_e32 v5, 4, v5
	v_and_b32_e32 v6, 24, v6
	v_sub_u32_e32 v1, v1, v2
	v_mov_b32_e32 v2, 1
	v_or3_b32 v4, v4, v5, v6
	v_lshlrev_b32_e32 v5, 5, v9
	v_ashrrev_i16_sdwa v1, v2, sext(v1) dst_sel:DWORD dst_unused:UNUSED_PAD src0_sel:DWORD src1_sel:BYTE_0
	v_and_b32_e32 v5, 32, v5
	v_bfe_i32 v11, v1, 0, 16
	v_add_lshl_u32 v1, v5, v11, 1
	v_lshl_add_u32 v128, v4, 12, v1
	v_lshl_add_u32 v130, v3, 12, v1
	v_bfe_i32 v1, v8, 27, 1
	v_lshrrev_b32_e32 v1, 22, v1
	v_add_u32_e32 v1, v0, v1
	v_and_b32_e32 v1, 0xfffffc00, v1
	v_sub_u32_e32 v0, v0, v1
	v_lshrrev_b32_e32 v1, 4, v0
	v_ashrrev_i32_e32 v3, 31, v8
	v_bitop3_b32 v0, v1, v0, 32 bitop3:0x6c
	v_lshrrev_b32_e32 v3, 26, v3
	v_ashrrev_i32_e32 v1, 31, v0
	v_add_u32_e32 v3, v8, v3
	v_lshrrev_b32_e32 v1, 26, v1
	v_ashrrev_i32_e32 v13, 6, v3
	v_add_u32_e32 v1, v0, v1
	v_lshlrev_b32_e32 v3, 3, v13
	s_add_u32 s33, s6, 0x100000
	v_ashrrev_i32_e32 v12, 6, v1
	v_and_b32_e32 v3, -16, v3
	s_addc_u32 s34, s4, 0
	v_add_u32_e32 v3, v12, v3
	v_and_b32_e32 v4, 3, v12
	s_ashr_i32 s36, s3, 31
	v_and_or_b32 v4, v3, s0, v4
	s_lshr_b32 s0, s36, 29
	s_add_i32 s0, s3, s0
	s_ashr_i32 s12, s1, 6
	s_ashr_i32 s4, s0, 3
	s_and_b32 s0, s0, -8
	s_ashr_i32 s14, s1, 8
	s_lshl_b32 s35, s12, 10
	s_sub_i32 s0, s3, s0
	s_cmp_lt_i32 s0, 0
	s_movk_i32 s37, 0x211
	s_cselect_b32 s5, s37, 0x210
	s_mul_i32 s0, s5, s0
	s_add_i32 s0, s0, s4
	s_mul_hi_i32 s4, s0, 0x2e8ba2e9
	s_lshr_b32 s5, s4, 31
	s_ashr_i32 s4, s4, 6
	s_add_i32 s4, s4, s5
	s_lshl_b32 s5, s4, 3
	s_mulk_i32 s4, 0x160
	s_sub_i32 s4, s0, s4
	s_sext_i32_i16 s0, s4
	s_bfe_u32 s0, s0, 0x3001c
	s_add_i32 s6, s4, s0
	s_sext_i32_i16 s0, s6
	s_and_b32 s6, s6, 0xfff8
	s_sub_i32 s4, s4, s6
	s_sext_i32_i16 s4, s4
	v_lshrrev_b32_e32 v5, 2, v3
	v_lshlrev_b32_e32 v6, 1, v3
	v_and_b32_e32 v1, 0xc0, v1
	s_lshr_b32 s0, s0, 3
	s_add_i32 s4, s5, s4
	v_and_b32_e32 v5, 4, v5
	v_and_b32_e32 v6, 24, v6
	v_sub_u32_e32 v0, v0, v1
	s_ashr_i32 s5, s4, 31
	s_bfe_i64 s[16:17], s[0:1], 0x100000
	v_or3_b32 v4, v4, v5, v6
	v_lshlrev_b32_e32 v5, 5, v13
	v_ashrrev_i16_sdwa v0, v2, sext(v0) dst_sel:DWORD dst_unused:UNUSED_PAD src0_sel:DWORD src1_sel:BYTE_0
	s_lshl_b64 s[6:7], s[4:5], 20
	s_lshl_b64 s[16:17], s[16:17], 20
	v_and_b32_e32 v5, 32, v5
	v_bfe_i32 v14, v0, 0, 16
	s_add_u32 s24, s33, s16
	v_add_lshl_u32 v0, v5, v14, 1
	s_addc_u32 s25, s34, s17
	s_add_i32 s38, s35, 0
	v_lshl_add_u32 v132, v4, 12, v0
	s_add_i32 m0, s38, 0x10000
	v_lshl_add_u32 v134, v3, 12, v0
	global_load_lds_dwordx4 v132, s[24:25]
	s_add_i32 m0, s38, 0x12000
	s_add_u32 s16, s24, 0x80000
	global_load_lds_dwordx4 v128, s[24:25]
	s_addc_u32 s17, s25, 0
	s_add_i32 m0, s38, 0x14000
	v_mov_b32_e32 v133, 0
	global_load_lds_dwordx4 v132, s[16:17]
	s_add_i32 m0, s38, 0x16000
	s_add_u32 s26, s30, s6
	s_addc_u32 s27, s31, s7
	s_add_i32 s39, s38, 0x2000
	global_load_lds_dwordx4 v128, s[16:17]
	s_mov_b32 m0, s38
	s_add_u32 s6, s26, 0x80000
	global_load_lds_dwordx4 v134, s[26:27]
	s_mov_b32 m0, s39
	s_addc_u32 s7, s27, 0
	s_add_i32 s40, s38, 0x4000
	global_load_lds_dwordx4 v130, s[26:27]
	s_mov_b32 m0, s40
	s_add_i32 s41, s38, 0x6000
	global_load_lds_dwordx4 v134, s[6:7]
	s_mov_b32 m0, s41
	v_mov_b32_e32 v129, v133
	global_load_lds_dwordx4 v130, s[6:7]
	v_mov_b32_e32 v135, v133
	v_mov_b32_e32 v131, v133
	s_cmp_eq_u32 s14, 1
	v_lshl_add_u64 v[6:7], s[24:25], 0, v[132:133]
	v_lshl_add_u64 v[4:5], s[24:25], 0, v[128:129]
	v_lshl_add_u64 v[0:1], s[26:27], 0, v[134:135]
	s_cselect_b64 s[6:7], -1, 0
	s_cmp_lg_u32 s14, 1
	v_lshl_add_u64 v[2:3], s[26:27], 0, v[130:131]
	s_cbranch_scc1 .LBB0_1287
	s_barrier

; #define PG8_STAGE(bufoff, gbase, voff) do { _Pragma("unroll") for (int _i = 0; _i < 2; ++_i) \
;         __builtin_amdgcn_global_load_lds((const unsigned*)((const char*)(gbase) + (voff)[_i]), (LAS unsigned*)(lds + (bufoff) + ldsw + _i * 8192), 16, 0, 0); } while (0)
; #define PG8_LDA(dst, b, h) do { _Pragma("unroll") for (int m = 0; m < 4; ++m) _Pragma("unroll") for (int k = 0; k < 2; ++k) dst[m][k] = *(const LAS bf16x8*)(lds + PG8_SA(b, h) + aoff + m * 2048 + k * 1024); } while (0)
; #define PG8_LDB(dst, b, h) do { _Pragma("unroll") for (int n = 0; n < 2; ++n) _Pragma("unroll") for (int k = 0; k < 2; ++k) dst[n][k] = *(const LAS bf16x8*)(lds + PG8_SB(b, h) + boff + n * 2048 + k * 1024); } while (0)
; #define PG8_MMA(ai, bj, At, Bt) do { __builtin_amdgcn_s_setprio(1); _Pragma("unroll") for (int m = 0; m < 4; ++m) _Pragma("unroll") for (int n = 0; n < 2; ++n) _Pragma("unroll") for (int k = 0; k < 2; ++k) \
;         acc[ai][bj][m][n] = __builtin_amdgcn_mfma_f32_16x16x32_bf16(Bt[n][k], At[m][k], acc[ai][bj][m][n], 0, 0, 0); __builtin_amdgcn_s_setprio(0); } while (0)
; #define PG8_WAIT_V(n) asm volatile("s_waitcnt vmcnt(" #n ")" ::: "memory")
; #define PG8_WAIT_L(n) asm volatile("s_waitcnt lgkmcnt(" #n ")" ::: "memory")
; #define PG8_BAR __builtin_amdgcn_s_barrier()
; #define PG8_SCHED __builtin_amdgcn_sched_barrier(0)
; template <class Epi, bool ALIGN_EPI>
; __device__ __forceinline__ void gemm_phase(LAS unsigned char* lds, const Gemm g, const StaticOrder& S, const Epi& E) {
;     ...
;             const bool last = (t == nt - 2);
;             const char* a1 = cA + (size_t)(t + 1) * kstep;
;             const char* a2 = last ? nA : cA + (size_t)(t + 2) * kstep; const char* b2 = last ? nB : cB + (size_t)(t + 2) * kstep;
;             const char* a3 = a2 + kstep; const char* b3 = b2 + kstep;
;             PG8_LDB(B0, 0, 0); PG8_LDB(B1, 0, 1); PG8_SCHED; PG8_LDA(At, 0, 0); PG8_STAGE(PG8_SA(1, 1), a1 + hstepA, voffA);
;             PG8_WAIT_V(8); PG8_WAIT_L(0); PG8_BAR; PG8_MMA(0, 0, At, B0); PG8_MMA(0, 1, At, B1); PG8_BAR; PG8_SCHED;
;             PG8_LDA(At, 0, 1); PG8_STAGE(PG8_SB(0, 0), b2, voffB); PG8_STAGE(PG8_SB(0, 1), b2 + hstepB, voffB); PG8_STAGE(PG8_SA(0, 0), a2, voffA);
;             PG8_WAIT_V(8); PG8_WAIT_L(0); PG8_BAR; PG8_MMA(1, 0, At, B0); PG8_MMA(1, 1, At, B1); PG8_BAR; PG8_SCHED;
.LBB0_1293:
	ds_read_b128 v[144:147], v156
	ds_read_b128 v[148:151], v156 offset:1024
	ds_read_b128 v[160:163], v156 offset:2048
	ds_read_b128 v[168:171], v156 offset:3072
	ds_read_b128 v[172:175], v157
	ds_read_b128 v[176:179], v157 offset:1024
	ds_read_b128 v[180:183], v157 offset:2048
	ds_read_b128 v[184:187], v157 offset:3072
	s_add_u32 s26, s24, 0xfff80080
	s_addc_u32 s27, s25, -1
	s_cmp_eq_u32 s56, 28
	s_cselect_b32 s29, s19, s27
	s_cselect_b32 s28, s52, s26
	s_cselect_b32 s27, s17, s55
	s_cselect_b32 s26, s53, s54
	v_lshl_add_u64 v[164:165], s[24:25], 0, v[138:139]
	s_add_i32 m0, s38, 0xc000
	ds_read_b128 v[188:191], v158
	ds_read_b128 v[192:195], v158 offset:1024
	ds_read_b128 v[196:199], v158 offset:2048
	ds_read_b128 v[200:203], v158 offset:3072
	ds_read_b128 v[204:207], v158 offset:4096
	ds_read_b128 v[208:211], v158 offset:5120
	ds_read_b128 v[212:215], v158 offset:6144
	ds_read_b128 v[216:219], v158 offset:7168
	global_load_lds_dwordx4 v[164:165], off
	v_lshl_add_u64 v[164:165], s[24:25], 0, v[136:137]
	s_add_i32 m0, s38, 0xe000
	s_nop 0
	global_load_lds_dwordx4 v[164:165], off
	s_waitcnt vmcnt(8)
	s_waitcnt lgkmcnt(0)
	s_barrier
	v_mfma_f32_16x16x32_bf16 v[124:127], v[144:147], v[188:191], v[124:127]
	v_mfma_f32_16x16x32_bf16 v[120:123], v[160:163], v[188:191], v[120:123]
	v_mfma_f32_16x16x32_bf16 v[108:111], v[144:147], v[196:199], v[108:111]
	v_mfma_f32_16x16x32_bf16 v[104:107], v[160:163], v[196:199], v[104:107]
	v_mfma_f32_16x16x32_bf16 v[92:95], v[144:147], v[204:207], v[92:95]
	v_mfma_f32_16x16x32_bf16 v[88:91], v[160:163], v[204:207], v[88:91]
	v_mfma_f32_16x16x32_bf16 v[76:79], v[144:147], v[212:215], v[76:79]
	v_mfma_f32_16x16x32_bf16 v[72:75], v[160:163], v[212:215], v[72:75]
	v_mfma_f32_16x16x32_bf16 v[124:127], v[148:151], v[192:195], v[124:127]
	v_mfma_f32_16x16x32_bf16 v[120:123], v[168:171], v[192:195], v[120:123]
	v_mfma_f32_16x16x32_bf16 v[108:111], v[148:151], v[200:203], v[108:111]
	v_mfma_f32_16x16x32_bf16 v[104:107], v[168:171], v[200:203], v[104:107]
	v_mfma_f32_16x16x32_bf16 v[92:95], v[148:151], v[208:211], v[92:95]
	v_mfma_f32_16x16x32_bf16 v[88:91], v[168:171], v[208:211], v[88:91]
	v_mfma_f32_16x16x32_bf16 v[76:79], v[148:151], v[216:219], v[76:79]
	v_mfma_f32_16x16x32_bf16 v[72:75], v[168:171], v[216:219], v[72:75]
	v_mfma_f32_16x16x32_bf16 v[116:119], v[172:175], v[188:191], v[116:119]
	v_mfma_f32_16x16x32_bf16 v[112:115], v[180:183], v[188:191], v[112:115]
	v_mfma_f32_16x16x32_bf16 v[100:103], v[172:175], v[196:199], v[100:103]
	v_mfma_f32_16x16x32_bf16 v[96:99], v[180:183], v[196:199], v[96:99]
	v_mfma_f32_16x16x32_bf16 v[84:87], v[172:175], v[204:207], v[84:87]
	v_mfma_f32_16x16x32_bf16 v[80:83], v[180:183], v[204:207], v[80:83]
	v_mfma_f32_16x16x32_bf16 v[68:71], v[172:175], v[212:215], v[68:71]
	v_mfma_f32_16x16x32_bf16 v[64:67], v[180:183], v[212:215], v[64:67]
	v_mfma_f32_16x16x32_bf16 v[116:119], v[176:179], v[192:195], v[116:119]
	v_mfma_f32_16x16x32_bf16 v[112:115], v[184:187], v[192:195], v[112:115]
	v_mfma_f32_16x16x32_bf16 v[100:103], v[176:179], v[200:203], v[100:103]
	v_mfma_f32_16x16x32_bf16 v[96:99], v[184:187], v[200:203], v[96:99]
	v_mfma_f32_16x16x32_bf16 v[84:87], v[176:179], v[208:211], v[84:87]
	v_mfma_f32_16x16x32_bf16 v[80:83], v[184:187], v[208:211], v[80:83]
	v_mfma_f32_16x16x32_bf16 v[68:71], v[176:179], v[216:219], v[68:71]
	v_mfma_f32_16x16x32_bf16 v[64:67], v[184:187], v[216:219], v[64:67]
	s_barrier
	s_add_i32 s57, s47, s35
	v_lshl_add_u64 v[164:165], s[26:27], 0, v[132:133]
	s_mov_b32 m0, s57
	ds_read_b128 v[188:191], v158 offset:16384
	ds_read_b128 v[192:195], v158 offset:17408
	ds_read_b128 v[196:199], v158 offset:18432
	ds_read_b128 v[200:203], v158 offset:19456
	ds_read_b128 v[204:207], v158 offset:20480
	ds_read_b128 v[208:211], v158 offset:21504
	ds_read_b128 v[212:215], v158 offset:22528
	ds_read_b128 v[216:219], v158 offset:23552
	global_load_lds_dwordx4 v[164:165], off
	s_add_i32 m0, s57, 0x2000
	s_add_u32 s58, s26, 0x80000
	v_lshl_add_u64 v[220:221], s[26:27], 0, v[128:129]
	s_addc_u32 s59, s27, 0
	s_add_i32 s57, s48, s35
	global_load_lds_dwordx4 v[220:221], off
	v_lshl_add_u64 v[222:223], s[58:59], 0, v[132:133]
	s_mov_b32 m0, s57
	v_lshl_add_u64 v[224:225], s[28:29], 0, v[130:131]
	global_load_lds_dwordx4 v[222:223], off
	v_lshl_add_u64 v[222:223], s[58:59], 0, v[128:129]
	s_add_i32 m0, s57, 0x2000
	s_nop 0
	global_load_lds_dwordx4 v[222:223], off
	v_lshl_add_u64 v[222:223], s[28:29], 0, v[134:135]
	s_mov_b32 m0, s38
	s_nop 0
	global_load_lds_dwordx4 v[222:223], off
	s_mov_b32 m0, s39
	s_nop 0
	global_load_lds_dwordx4 v[224:225], off
	s_waitcnt vmcnt(8)
	s_waitcnt lgkmcnt(0)
	s_barrier
; #define PG8_STAGE(bufoff, gbase, voff) do { _Pragma("unroll") for (int _i = 0; _i < 2; ++_i) \
;         __builtin_amdgcn_global_load_lds((const unsigned*)((const char*)(gbase) + (voff)[_i]), (LAS unsigned*)(lds + (bufoff) + ldsw + _i * 8192), 16, 0, 0); } while (0)
; #define PG8_LDA(dst, b, h) do { _Pragma("unroll") for (int m = 0; m < 4; ++m) _Pragma("unroll") for (int k = 0; k < 2; ++k) dst[m][k] = *(const LAS bf16x8*)(lds + PG8_SA(b, h) + aoff + m * 2048 + k * 1024); } while (0)
; #define PG8_LDB(dst, b, h) do { _Pragma("unroll") for (int n = 0; n < 2; ++n) _Pragma("unroll") for (int k = 0; k < 2; ++k) dst[n][k] = *(const LAS bf16x8*)(lds + PG8_SB(b, h) + boff + n * 2048 + k * 1024); } while (0)
; #define PG8_MMA(ai, bj, At, Bt) do { __builtin_amdgcn_s_setprio(1); _Pragma("unroll") for (int m = 0; m < 4; ++m) _Pragma("unroll") for (int n = 0; n < 2; ++n) _Pragma("unroll") for (int k = 0; k < 2; ++k) \
;         acc[ai][bj][m][n] = __builtin_amdgcn_mfma_f32_16x16x32_bf16(Bt[n][k], At[m][k], acc[ai][bj][m][n], 0, 0, 0); __builtin_amdgcn_s_setprio(0); } while (0)
; #define PG8_WAIT_V(n) asm volatile("s_waitcnt vmcnt(" #n ")" ::: "memory")
; #define PG8_WAIT_L(n) asm volatile("s_waitcnt lgkmcnt(" #n ")" ::: "memory")
; #define PG8_BAR __builtin_amdgcn_s_barrier()
; #define PG8_SCHED __builtin_amdgcn_sched_barrier(0)
; template <class Epi, bool ALIGN_EPI>
; __device__ __forceinline__ void gemm_phase(LAS unsigned char* lds, const Gemm g, const StaticOrder& S, const Epi& E) {
;     ...
;             PG8_WAIT_V(8); PG8_WAIT_L(0); PG8_BAR; PG8_MMA(1, 0, At, B0); PG8_MMA(1, 1, At, B1); PG8_BAR; PG8_SCHED;
;             PG8_LDB(B0, 1, 0); PG8_LDB(B1, 1, 1); PG8_SCHED; PG8_LDA(At, 1, 0); PG8_STAGE(PG8_SA(0, 1), a2 + hstepA, voffA);
;             PG8_WAIT_V(8); PG8_WAIT_L(0); PG8_BAR; PG8_MMA(0, 0, At, B0); PG8_MMA(0, 1, At, B1); PG8_BAR; PG8_SCHED;
	v_mfma_f32_16x16x32_bf16 v[60:63], v[144:147], v[188:191], v[60:63]
	v_mfma_f32_16x16x32_bf16 v[56:59], v[160:163], v[188:191], v[56:59]
	v_mfma_f32_16x16x32_bf16 v[44:47], v[144:147], v[196:199], v[44:47]
	v_mfma_f32_16x16x32_bf16 v[40:43], v[160:163], v[196:199], v[40:43]
	v_mfma_f32_16x16x32_bf16 v[28:31], v[144:147], v[204:207], v[28:31]
	v_mfma_f32_16x16x32_bf16 v[24:27], v[160:163], v[204:207], v[24:27]
	v_mfma_f32_16x16x32_bf16 v[12:15], v[144:147], v[212:215], v[12:15]
	v_mfma_f32_16x16x32_bf16 v[8:11], v[160:163], v[212:215], v[8:11]
	v_mfma_f32_16x16x32_bf16 v[60:63], v[148:151], v[192:195], v[60:63]
	v_mfma_f32_16x16x32_bf16 v[56:59], v[168:171], v[192:195], v[56:59]
	v_mfma_f32_16x16x32_bf16 v[44:47], v[148:151], v[200:203], v[44:47]
	v_mfma_f32_16x16x32_bf16 v[40:43], v[168:171], v[200:203], v[40:43]
	v_mfma_f32_16x16x32_bf16 v[28:31], v[148:151], v[208:211], v[28:31]
	v_mfma_f32_16x16x32_bf16 v[24:27], v[168:171], v[208:211], v[24:27]
	v_mfma_f32_16x16x32_bf16 v[12:15], v[148:151], v[216:219], v[12:15]
	v_mfma_f32_16x16x32_bf16 v[8:11], v[168:171], v[216:219], v[8:11]
	v_mfma_f32_16x16x32_bf16 v[52:55], v[172:175], v[188:191], v[52:55]
	v_mfma_f32_16x16x32_bf16 v[48:51], v[180:183], v[188:191], v[48:51]
	v_mfma_f32_16x16x32_bf16 v[36:39], v[172:175], v[196:199], v[36:39]
	v_mfma_f32_16x16x32_bf16 v[32:35], v[180:183], v[196:199], v[32:35]
	v_mfma_f32_16x16x32_bf16 v[20:23], v[172:175], v[204:207], v[20:23]
	v_mfma_f32_16x16x32_bf16 v[16:19], v[180:183], v[204:207], v[16:19]
	v_mfma_f32_16x16x32_bf16 v[4:7], v[172:175], v[212:215], v[4:7]
	v_mfma_f32_16x16x32_bf16 v[0:3], v[180:183], v[212:215], v[0:3]
	v_mfma_f32_16x16x32_bf16 v[52:55], v[176:179], v[192:195], v[52:55]
	v_mfma_f32_16x16x32_bf16 v[48:51], v[184:187], v[192:195], v[48:51]
	v_mfma_f32_16x16x32_bf16 v[36:39], v[176:179], v[200:203], v[36:39]
	v_mfma_f32_16x16x32_bf16 v[32:35], v[184:187], v[200:203], v[32:35]
	v_mfma_f32_16x16x32_bf16 v[20:23], v[176:179], v[208:211], v[20:23]
	v_mfma_f32_16x16x32_bf16 v[16:19], v[184:187], v[208:211], v[16:19]
	v_mfma_f32_16x16x32_bf16 v[4:7], v[176:179], v[216:219], v[4:7]
	v_mfma_f32_16x16x32_bf16 v[0:3], v[184:187], v[216:219], v[0:3]
	s_barrier
	s_add_i32 s57, 0, 0x18000
	s_add_i32 s58, 0, 0x1c000
	v_add_u32_e32 v168, s57, v154
	v_add_u32_e32 v184, s58, v154
	ds_read_b128 v[144:147], v168
	ds_read_b128 v[148:151], v168 offset:1024
	ds_read_b128 v[160:163], v168 offset:2048
	ds_read_b128 v[168:171], v168 offset:3072
	ds_read_b128 v[172:175], v184
	ds_read_b128 v[176:179], v184 offset:1024
	ds_read_b128 v[180:183], v184 offset:2048
	ds_read_b128 v[184:187], v184 offset:3072
	s_add_u32 s28, s28, 0x80000
	s_addc_u32 s29, s29, 0
	s_mov_b32 m0, s40
	v_lshl_add_u64 v[226:227], s[28:29], 0, v[134:135]
	ds_read_b128 v[188:191], v158 offset:32768
	ds_read_b128 v[192:195], v158 offset:33792
	ds_read_b128 v[196:199], v158 offset:34816
	ds_read_b128 v[200:203], v158 offset:35840
	ds_read_b128 v[204:207], v158 offset:36864
	ds_read_b128 v[208:211], v158 offset:37888
	ds_read_b128 v[212:215], v158 offset:38912
	ds_read_b128 v[216:219], v158 offset:39936
	global_load_lds_dwordx4 v[226:227], off
	v_lshl_add_u64 v[226:227], s[28:29], 0, v[130:131]
	s_mov_b32 m0, s41
	s_nop 0
	global_load_lds_dwordx4 v[226:227], off
	s_waitcnt vmcnt(8)
	s_waitcnt lgkmcnt(0)
	s_barrier
	v_mfma_f32_16x16x32_bf16 v[124:127], v[144:147], v[188:191], v[124:127]
	v_mfma_f32_16x16x32_bf16 v[120:123], v[160:163], v[188:191], v[120:123]
	v_mfma_f32_16x16x32_bf16 v[108:111], v[144:147], v[196:199], v[108:111]
	v_mfma_f32_16x16x32_bf16 v[104:107], v[160:163], v[196:199], v[104:107]
	v_mfma_f32_16x16x32_bf16 v[92:95], v[144:147], v[204:207], v[92:95]
	v_mfma_f32_16x16x32_bf16 v[88:91], v[160:163], v[204:207], v[88:91]
	v_mfma_f32_16x16x32_bf16 v[76:79], v[144:147], v[212:215], v[76:79]
	v_mfma_f32_16x16x32_bf16 v[72:75], v[160:163], v[212:215], v[72:75]
	v_mfma_f32_16x16x32_bf16 v[124:127], v[148:151], v[192:195], v[124:127]
	v_mfma_f32_16x16x32_bf16 v[120:123], v[168:171], v[192:195], v[120:123]
	v_mfma_f32_16x16x32_bf16 v[108:111], v[148:151], v[200:203], v[108:111]
	v_mfma_f32_16x16x32_bf16 v[104:107], v[168:171], v[200:203], v[104:107]
	v_mfma_f32_16x16x32_bf16 v[92:95], v[148:151], v[208:211], v[92:95]
	v_mfma_f32_16x16x32_bf16 v[88:91], v[168:171], v[208:211], v[88:91]
	v_mfma_f32_16x16x32_bf16 v[76:79], v[148:151], v[216:219], v[76:79]
	v_mfma_f32_16x16x32_bf16 v[72:75], v[168:171], v[216:219], v[72:75]
	v_mfma_f32_16x16x32_bf16 v[116:119], v[172:175], v[188:191], v[116:119]
	v_mfma_f32_16x16x32_bf16 v[112:115], v[180:183], v[188:191], v[112:115]
	v_mfma_f32_16x16x32_bf16 v[100:103], v[172:175], v[196:199], v[100:103]
	v_mfma_f32_16x16x32_bf16 v[96:99], v[180:183], v[196:199], v[96:99]
	v_mfma_f32_16x16x32_bf16 v[84:87], v[172:175], v[204:207], v[84:87]
	v_mfma_f32_16x16x32_bf16 v[80:83], v[180:183], v[204:207], v[80:83]
	v_mfma_f32_16x16x32_bf16 v[68:71], v[172:175], v[212:215], v[68:71]
	v_mfma_f32_16x16x32_bf16 v[64:67], v[180:183], v[212:215], v[64:67]
	v_mfma_f32_16x16x32_bf16 v[116:119], v[176:179], v[192:195], v[116:119]
	v_mfma_f32_16x16x32_bf16 v[112:115], v[184:187], v[192:195], v[112:115]
	v_mfma_f32_16x16x32_bf16 v[100:103], v[176:179], v[200:203], v[100:103]
	v_mfma_f32_16x16x32_bf16 v[96:99], v[184:187], v[200:203], v[96:99]
	v_mfma_f32_16x16x32_bf16 v[84:87], v[176:179], v[208:211], v[84:87]
	v_mfma_f32_16x16x32_bf16 v[80:83], v[184:187], v[208:211], v[80:83]
	v_mfma_f32_16x16x32_bf16 v[68:71], v[176:179], v[216:219], v[68:71]
	v_mfma_f32_16x16x32_bf16 v[64:67], v[184:187], v[216:219], v[64:67]
	s_barrier
; #define PG8_STAGE(bufoff, gbase, voff) do { _Pragma("unroll") for (int _i = 0; _i < 2; ++_i) \
;         __builtin_amdgcn_global_load_lds((const unsigned*)((const char*)(gbase) + (voff)[_i]), (LAS unsigned*)(lds + (bufoff) + ldsw + _i * 8192), 16, 0, 0); } while (0)
; #define PG8_LDA(dst, b, h) do { _Pragma("unroll") for (int m = 0; m < 4; ++m) _Pragma("unroll") for (int k = 0; k < 2; ++k) dst[m][k] = *(const LAS bf16x8*)(lds + PG8_SA(b, h) + aoff + m * 2048 + k * 1024); } while (0)
; #define PG8_MMA(ai, bj, At, Bt) do { __builtin_amdgcn_s_setprio(1); _Pragma("unroll") for (int m = 0; m < 4; ++m) _Pragma("unroll") for (int n = 0; n < 2; ++n) _Pragma("unroll") for (int k = 0; k < 2; ++k) \
;         acc[ai][bj][m][n] = __builtin_amdgcn_mfma_f32_16x16x32_bf16(Bt[n][k], At[m][k], acc[ai][bj][m][n], 0, 0, 0); __builtin_amdgcn_s_setprio(0); } while (0)
; #define PG8_WAIT_V(n) asm volatile("s_waitcnt vmcnt(" #n ")" ::: "memory")
; #define PG8_WAIT_L(n) asm volatile("s_waitcnt lgkmcnt(" #n ")" ::: "memory")
; #define PG8_BAR __builtin_amdgcn_s_barrier()
; #define PG8_SCHED __builtin_amdgcn_sched_barrier(0)
; template <class Epi, bool ALIGN_EPI>
; __device__ __forceinline__ void gemm_phase(LAS unsigned char* lds, const Gemm g, const StaticOrder& S, const Epi& E) {
;     ...
;             PG8_LDA(At, 1, 1); PG8_STAGE(PG8_SB(1, 0), b3, voffB); PG8_STAGE(PG8_SB(1, 1), b3 + hstepB, voffB); PG8_STAGE(PG8_SA(1, 0), a3, voffA);
;             PG8_WAIT_V(8); PG8_WAIT_L(0); PG8_BAR; PG8_MMA(1, 0, At, B0); PG8_MMA(1, 1, At, B1); PG8_BAR; PG8_SCHED;
;         }
	s_add_i32 s28, s57, s35
	v_lshl_add_u64 v[164:165], v[164:165], 0, s[12:13]
	s_mov_b32 m0, s28
	ds_read_b128 v[188:191], v158 offset:49152
	ds_read_b128 v[192:195], v158 offset:50176
	ds_read_b128 v[196:199], v158 offset:51200
	ds_read_b128 v[200:203], v158 offset:52224
	ds_read_b128 v[204:207], v158 offset:53248
	ds_read_b128 v[208:211], v158 offset:54272
	ds_read_b128 v[212:215], v158 offset:55296
	ds_read_b128 v[216:219], v158 offset:56320
	global_load_lds_dwordx4 v[164:165], off
	s_add_i32 m0, s28, 0x2000
	s_add_u32 s26, s26, 0x80080
	v_lshl_add_u64 v[164:165], v[220:221], 0, s[12:13]
	s_addc_u32 s27, s27, 0
	s_add_i32 s28, s58, s35
	global_load_lds_dwordx4 v[164:165], off
	v_lshl_add_u64 v[164:165], s[26:27], 0, v[132:133]
	s_mov_b32 m0, s28
	s_nop 0
	global_load_lds_dwordx4 v[164:165], off
	v_lshl_add_u64 v[164:165], s[26:27], 0, v[128:129]
	s_add_i32 m0, s28, 0x2000
	s_nop 0
	global_load_lds_dwordx4 v[164:165], off
	v_lshl_add_u64 v[164:165], v[222:223], 0, s[12:13]
	s_mov_b32 m0, s42
	s_nop 0
	global_load_lds_dwordx4 v[164:165], off
	v_lshl_add_u64 v[164:165], v[224:225], 0, s[12:13]
	s_mov_b32 m0, s43
	s_nop 0
	global_load_lds_dwordx4 v[164:165], off
	s_waitcnt vmcnt(8)
	s_waitcnt lgkmcnt(0)
	s_barrier
	v_mfma_f32_16x16x32_bf16 v[60:63], v[144:147], v[188:191], v[60:63]
	v_mfma_f32_16x16x32_bf16 v[56:59], v[160:163], v[188:191], v[56:59]
	v_mfma_f32_16x16x32_bf16 v[44:47], v[144:147], v[196:199], v[44:47]
	v_mfma_f32_16x16x32_bf16 v[40:43], v[160:163], v[196:199], v[40:43]
	v_mfma_f32_16x16x32_bf16 v[28:31], v[144:147], v[204:207], v[28:31]
	v_mfma_f32_16x16x32_bf16 v[24:27], v[160:163], v[204:207], v[24:27]
	v_mfma_f32_16x16x32_bf16 v[12:15], v[144:147], v[212:215], v[12:15]
	v_mfma_f32_16x16x32_bf16 v[8:11], v[160:163], v[212:215], v[8:11]
	v_mfma_f32_16x16x32_bf16 v[60:63], v[148:151], v[192:195], v[60:63]
	v_mfma_f32_16x16x32_bf16 v[56:59], v[168:171], v[192:195], v[56:59]
	v_mfma_f32_16x16x32_bf16 v[44:47], v[148:151], v[200:203], v[44:47]
	v_mfma_f32_16x16x32_bf16 v[40:43], v[168:171], v[200:203], v[40:43]
	v_mfma_f32_16x16x32_bf16 v[28:31], v[148:151], v[208:211], v[28:31]
	v_mfma_f32_16x16x32_bf16 v[24:27], v[168:171], v[208:211], v[24:27]
	v_mfma_f32_16x16x32_bf16 v[12:15], v[148:151], v[216:219], v[12:15]
	v_mfma_f32_16x16x32_bf16 v[8:11], v[168:171], v[216:219], v[8:11]
	v_mfma_f32_16x16x32_bf16 v[52:55], v[172:175], v[188:191], v[52:55]
	v_mfma_f32_16x16x32_bf16 v[48:51], v[180:183], v[188:191], v[48:51]
	v_mfma_f32_16x16x32_bf16 v[36:39], v[172:175], v[196:199], v[36:39]
	v_mfma_f32_16x16x32_bf16 v[32:35], v[180:183], v[196:199], v[32:35]
	v_mfma_f32_16x16x32_bf16 v[20:23], v[172:175], v[204:207], v[20:23]
	v_mfma_f32_16x16x32_bf16 v[16:19], v[180:183], v[204:207], v[16:19]
	v_mfma_f32_16x16x32_bf16 v[4:7], v[172:175], v[212:215], v[4:7]
	v_mfma_f32_16x16x32_bf16 v[0:3], v[180:183], v[212:215], v[0:3]
	v_mfma_f32_16x16x32_bf16 v[52:55], v[176:179], v[192:195], v[52:55]
	v_mfma_f32_16x16x32_bf16 v[48:51], v[184:187], v[192:195], v[48:51]
	v_mfma_f32_16x16x32_bf16 v[36:39], v[176:179], v[200:203], v[36:39]
	v_mfma_f32_16x16x32_bf16 v[32:35], v[184:187], v[200:203], v[32:35]
	v_mfma_f32_16x16x32_bf16 v[20:23], v[176:179], v[208:211], v[20:23]
	v_mfma_f32_16x16x32_bf16 v[16:19], v[184:187], v[208:211], v[16:19]
	v_mfma_f32_16x16x32_bf16 v[4:7], v[176:179], v[216:219], v[4:7]
	v_mfma_f32_16x16x32_bf16 v[0:3], v[184:187], v[216:219], v[0:3]
	s_barrier
	s_add_i32 s56, s56, 2
	s_add_u32 s54, s54, 0x100
	s_addc_u32 s55, s55, 0
	s_add_u32 s24, s24, 0x100
	s_addc_u32 s25, s25, 0
	s_cmp_gt_u32 s56, 29
	s_cbranch_scc0 .LBB0_1293
	s_and_b64 vcc, exec, s[14:15]
	s_cbranch_vccz .LBB0_1296
	s_barrier

; #define INP(k) ((const float*)PTR(k))
; #define WSP(off) (PTR(29) + (off))
;     __device__ bool next(int i, Unit& u) const {
;         const long L = (long)i * G + c; if (L >= nwg) return false;
;         int wgid = (int)L; { const int q = nwg / NXCD, r = nwg % NXCD, xcd = wgid % NXCD, off = wgid / NXCD; wgid = (xcd < r ? xcd * (q + 1) : r * (q + 1) + (xcd - r) * q) + off; }
;         const int nig = WGM * nN, gid = wgid / nig, fm = gid * WGM, gsz = (nM - fm) < WGM ? (nM - fm) : WGM;
;         u.pm = fm + ((wgid % nig) % gsz); u.pn = (wgid % nig) / gsz; return true;
; template <int K>
; __device__ __forceinline__ void run_phase(LAS unsigned char* lds, volatile LAS unsigned* ptab) {
;     ...
;         float* out = OUTP;
;         pg8::Gemm g{(const bf16_t*)WSP(WS_H2), (const bf16_t*)WSP(WS_WAD2), MROWS, DM, DFF, DFF}; pg8::StaticOrder S; S.init(MROWS, DM, G, bx);
;         pg8::EpiResid E{out, out + (size_t)SEQ_P * DM, nullptr, DM, 0.5f, (bf16_t*)WSP(WS_XN2), INP(27), (float*)WSP(WS_SS3)};
;         pg8::gemm_phase<pg8::EpiResid, true>(lds, g, S, E);
.Lprio_skip_6:
	s_waitcnt lgkmcnt(0)
	v_mov_b32_e32 v0, v166
	s_barrier
	s_add_i32 s0, 0, 0x230e4
	v_mov_b32_e32 v0, s0
	s_add_i32 s0, 0, 0x230e0
	ds_read_b32 v0, v0
	v_mov_b32_e32 v1, s0
	ds_read_b32 v1, v1
	s_add_i32 s0, 0, 0x230ec
	v_readlane_b32 s16, v252, 14
	s_waitcnt lgkmcnt(1)
	v_readfirstlane_b32 s9, v0
	v_mov_b32_e32 v0, s0
	s_add_i32 s0, 0, 0x230e8
	s_waitcnt lgkmcnt(0)
	v_readfirstlane_b32 s8, v1
	ds_read_b32 v1, v0
	v_mov_b32_e32 v2, s0
	ds_read_b32 v3, v2
	ds_read_b32 v4, v0
	ds_read_b32 v5, v2
	ds_read_b32 v6, v0
	s_add_i32 s0, 0, 0x230dc
	s_waitcnt lgkmcnt(3)
	v_readfirstlane_b32 s2, v3
	v_mov_b32_e32 v3, s0
	s_add_i32 s0, 0, 0x230d8
	s_waitcnt lgkmcnt(2)
	v_readfirstlane_b32 s6, v4
	v_mov_b32_e32 v4, s0
	v_readfirstlane_b32 s4, v1
	ds_read_b32 v1, v2
	ds_read_b32 v3, v3
	ds_read_b32 v4, v4
	ds_read_b32 v0, v0
	ds_read_b32 v2, v2
	v_mov_b32_e32 v8, v166
	v_readlane_b32 s17, v252, 15
	s_waitcnt lgkmcnt(6)
	v_readfirstlane_b32 s12, v5
	s_waitcnt lgkmcnt(5)
	v_readfirstlane_b32 s1, v6
	s_waitcnt lgkmcnt(4)
	v_readfirstlane_b32 s14, v1
	s_waitcnt lgkmcnt(3)
	v_readfirstlane_b32 s11, v3
	s_waitcnt lgkmcnt(2)
	v_readfirstlane_b32 s10, v4
	s_waitcnt lgkmcnt(1)
	v_readfirstlane_b32 s5, v0
	s_waitcnt lgkmcnt(0)
	v_readfirstlane_b32 s7, v2
	s_and_b64 vcc, exec, s[16:17]
	v_readfirstlane_b32 s0, v8
	s_cbranch_vccnz .LBB0_1366
	s_ashr_i32 s13, s3, 31
	s_lshr_b32 s13, s13, 29
	s_add_i32 s13, s3, s13
	s_ashr_i32 s15, s13, 3
	s_and_b32 s13, s13, -8
	s_sub_i32 s13, s3, s13
	s_cmp_lt_i32 s13, 0
	s_movk_i32 s16, 0x61
	s_cselect_b32 s16, s16, 0x60
	s_mul_i32 s13, s16, s13
	s_add_i32 s13, s13, s15
	s_ashr_i32 s15, s13, 31
	s_lshr_b32 s15, s15, 26
	s_add_i32 s15, s13, s15
	s_ashr_i32 s16, s15, 6
	s_and_b32 s15, s15, 0xffc0
	s_sub_i32 s13, s13, s15
	s_bfe_i32 s15, s13, 0x80000
	s_bfe_u32 s15, s15, 0x3000c
	s_add_i32 s15, s13, s15
	s_bfe_i32 s17, s15, 0x80000
	s_and_b32 s15, s15, 0xf8
	s_sub_i32 s13, s13, s15
	s_lshl_b32 s16, s16, 3
	s_sext_i32_i16 s17, s17
	s_sext_i32_i8 s13, s13
	s_add_i32 s54, s16, s13
	s_ashr_i32 s53, s17, 3

; #define PG8_STAGE(bufoff, gbase, voff) do { _Pragma("unroll") for (int _i = 0; _i < 2; ++_i) \
;         __builtin_amdgcn_global_load_lds((const unsigned*)((const char*)(gbase) + (voff)[_i]), (LAS unsigned*)(lds + (bufoff) + ldsw + _i * 8192), 16, 0, 0); } while (0)
; #define PG8_LDA(dst, b, h) do { _Pragma("unroll") for (int m = 0; m < 4; ++m) _Pragma("unroll") for (int k = 0; k < 2; ++k) dst[m][k] = *(const LAS bf16x8*)(lds + PG8_SA(b, h) + aoff + m * 2048 + k * 1024); } while (0)
; #define PG8_LDB(dst, b, h) do { _Pragma("unroll") for (int n = 0; n < 2; ++n) _Pragma("unroll") for (int k = 0; k < 2; ++k) dst[n][k] = *(const LAS bf16x8*)(lds + PG8_SB(b, h) + boff + n * 2048 + k * 1024); } while (0)
; #define PG8_MMA(ai, bj, At, Bt) do { __builtin_amdgcn_s_setprio(1); _Pragma("unroll") for (int m = 0; m < 4; ++m) _Pragma("unroll") for (int n = 0; n < 2; ++n) _Pragma("unroll") for (int k = 0; k < 2; ++k) \
;         acc[ai][bj][m][n] = __builtin_amdgcn_mfma_f32_16x16x32_bf16(Bt[n][k], At[m][k], acc[ai][bj][m][n], 0, 0, 0); __builtin_amdgcn_s_setprio(0); } while (0)
; #define PG8_WAIT_V(n) asm volatile("s_waitcnt vmcnt(" #n ")" ::: "memory")
; #define PG8_WAIT_L(n) asm volatile("s_waitcnt lgkmcnt(" #n ")" ::: "memory")
; #define PG8_BAR __builtin_amdgcn_s_barrier()
; #define PG8_SCHED __builtin_amdgcn_sched_barrier(0)
; template <class Epi, bool ALIGN_EPI>
; __device__ __forceinline__ void gemm_phase(LAS unsigned char* lds, const Gemm g, const StaticOrder& S, const Epi& E) {
;     ...
;             const bool last = (t == nt - 2);
;             const char* a1 = cA + (size_t)(t + 1) * kstep;
;             const char* a2 = last ? nA : cA + (size_t)(t + 2) * kstep; const char* b2 = last ? nB : cB + (size_t)(t + 2) * kstep;
;             const char* a3 = a2 + kstep; const char* b3 = b2 + kstep;
;             PG8_LDB(B0, 0, 0); PG8_LDB(B1, 0, 1); PG8_SCHED; PG8_LDA(At, 0, 0); PG8_STAGE(PG8_SA(1, 1), a1 + hstepA, voffA);
;             PG8_WAIT_V(8); PG8_WAIT_L(0); PG8_BAR; PG8_MMA(0, 0, At, B0); PG8_MMA(0, 1, At, B1); PG8_BAR; PG8_SCHED;
;             PG8_LDA(At, 0, 1); PG8_STAGE(PG8_SB(0, 0), b2, voffB); PG8_STAGE(PG8_SB(0, 1), b2 + hstepB, voffB); PG8_STAGE(PG8_SA(0, 0), a2, voffA);
;             PG8_WAIT_V(8); PG8_WAIT_L(0); PG8_BAR; PG8_MMA(1, 0, At, B0); PG8_MMA(1, 1, At, B1); PG8_BAR; PG8_SCHED;
.LBB0_1379:
	ds_read_b128 v[72:75], v163
	ds_read_b128 v[84:87], v163 offset:1024
	ds_read_b128 v[88:91], v163 offset:2048
	ds_read_b128 v[96:99], v163 offset:3072
	ds_read_b128 v[156:159], v164
	ds_read_b128 v[168:171], v164 offset:1024
	ds_read_b128 v[172:175], v164 offset:2048
	ds_read_b128 v[176:179], v164 offset:3072
	s_add_u32 s26, s24, 0x100
	s_addc_u32 s27, s25, 0
	s_cmpk_eq_i32 s57, 0x54
	s_cselect_b32 s31, s5, s27
	s_cselect_b32 s30, s4, s26
	s_cselect_b32 s29, s23, s56
	s_cselect_b32 s28, s22, s55
	v_lshl_add_u64 v[212:213], s[24:25], 0, v[150:151]
	s_add_i32 m0, s37, 0xc000
	ds_read_b128 v[180:183], v165
	ds_read_b128 v[184:187], v165 offset:1024
	ds_read_b128 v[188:191], v165 offset:2048
	ds_read_b128 v[192:195], v165 offset:3072
	ds_read_b128 v[196:199], v165 offset:4096
	ds_read_b128 v[200:203], v165 offset:5120
	ds_read_b128 v[204:207], v165 offset:6144
	ds_read_b128 v[208:211], v165 offset:7168
	global_load_lds_dwordx4 v[212:213], off
	v_lshl_add_u64 v[212:213], s[24:25], 0, v[148:149]
	s_add_i32 m0, s37, 0xe000
	s_nop 0
	global_load_lds_dwordx4 v[212:213], off
	s_waitcnt vmcnt(8)
	s_waitcnt lgkmcnt(0)
	s_barrier
	v_mfma_f32_16x16x32_bf16 v[140:143], v[72:75], v[180:183], v[140:143]
	v_mfma_f32_16x16x32_bf16 v[136:139], v[88:91], v[180:183], v[136:139]
	v_mfma_f32_16x16x32_bf16 v[124:127], v[72:75], v[188:191], v[124:127]
	v_mfma_f32_16x16x32_bf16 v[120:123], v[88:91], v[188:191], v[120:123]
	v_mfma_f32_16x16x32_bf16 v[108:111], v[72:75], v[196:199], v[108:111]
	v_mfma_f32_16x16x32_bf16 v[104:107], v[88:91], v[196:199], v[104:107]
	v_mfma_f32_16x16x32_bf16 v[80:83], v[72:75], v[204:207], v[80:83]
	v_mfma_f32_16x16x32_bf16 v[76:79], v[88:91], v[204:207], v[76:79]
	v_mfma_f32_16x16x32_bf16 v[140:143], v[84:87], v[184:187], v[140:143]
	v_mfma_f32_16x16x32_bf16 v[136:139], v[96:99], v[184:187], v[136:139]
	v_mfma_f32_16x16x32_bf16 v[124:127], v[84:87], v[192:195], v[124:127]
	v_mfma_f32_16x16x32_bf16 v[120:123], v[96:99], v[192:195], v[120:123]
	v_mfma_f32_16x16x32_bf16 v[108:111], v[84:87], v[200:203], v[108:111]
	v_mfma_f32_16x16x32_bf16 v[104:107], v[96:99], v[200:203], v[104:107]
	v_mfma_f32_16x16x32_bf16 v[80:83], v[84:87], v[208:211], v[80:83]
	v_mfma_f32_16x16x32_bf16 v[76:79], v[96:99], v[208:211], v[76:79]
	v_mfma_f32_16x16x32_bf16 v[132:135], v[156:159], v[180:183], v[132:135]
	v_mfma_f32_16x16x32_bf16 v[128:131], v[172:175], v[180:183], v[128:131]
	v_mfma_f32_16x16x32_bf16 v[116:119], v[156:159], v[188:191], v[116:119]
	v_mfma_f32_16x16x32_bf16 v[112:115], v[172:175], v[188:191], v[112:115]
	v_mfma_f32_16x16x32_bf16 v[100:103], v[156:159], v[196:199], v[100:103]
	v_mfma_f32_16x16x32_bf16 v[92:95], v[172:175], v[196:199], v[92:95]
	v_mfma_f32_16x16x32_bf16 v[68:71], v[156:159], v[204:207], v[68:71]
	v_mfma_f32_16x16x32_bf16 v[64:67], v[172:175], v[204:207], v[64:67]
	v_mfma_f32_16x16x32_bf16 v[132:135], v[168:171], v[184:187], v[132:135]
	v_mfma_f32_16x16x32_bf16 v[128:131], v[176:179], v[184:187], v[128:131]
	v_mfma_f32_16x16x32_bf16 v[116:119], v[168:171], v[192:195], v[116:119]
	v_mfma_f32_16x16x32_bf16 v[112:115], v[176:179], v[192:195], v[112:115]
	v_mfma_f32_16x16x32_bf16 v[100:103], v[168:171], v[200:203], v[100:103]
	v_mfma_f32_16x16x32_bf16 v[92:95], v[176:179], v[200:203], v[92:95]
	v_mfma_f32_16x16x32_bf16 v[68:71], v[168:171], v[208:211], v[68:71]
	v_mfma_f32_16x16x32_bf16 v[64:67], v[176:179], v[208:211], v[64:67]
	s_barrier
	s_add_i32 s24, s48, s36
	v_lshl_add_u64 v[212:213], s[28:29], 0, v[144:145]
	s_mov_b32 m0, s24
	ds_read_b128 v[180:183], v165 offset:16384
	ds_read_b128 v[184:187], v165 offset:17408
	ds_read_b128 v[188:191], v165 offset:18432
	ds_read_b128 v[192:195], v165 offset:19456
	ds_read_b128 v[196:199], v165 offset:20480
	ds_read_b128 v[200:203], v165 offset:21504
	ds_read_b128 v[204:207], v165 offset:22528
	ds_read_b128 v[208:211], v165 offset:23552
	global_load_lds_dwordx4 v[212:213], off
	s_add_i32 m0, s24, 0x2000
	s_add_u32 s24, s28, 0x160000
	v_lshl_add_u64 v[214:215], s[28:29], 0, v[146:147]
	s_addc_u32 s25, s29, 0
	s_add_i32 s58, s49, s36
	global_load_lds_dwordx4 v[214:215], off
	v_lshl_add_u64 v[216:217], s[24:25], 0, v[144:145]
	s_mov_b32 m0, s58
	v_lshl_add_u64 v[218:219], s[30:31], 0, v[146:147]
	global_load_lds_dwordx4 v[216:217], off
	v_lshl_add_u64 v[216:217], s[24:25], 0, v[146:147]
	s_add_i32 m0, s58, 0x2000
	s_nop 0
	global_load_lds_dwordx4 v[216:217], off
	v_lshl_add_u64 v[216:217], s[30:31], 0, v[144:145]
	s_mov_b32 m0, s37
	s_nop 0
	global_load_lds_dwordx4 v[216:217], off
	s_mov_b32 m0, s38
	s_nop 0
	global_load_lds_dwordx4 v[218:219], off
	s_waitcnt vmcnt(8)
	s_waitcnt lgkmcnt(0)
	s_barrier
; #define PG8_STAGE(bufoff, gbase, voff) do { _Pragma("unroll") for (int _i = 0; _i < 2; ++_i) \
;         __builtin_amdgcn_global_load_lds((const unsigned*)((const char*)(gbase) + (voff)[_i]), (LAS unsigned*)(lds + (bufoff) + ldsw + _i * 8192), 16, 0, 0); } while (0)
; #define PG8_LDA(dst, b, h) do { _Pragma("unroll") for (int m = 0; m < 4; ++m) _Pragma("unroll") for (int k = 0; k < 2; ++k) dst[m][k] = *(const LAS bf16x8*)(lds + PG8_SA(b, h) + aoff + m * 2048 + k * 1024); } while (0)
; #define PG8_LDB(dst, b, h) do { _Pragma("unroll") for (int n = 0; n < 2; ++n) _Pragma("unroll") for (int k = 0; k < 2; ++k) dst[n][k] = *(const LAS bf16x8*)(lds + PG8_SB(b, h) + boff + n * 2048 + k * 1024); } while (0)
; #define PG8_MMA(ai, bj, At, Bt) do { __builtin_amdgcn_s_setprio(1); _Pragma("unroll") for (int m = 0; m < 4; ++m) _Pragma("unroll") for (int n = 0; n < 2; ++n) _Pragma("unroll") for (int k = 0; k < 2; ++k) \
;         acc[ai][bj][m][n] = __builtin_amdgcn_mfma_f32_16x16x32_bf16(Bt[n][k], At[m][k], acc[ai][bj][m][n], 0, 0, 0); __builtin_amdgcn_s_setprio(0); } while (0)
; #define PG8_WAIT_V(n) asm volatile("s_waitcnt vmcnt(" #n ")" ::: "memory")
; #define PG8_WAIT_L(n) asm volatile("s_waitcnt lgkmcnt(" #n ")" ::: "memory")
; #define PG8_BAR __builtin_amdgcn_s_barrier()
; #define PG8_SCHED __builtin_amdgcn_sched_barrier(0)
; template <class Epi, bool ALIGN_EPI>
; __device__ __forceinline__ void gemm_phase(LAS unsigned char* lds, const Gemm g, const StaticOrder& S, const Epi& E) {
;     ...
;             PG8_WAIT_V(8); PG8_WAIT_L(0); PG8_BAR; PG8_MMA(1, 0, At, B0); PG8_MMA(1, 1, At, B1); PG8_BAR; PG8_SCHED;
;             PG8_LDB(B0, 1, 0); PG8_LDB(B1, 1, 1); PG8_SCHED; PG8_LDA(At, 1, 0); PG8_STAGE(PG8_SA(0, 1), a2 + hstepA, voffA);
;             PG8_WAIT_V(8); PG8_WAIT_L(0); PG8_BAR; PG8_MMA(0, 0, At, B0); PG8_MMA(0, 1, At, B1); PG8_BAR; PG8_SCHED;
	v_mfma_f32_16x16x32_bf16 v[60:63], v[72:75], v[180:183], v[60:63]
	v_mfma_f32_16x16x32_bf16 v[56:59], v[88:91], v[180:183], v[56:59]
	v_mfma_f32_16x16x32_bf16 v[44:47], v[72:75], v[188:191], v[44:47]
	v_mfma_f32_16x16x32_bf16 v[40:43], v[88:91], v[188:191], v[40:43]
	v_mfma_f32_16x16x32_bf16 v[28:31], v[72:75], v[196:199], v[28:31]
	v_mfma_f32_16x16x32_bf16 v[24:27], v[88:91], v[196:199], v[24:27]
	v_mfma_f32_16x16x32_bf16 v[12:15], v[72:75], v[204:207], v[12:15]
	v_mfma_f32_16x16x32_bf16 v[8:11], v[88:91], v[204:207], v[8:11]
	v_mfma_f32_16x16x32_bf16 v[60:63], v[84:87], v[184:187], v[60:63]
	v_mfma_f32_16x16x32_bf16 v[56:59], v[96:99], v[184:187], v[56:59]
	v_mfma_f32_16x16x32_bf16 v[44:47], v[84:87], v[192:195], v[44:47]
	v_mfma_f32_16x16x32_bf16 v[40:43], v[96:99], v[192:195], v[40:43]
	v_mfma_f32_16x16x32_bf16 v[28:31], v[84:87], v[200:203], v[28:31]
	v_mfma_f32_16x16x32_bf16 v[24:27], v[96:99], v[200:203], v[24:27]
	v_mfma_f32_16x16x32_bf16 v[12:15], v[84:87], v[208:211], v[12:15]
	v_mfma_f32_16x16x32_bf16 v[8:11], v[96:99], v[208:211], v[8:11]
	v_mfma_f32_16x16x32_bf16 v[52:55], v[156:159], v[180:183], v[52:55]
	v_mfma_f32_16x16x32_bf16 v[48:51], v[172:175], v[180:183], v[48:51]
	v_mfma_f32_16x16x32_bf16 v[36:39], v[156:159], v[188:191], v[36:39]
	v_mfma_f32_16x16x32_bf16 v[32:35], v[172:175], v[188:191], v[32:35]
	v_mfma_f32_16x16x32_bf16 v[20:23], v[156:159], v[196:199], v[20:23]
	v_mfma_f32_16x16x32_bf16 v[16:19], v[172:175], v[196:199], v[16:19]
	v_mfma_f32_16x16x32_bf16 v[4:7], v[156:159], v[204:207], v[4:7]
	v_mfma_f32_16x16x32_bf16 v[0:3], v[172:175], v[204:207], v[0:3]
	v_mfma_f32_16x16x32_bf16 v[52:55], v[168:171], v[184:187], v[52:55]
	v_mfma_f32_16x16x32_bf16 v[48:51], v[176:179], v[184:187], v[48:51]
	v_mfma_f32_16x16x32_bf16 v[36:39], v[168:171], v[192:195], v[36:39]
	v_mfma_f32_16x16x32_bf16 v[32:35], v[176:179], v[192:195], v[32:35]
	v_mfma_f32_16x16x32_bf16 v[20:23], v[168:171], v[200:203], v[20:23]
	v_mfma_f32_16x16x32_bf16 v[16:19], v[176:179], v[200:203], v[16:19]
	v_mfma_f32_16x16x32_bf16 v[4:7], v[168:171], v[208:211], v[4:7]
	v_mfma_f32_16x16x32_bf16 v[0:3], v[176:179], v[208:211], v[0:3]
	s_barrier
	s_add_i32 s58, 0, 0x18000
	s_add_i32 s59, 0, 0x1c000
	v_add_u32_e32 v96, s58, v161
	v_add_u32_e32 v176, s59, v161
	ds_read_b128 v[72:75], v96
	ds_read_b128 v[84:87], v96 offset:1024
	ds_read_b128 v[88:91], v96 offset:2048
	ds_read_b128 v[96:99], v96 offset:3072
	ds_read_b128 v[156:159], v176
	ds_read_b128 v[168:171], v176 offset:1024
	ds_read_b128 v[172:175], v176 offset:2048
	ds_read_b128 v[176:179], v176 offset:3072
	s_add_u32 s24, s30, 0x160000
	s_addc_u32 s25, s31, 0
	s_mov_b32 m0, s39
	v_lshl_add_u64 v[220:221], s[24:25], 0, v[144:145]
	ds_read_b128 v[180:183], v165 offset:32768
	ds_read_b128 v[184:187], v165 offset:33792
	ds_read_b128 v[188:191], v165 offset:34816
	ds_read_b128 v[192:195], v165 offset:35840
	ds_read_b128 v[196:199], v165 offset:36864
	ds_read_b128 v[200:203], v165 offset:37888
	ds_read_b128 v[204:207], v165 offset:38912
	ds_read_b128 v[208:211], v165 offset:39936
	global_load_lds_dwordx4 v[220:221], off
	v_lshl_add_u64 v[220:221], s[24:25], 0, v[146:147]
	s_mov_b32 m0, s40
	s_nop 0
	global_load_lds_dwordx4 v[220:221], off
	s_waitcnt vmcnt(8)
	s_waitcnt lgkmcnt(0)
	s_barrier
	v_mfma_f32_16x16x32_bf16 v[140:143], v[72:75], v[180:183], v[140:143]
	v_mfma_f32_16x16x32_bf16 v[136:139], v[88:91], v[180:183], v[136:139]
	v_mfma_f32_16x16x32_bf16 v[124:127], v[72:75], v[188:191], v[124:127]
	v_mfma_f32_16x16x32_bf16 v[120:123], v[88:91], v[188:191], v[120:123]
	v_mfma_f32_16x16x32_bf16 v[108:111], v[72:75], v[196:199], v[108:111]
	v_mfma_f32_16x16x32_bf16 v[104:107], v[88:91], v[196:199], v[104:107]
	v_mfma_f32_16x16x32_bf16 v[80:83], v[72:75], v[204:207], v[80:83]
	v_mfma_f32_16x16x32_bf16 v[76:79], v[88:91], v[204:207], v[76:79]
	v_mfma_f32_16x16x32_bf16 v[140:143], v[84:87], v[184:187], v[140:143]
	v_mfma_f32_16x16x32_bf16 v[136:139], v[96:99], v[184:187], v[136:139]
	v_mfma_f32_16x16x32_bf16 v[124:127], v[84:87], v[192:195], v[124:127]
	v_mfma_f32_16x16x32_bf16 v[120:123], v[96:99], v[192:195], v[120:123]
	v_mfma_f32_16x16x32_bf16 v[108:111], v[84:87], v[200:203], v[108:111]
	v_mfma_f32_16x16x32_bf16 v[104:107], v[96:99], v[200:203], v[104:107]
	v_mfma_f32_16x16x32_bf16 v[80:83], v[84:87], v[208:211], v[80:83]
	v_mfma_f32_16x16x32_bf16 v[76:79], v[96:99], v[208:211], v[76:79]
	v_mfma_f32_16x16x32_bf16 v[132:135], v[156:159], v[180:183], v[132:135]
	v_mfma_f32_16x16x32_bf16 v[128:131], v[172:175], v[180:183], v[128:131]
	v_mfma_f32_16x16x32_bf16 v[116:119], v[156:159], v[188:191], v[116:119]
	v_mfma_f32_16x16x32_bf16 v[112:115], v[172:175], v[188:191], v[112:115]
	v_mfma_f32_16x16x32_bf16 v[100:103], v[156:159], v[196:199], v[100:103]
	v_mfma_f32_16x16x32_bf16 v[92:95], v[172:175], v[196:199], v[92:95]
	v_mfma_f32_16x16x32_bf16 v[68:71], v[156:159], v[204:207], v[68:71]
	v_mfma_f32_16x16x32_bf16 v[64:67], v[172:175], v[204:207], v[64:67]
	v_mfma_f32_16x16x32_bf16 v[132:135], v[168:171], v[184:187], v[132:135]
	v_mfma_f32_16x16x32_bf16 v[128:131], v[176:179], v[184:187], v[128:131]
	v_mfma_f32_16x16x32_bf16 v[116:119], v[168:171], v[192:195], v[116:119]
	v_mfma_f32_16x16x32_bf16 v[112:115], v[176:179], v[192:195], v[112:115]
	v_mfma_f32_16x16x32_bf16 v[100:103], v[168:171], v[200:203], v[100:103]
	v_mfma_f32_16x16x32_bf16 v[92:95], v[176:179], v[200:203], v[92:95]
	v_mfma_f32_16x16x32_bf16 v[68:71], v[168:171], v[208:211], v[68:71]
	v_mfma_f32_16x16x32_bf16 v[64:67], v[176:179], v[208:211], v[64:67]
	s_barrier
; #define PG8_STAGE(bufoff, gbase, voff) do { _Pragma("unroll") for (int _i = 0; _i < 2; ++_i) \
;         __builtin_amdgcn_global_load_lds((const unsigned*)((const char*)(gbase) + (voff)[_i]), (LAS unsigned*)(lds + (bufoff) + ldsw + _i * 8192), 16, 0, 0); } while (0)
; #define PG8_LDA(dst, b, h) do { _Pragma("unroll") for (int m = 0; m < 4; ++m) _Pragma("unroll") for (int k = 0; k < 2; ++k) dst[m][k] = *(const LAS bf16x8*)(lds + PG8_SA(b, h) + aoff + m * 2048 + k * 1024); } while (0)
; #define PG8_MMA(ai, bj, At, Bt) do { __builtin_amdgcn_s_setprio(1); _Pragma("unroll") for (int m = 0; m < 4; ++m) _Pragma("unroll") for (int n = 0; n < 2; ++n) _Pragma("unroll") for (int k = 0; k < 2; ++k) \
;         acc[ai][bj][m][n] = __builtin_amdgcn_mfma_f32_16x16x32_bf16(Bt[n][k], At[m][k], acc[ai][bj][m][n], 0, 0, 0); __builtin_amdgcn_s_setprio(0); } while (0)
; #define PG8_WAIT_V(n) asm volatile("s_waitcnt vmcnt(" #n ")" ::: "memory")
; #define PG8_WAIT_L(n) asm volatile("s_waitcnt lgkmcnt(" #n ")" ::: "memory")
; #define PG8_BAR __builtin_amdgcn_s_barrier()
; #define PG8_SCHED __builtin_amdgcn_sched_barrier(0)
; template <class Epi, bool ALIGN_EPI>
; __device__ __forceinline__ void gemm_phase(LAS unsigned char* lds, const Gemm g, const StaticOrder& S, const Epi& E) {
;     ...
;             PG8_LDA(At, 1, 1); PG8_STAGE(PG8_SB(1, 0), b3, voffB); PG8_STAGE(PG8_SB(1, 1), b3 + hstepB, voffB); PG8_STAGE(PG8_SA(1, 0), a3, voffA);
;             PG8_WAIT_V(8); PG8_WAIT_L(0); PG8_BAR; PG8_MMA(1, 0, At, B0); PG8_MMA(1, 1, At, B1); PG8_BAR; PG8_SCHED;
;         }
	s_add_i32 s24, s58, s36
	v_lshl_add_u64 v[212:213], v[212:213], 0, s[18:19]
	s_mov_b32 m0, s24
	ds_read_b128 v[180:183], v165 offset:49152
	ds_read_b128 v[184:187], v165 offset:50176
	ds_read_b128 v[188:191], v165 offset:51200
	ds_read_b128 v[192:195], v165 offset:52224
	ds_read_b128 v[196:199], v165 offset:53248
	ds_read_b128 v[200:203], v165 offset:54272
	ds_read_b128 v[204:207], v165 offset:55296
	ds_read_b128 v[208:211], v165 offset:56320
	global_load_lds_dwordx4 v[212:213], off
	s_add_i32 m0, s24, 0x2000
	s_add_u32 s24, s28, 0x160080
	v_lshl_add_u64 v[212:213], v[214:215], 0, s[18:19]
	s_addc_u32 s25, s29, 0
	s_add_i32 s28, s59, s36
	global_load_lds_dwordx4 v[212:213], off
	v_lshl_add_u64 v[212:213], s[24:25], 0, v[144:145]
	s_mov_b32 m0, s28
	s_nop 0
	global_load_lds_dwordx4 v[212:213], off
	v_lshl_add_u64 v[212:213], s[24:25], 0, v[146:147]
	s_add_i32 m0, s28, 0x2000
	s_nop 0
	global_load_lds_dwordx4 v[212:213], off
	v_lshl_add_u64 v[212:213], v[216:217], 0, s[18:19]
	s_mov_b32 m0, s42
	s_nop 0
	global_load_lds_dwordx4 v[212:213], off
	v_lshl_add_u64 v[212:213], v[218:219], 0, s[18:19]
	s_mov_b32 m0, s43
	s_nop 0
	global_load_lds_dwordx4 v[212:213], off
	s_waitcnt vmcnt(8)
	s_waitcnt lgkmcnt(0)
	s_barrier
	v_mfma_f32_16x16x32_bf16 v[60:63], v[72:75], v[180:183], v[60:63]
	v_mfma_f32_16x16x32_bf16 v[56:59], v[88:91], v[180:183], v[56:59]
	v_mfma_f32_16x16x32_bf16 v[44:47], v[72:75], v[188:191], v[44:47]
	v_mfma_f32_16x16x32_bf16 v[40:43], v[88:91], v[188:191], v[40:43]
	v_mfma_f32_16x16x32_bf16 v[28:31], v[72:75], v[196:199], v[28:31]
	v_mfma_f32_16x16x32_bf16 v[24:27], v[88:91], v[196:199], v[24:27]
	v_mfma_f32_16x16x32_bf16 v[12:15], v[72:75], v[204:207], v[12:15]
	v_mfma_f32_16x16x32_bf16 v[8:11], v[88:91], v[204:207], v[8:11]
	v_mfma_f32_16x16x32_bf16 v[60:63], v[84:87], v[184:187], v[60:63]
	v_mfma_f32_16x16x32_bf16 v[56:59], v[96:99], v[184:187], v[56:59]
	v_mfma_f32_16x16x32_bf16 v[44:47], v[84:87], v[192:195], v[44:47]
	v_mfma_f32_16x16x32_bf16 v[40:43], v[96:99], v[192:195], v[40:43]
	v_mfma_f32_16x16x32_bf16 v[28:31], v[84:87], v[200:203], v[28:31]
	v_mfma_f32_16x16x32_bf16 v[24:27], v[96:99], v[200:203], v[24:27]
	v_mfma_f32_16x16x32_bf16 v[12:15], v[84:87], v[208:211], v[12:15]
	v_mfma_f32_16x16x32_bf16 v[8:11], v[96:99], v[208:211], v[8:11]
	v_mfma_f32_16x16x32_bf16 v[52:55], v[156:159], v[180:183], v[52:55]
	v_mfma_f32_16x16x32_bf16 v[48:51], v[172:175], v[180:183], v[48:51]
	v_mfma_f32_16x16x32_bf16 v[36:39], v[156:159], v[188:191], v[36:39]
	v_mfma_f32_16x16x32_bf16 v[32:35], v[172:175], v[188:191], v[32:35]
	v_mfma_f32_16x16x32_bf16 v[20:23], v[156:159], v[196:199], v[20:23]
	v_mfma_f32_16x16x32_bf16 v[16:19], v[172:175], v[196:199], v[16:19]
	v_mfma_f32_16x16x32_bf16 v[4:7], v[156:159], v[204:207], v[4:7]
	v_mfma_f32_16x16x32_bf16 v[0:3], v[172:175], v[204:207], v[0:3]
	v_mfma_f32_16x16x32_bf16 v[52:55], v[168:171], v[184:187], v[52:55]
	v_mfma_f32_16x16x32_bf16 v[48:51], v[176:179], v[184:187], v[48:51]
	v_mfma_f32_16x16x32_bf16 v[36:39], v[168:171], v[192:195], v[36:39]
	v_mfma_f32_16x16x32_bf16 v[32:35], v[176:179], v[192:195], v[32:35]
	v_mfma_f32_16x16x32_bf16 v[20:23], v[168:171], v[200:203], v[20:23]
	v_mfma_f32_16x16x32_bf16 v[16:19], v[176:179], v[200:203], v[16:19]
	v_mfma_f32_16x16x32_bf16 v[4:7], v[168:171], v[208:211], v[4:7]
	v_mfma_f32_16x16x32_bf16 v[0:3], v[176:179], v[208:211], v[0:3]
	s_barrier
	s_add_i32 s57, s57, 2
	s_add_u32 s55, s55, 0x100
	s_addc_u32 s56, s56, 0
	s_cmpk_gt_u32 s57, 0x55
	s_mov_b64 s[24:25], s[26:27]
	s_cbranch_scc0 .LBB0_1379
	s_and_b64 vcc, exec, s[20:21]
	s_cbranch_vccz .LBB0_1382
	s_barrier

; #define WSP(off) (PTR(29) + (off))
; __device__ __forceinline__ void final_scale_rows(const bf16_t* xw, const float* ss, float* y, int gw, int NGW, int lane) {
;     for (int m = gw; m < MROWS; m += NGW) {
;         const u32x2* src = (const u32x2*)(xw + (size_t)m * DM);
;         u32x2 v[8];
; #pragma unroll
;         for (int j = 0; j < 8; ++j) v[j] = src[lane + 64 * j];
;         const float rs = rsqrtf(ss[m] * (1.f / DM) + EPS);
;         f32x4* dst = (f32x4*)(y + (size_t)m * DM);
; template <int K>
; __device__ __forceinline__ void run_phase(LAS unsigned char* lds, volatile LAS unsigned* ptab) {
;     ...
;     if constexpr (K == 16) final_scale_rows((const bf16_t*)WSP(WS_XN2), (const float*)WSP(WS_SS3), OUTP, gw, NGW, lane);
.LBB0_1454:
	s_or_b64 exec, exec, s[0:1]
	s_setprio 0
	s_add_i32 s0, 0, 0x230ec
	s_waitcnt lgkmcnt(0)
	v_mov_b32_e32 v0, s0
	s_add_i32 s0, 0, 0x230e8
	s_barrier
	ds_read_b32 v1, v0
	v_mov_b32_e32 v2, s0
	ds_read_b32 v3, v2
	s_add_i32 s1, 0, 0x230e4
	v_readfirstlane_b32 s0, v166
	s_waitcnt lgkmcnt(1)
	v_readfirstlane_b32 s6, v1
	ds_read_b32 v0, v0
	ds_read_b32 v1, v2
	v_mov_b32_e32 v2, s1
	s_add_i32 s1, 0, 0x230e0
	s_waitcnt lgkmcnt(2)
	v_readfirstlane_b32 s7, v3
	v_mov_b32_e32 v3, s1
	ds_read_b32 v2, v2
	ds_read_b32 v3, v3
	s_ashr_i32 s0, s0, 6
	s_add_i32 s8, s0, s95
	s_waitcnt lgkmcnt(3)
	v_readfirstlane_b32 s1, v0
	s_waitcnt lgkmcnt(2)
	v_readfirstlane_b32 s2, v1
	s_waitcnt lgkmcnt(1)
	v_readfirstlane_b32 s4, v2
	s_cmpk_gt_i32 s8, 0x5fff
	s_waitcnt lgkmcnt(0)
	v_readfirstlane_b32 s5, v3
	s_cbranch_scc1 .LBB0_1457
	s_ashr_i32 s3, s0, 31
	s_ashr_i32 s9, s95, 31
	s_add_u32 s10, s0, s95
	s_addc_u32 s11, s3, s9
	s_lshl_b64 s[12:13], s[10:11], 2
	s_add_u32 s0, s2, s12
	s_addc_u32 s1, s1, s13
	s_add_u32 s0, s0, 0x40000
	s_addc_u32 s1, s1, 0
	s_ashr_i32 s73, s72, 31
	s_lshl_b64 s[2:3], s[72:73], 2
	s_lshl_b64 s[12:13], s[10:11], 13
	v_and_b32_e32 v4, 63, v166
	s_add_u32 s12, s5, s12
	v_lshlrev_b32_e32 v0, 4, v4
	v_mov_b32_e32 v1, 0
	s_addc_u32 s13, s4, s13
	v_lshl_add_u64 v[2:3], s[12:13], 0, v[0:1]
	s_mov_b64 s[4:5], 0x1c00
	v_lshl_add_u64 v[2:3], v[2:3], 0, s[4:5]
	s_lshl_b64 s[4:5], s[72:73], 13
	s_lshl_b64 s[10:11], s[10:11], 12
	s_add_u32 s10, s7, s10
	v_lshlrev_b32_e32 v0, 3, v4
	s_addc_u32 s11, s6, s11
	v_lshl_add_u64 v[4:5], s[10:11], 0, v[0:1]
	s_mov_b64 s[6:7], 0x8200800
	v_lshl_add_u64 v[4:5], v[4:5], 0, s[6:7]
	s_lshl_b64 s[6:7], s[72:73], 12
	v_mov_b32_e32 v0, 0x358637bd
	s_mov_b32 s9, 0x800000
	s_movk_i32 s10, 0xf000
